# GEMM phases: one static s_setprio 1 for the wave group that runs one barrier behind, per-MFMA-block toggles removed
# baseline (speedup 1.0000x reference)
; #define PG8_STAGE(bufoff, gbase, voff) do { _Pragma("unroll") for (int _i = 0; _i < 2; ++_i) \
;         __builtin_amdgcn_global_load_lds((const unsigned*)((const char*)(gbase) + (voff)[_i]), (PG8_LAS unsigned*)(lds + (bufoff) + ldsw + _i * 8192), 16, 0, 0); } while (0)
; #define PG8_WAIT_V(n) asm volatile("s_waitcnt vmcnt(" #n ")" ::: "memory")
; #define PG8_BAR __builtin_amdgcn_s_barrier()
; template <class Epi>
; __device__ __forceinline__ void gemm_phase(PG8_LAS unsigned char* lds, const Gemm g, const StaticOrder& S, const Epi& E) {
;     ...
;     const char* cA = (const char*)g.A + (size_t)cur.pm * tstep; const char* cB = (const char*)g.Bt + (size_t)cur.pn * tstep;
;     PG8_STAGE(PG8_SB(0, 0), cB, voffB); PG8_STAGE(PG8_SA(0, 0), cA, voffA); PG8_STAGE(PG8_SB(0, 1), cB + hstep, voffB); PG8_STAGE(PG8_SA(0, 1), cA + hstep, voffA);
;     if (wr == 1) PG8_BAR;
;     PG8_WAIT_V(4); PG8_BAR;
.LBB0_44:
	s_andn2_b64 vcc, exec, s[2:3]
	s_cbranch_vccnz .LBB0_284
	v_lshrrev_b32_e32 v3, 1, v10
	v_and_b32_e32 v14, 24, v3
	v_lshrrev_b32_e32 v3, 5, v10
	v_and_b32_e32 v3, 4, v3
	v_bfe_u32 v4, v10, 2, 2
	v_lshlrev_b32_e32 v1, 4, v10
	v_and_b32_e32 v2, 32, v10
	v_bfe_u32 v13, v10, 2, 4
	v_or3_b32 v3, v3, v4, v14
	v_lshrrev_b32_e32 v4, 3, v10
	s_movk_i32 s3, 0x70
	v_bitop3_b32 v11, v1, v2, 48 bitop3:0x6c
	v_and_b32_e32 v12, 64, v10
	v_and_or_b32 v5, v4, s3, v13
	s_movk_i32 s3, 0x60
	v_add_u32_e32 v15, 0x2000, v1
	v_or_b32_e32 v2, v11, v12
	v_and_or_b32 v4, v4, s3, v3
	v_lshrrev_b32_e32 v1, 7, v15
	s_movk_i32 s3, 0xf0
	s_add_u32 s34, s64, 0x1c000000
	v_lshl_or_b32 v132, v4, 12, v2
	v_and_or_b32 v4, v1, s3, v13
	s_movk_i32 s3, 0xe0
	s_addc_u32 s35, s65, 0
	v_and_or_b32 v1, v1, s3, v3
	s_lshr_b32 s3, s33, 6
	s_ashr_i32 s25, s24, 31
	s_ashr_i32 s5, s4, 31
	s_lshr_b32 s2, s33, 8
	s_lshl_b32 s36, s3, 10
	s_waitcnt lgkmcnt(0)
	s_lshl_b64 s[6:7], s[24:25], 20
	s_lshl_b64 s[8:9], s[4:5], 20
	s_add_u32 s28, s34, s8
	s_addc_u32 s29, s35, s9
	s_add_i32 s37, s36, 0
	s_add_i32 m0, s37, 0x10000
	v_lshl_or_b32 v136, v1, 12, v2
	global_load_lds_dwordx4 v132, s[28:29]
	s_add_i32 m0, s37, 0x12000
	s_add_u32 s26, s64, s6
	v_lshl_or_b32 v130, v5, 12, v2
	global_load_lds_dwordx4 v136, s[28:29]
	s_addc_u32 s27, s65, s7
	s_mov_b32 m0, s37
	s_add_i32 s38, s37, 0x2000
	v_lshl_or_b32 v134, v4, 12, v2
	global_load_lds_dwordx4 v130, s[26:27]
	s_mov_b32 m0, s38
	s_add_u32 s6, s28, 0x80000
	global_load_lds_dwordx4 v134, s[26:27]
	s_addc_u32 s7, s29, 0
	s_add_i32 m0, s37, 0x14000
	v_mov_b32_e32 v139, 0
	global_load_lds_dwordx4 v132, s[6:7]
	s_add_i32 m0, s37, 0x16000
	v_mov_b32_e32 v133, v139
	global_load_lds_dwordx4 v136, s[6:7]
	s_add_u32 s6, s26, 0x80000
	s_addc_u32 s7, s27, 0
	s_add_i32 s39, s37, 0x4000
	s_mov_b32 m0, s39
	s_add_i32 s40, s37, 0x6000
	global_load_lds_dwordx4 v130, s[6:7]
	s_mov_b32 m0, s40
	v_mov_b32_e32 v137, v139
	global_load_lds_dwordx4 v134, s[6:7]
	v_mov_b32_e32 v131, v139
	v_mov_b32_e32 v135, v139
	s_mov_b32 s41, 0
	s_waitcnt vmcnt(0)
	v_lshl_add_u64 v[8:9], s[28:29], 0, v[132:133]
	v_lshl_add_u64 v[6:7], s[28:29], 0, v[136:137]
	v_lshl_add_u64 v[4:5], s[26:27], 0, v[130:131]
	s_cmp_lg_u32 s2, 1
	v_lshl_add_u64 v[2:3], s[26:27], 0, v[134:135]
	s_cbranch_scc1 .LBB0_47
	s_setprio 1
	s_barrier

; #define PG8_STAGE(bufoff, gbase, voff) do { _Pragma("unroll") for (int _i = 0; _i < 2; ++_i) \
;         __builtin_amdgcn_global_load_lds((const unsigned*)((const char*)(gbase) + (voff)[_i]), (PG8_LAS unsigned*)(lds + (bufoff) + ldsw + _i * 8192), 16, 0, 0); } while (0)
; #define PG8_LDA(dst, b, h) do { _Pragma("unroll") for (int m = 0; m < 4; ++m) _Pragma("unroll") for (int k = 0; k < 2; ++k) dst[m][k] = *(const PG8_LAS bf16x8*)(lds + PG8_SA(b, h) + aoff + m * 2048 + k * 1024); } while (0)
; #define PG8_LDB(dst, b, h) do { _Pragma("unroll") for (int n = 0; n < 2; ++n) _Pragma("unroll") for (int k = 0; k < 2; ++k) dst[n][k] = *(const PG8_LAS bf16x8*)(lds + PG8_SB(b, h) + boff + n * 2048 + k * 1024); } while (0)
; #define PG8_MMA(ai, bj, At, Bt) do { __builtin_amdgcn_s_setprio(1); _Pragma("unroll") for (int m = 0; m < 4; ++m) _Pragma("unroll") for (int n = 0; n < 2; ++n) _Pragma("unroll") for (int k = 0; k < 2; ++k) \
;         acc[ai][bj][m][n] = __builtin_amdgcn_mfma_f32_16x16x32_bf16(Bt[n][k], At[m][k], acc[ai][bj][m][n], 0, 0, 0); __builtin_amdgcn_s_setprio(0); } while (0)
; #define PG8_WAIT_V(n) asm volatile("s_waitcnt vmcnt(" #n ")" ::: "memory")
; #define PG8_WAIT_L(n) asm volatile("s_waitcnt lgkmcnt(" #n ")" ::: "memory")
; #define PG8_BAR __builtin_amdgcn_s_barrier()
; #define PG8_SCHED __builtin_amdgcn_sched_barrier(0)
; template <class Epi>
; __device__ __forceinline__ void gemm_phase(PG8_LAS unsigned char* lds, const Gemm g, const StaticOrder& S, const Epi& E) {
;     ...
;             PG8_LDB(B0, 0, 0); PG8_SCHED; PG8_LDA(At, 0, 0); PG8_STAGE(PG8_SA(1, 1), a1 + hstep, voffA);
;             PG8_WAIT_L(8); PG8_BAR; PG8_WAIT_L(0); PG8_MMA(0, 0, At, B0); PG8_BAR; PG8_SCHED;
;             PG8_LDB(B1, 0, 1); PG8_STAGE(PG8_SB(0, 0), b2, voffB);
;             PG8_BAR; PG8_WAIT_L(0); PG8_MMA(0, 1, At, B1); PG8_BAR;
;             PG8_LDA(At, 0, 1); PG8_STAGE(PG8_SA(0, 0), a2, voffA);
;             PG8_BAR; PG8_WAIT_L(0); PG8_MMA(1, 0, At, B0); PG8_BAR; PG8_SCHED;
;             PG8_STAGE(PG8_SB(0, 1), b2 + hstep, voffB);
;             PG8_WAIT_V(6); PG8_BAR; PG8_MMA(1, 1, At, B1); PG8_BAR;
.LBB0_56:
	ds_read_b128 v[148:151], v158
	ds_read_b128 v[152:155], v158 offset:1024
	ds_read_b128 v[162:165], v158 offset:2048
	ds_read_b128 v[166:169], v158 offset:3072
	s_add_u32 s28, s26, 0xfff80080
	s_addc_u32 s29, s27, -1
	s_cmp_eq_u32 s50, 28
	s_cselect_b32 s31, s5, s29
	s_cselect_b32 s30, s19, s28
	s_cselect_b32 s29, s17, s49
	s_cselect_b32 s28, s25, s48
	v_lshl_add_u64 v[202:203], s[26:27], 0, v[140:141]
	s_add_i32 m0, s37, 0xc000
	ds_read_b128 v[170:173], v159
	ds_read_b128 v[174:177], v159 offset:1024
	ds_read_b128 v[178:181], v159 offset:2048
	ds_read_b128 v[182:185], v159 offset:3072
	ds_read_b128 v[186:189], v159 offset:4096
	ds_read_b128 v[190:193], v159 offset:5120
	ds_read_b128 v[194:197], v159 offset:6144
	ds_read_b128 v[198:201], v159 offset:7168
	global_load_lds_dwordx4 v[202:203], off
	v_lshl_add_u64 v[202:203], s[26:27], 0, v[142:143]
	s_add_i32 m0, s37, 0xe000
	s_nop 0
	global_load_lds_dwordx4 v[202:203], off
	s_waitcnt lgkmcnt(8)
	s_barrier
	s_waitcnt lgkmcnt(0)
	s_nop 0
	s_waitcnt lgkmcnt(0)
	v_mfma_f32_16x16x32_bf16 v[126:129], v[148:151], v[170:173], v[126:129]
	v_mfma_f32_16x16x32_bf16 v[122:125], v[162:165], v[170:173], v[122:125]
	v_mfma_f32_16x16x32_bf16 v[110:113], v[148:151], v[178:181], v[110:113]
	v_mfma_f32_16x16x32_bf16 v[106:109], v[162:165], v[178:181], v[106:109]
	v_mfma_f32_16x16x32_bf16 v[94:97], v[148:151], v[186:189], v[94:97]
	v_mfma_f32_16x16x32_bf16 v[90:93], v[162:165], v[186:189], v[90:93]
	v_mfma_f32_16x16x32_bf16 v[78:81], v[148:151], v[194:197], v[78:81]
	v_mfma_f32_16x16x32_bf16 v[74:77], v[162:165], v[194:197], v[74:77]
	v_mfma_f32_16x16x32_bf16 v[126:129], v[152:155], v[174:177], v[126:129]
	v_mfma_f32_16x16x32_bf16 v[122:125], v[166:169], v[174:177], v[122:125]
	v_mfma_f32_16x16x32_bf16 v[110:113], v[152:155], v[182:185], v[110:113]
	v_mfma_f32_16x16x32_bf16 v[106:109], v[166:169], v[182:185], v[106:109]
	v_mfma_f32_16x16x32_bf16 v[94:97], v[152:155], v[190:193], v[94:97]
	v_mfma_f32_16x16x32_bf16 v[90:93], v[166:169], v[190:193], v[90:93]
	v_mfma_f32_16x16x32_bf16 v[78:81], v[152:155], v[198:201], v[78:81]
	v_mfma_f32_16x16x32_bf16 v[74:77], v[166:169], v[198:201], v[74:77]
	s_nop 0
	s_barrier
	s_add_i32 s51, s46, s36
	v_lshl_add_u64 v[218:219], s[28:29], 0, v[132:133]
	s_mov_b32 m0, s51
	ds_read_b128 v[202:205], v160
	ds_read_b128 v[206:209], v160 offset:1024
	ds_read_b128 v[210:213], v160 offset:2048
	ds_read_b128 v[214:217], v160 offset:3072
	global_load_lds_dwordx4 v[218:219], off
	v_lshl_add_u64 v[220:221], s[28:29], 0, v[136:137]
	s_add_i32 m0, s51, 0x2000
	s_nop 0
	global_load_lds_dwordx4 v[220:221], off
	s_barrier
	s_waitcnt lgkmcnt(0)
	s_nop 0
	s_waitcnt lgkmcnt(0)
	v_mfma_f32_16x16x32_bf16 v[118:121], v[202:205], v[170:173], v[118:121]
	v_mfma_f32_16x16x32_bf16 v[114:117], v[210:213], v[170:173], v[114:117]
	v_mfma_f32_16x16x32_bf16 v[102:105], v[202:205], v[178:181], v[102:105]
	v_mfma_f32_16x16x32_bf16 v[98:101], v[210:213], v[178:181], v[98:101]
	v_mfma_f32_16x16x32_bf16 v[86:89], v[202:205], v[186:189], v[86:89]
	v_mfma_f32_16x16x32_bf16 v[82:85], v[210:213], v[186:189], v[82:85]
	v_mfma_f32_16x16x32_bf16 v[70:73], v[202:205], v[194:197], v[70:73]
	v_mfma_f32_16x16x32_bf16 v[66:69], v[210:213], v[194:197], v[66:69]
	v_mfma_f32_16x16x32_bf16 v[118:121], v[206:209], v[174:177], v[118:121]
	v_mfma_f32_16x16x32_bf16 v[114:117], v[214:217], v[174:177], v[114:117]
	v_mfma_f32_16x16x32_bf16 v[102:105], v[206:209], v[182:185], v[102:105]
	v_mfma_f32_16x16x32_bf16 v[98:101], v[214:217], v[182:185], v[98:101]
	v_mfma_f32_16x16x32_bf16 v[86:89], v[206:209], v[190:193], v[86:89]
	v_mfma_f32_16x16x32_bf16 v[82:85], v[214:217], v[190:193], v[82:85]
	v_mfma_f32_16x16x32_bf16 v[70:73], v[206:209], v[198:201], v[70:73]
	v_mfma_f32_16x16x32_bf16 v[66:69], v[214:217], v[198:201], v[66:69]
	s_nop 0
	s_mov_b32 m0, s37
	v_lshl_add_u64 v[222:223], s[30:31], 0, v[130:131]
	s_barrier
	ds_read_b128 v[170:173], v159 offset:16384
	ds_read_b128 v[174:177], v159 offset:17408
	ds_read_b128 v[178:181], v159 offset:18432
	ds_read_b128 v[182:185], v159 offset:19456
	ds_read_b128 v[186:189], v159 offset:20480
	ds_read_b128 v[190:193], v159 offset:21504
	ds_read_b128 v[194:197], v159 offset:22528
	ds_read_b128 v[198:201], v159 offset:23552
	global_load_lds_dwordx4 v[222:223], off
	v_lshl_add_u64 v[224:225], s[30:31], 0, v[134:135]
	s_mov_b32 m0, s38
	s_nop 0
	global_load_lds_dwordx4 v[224:225], off
	s_barrier
	s_waitcnt lgkmcnt(0)
	s_nop 0
	s_waitcnt lgkmcnt(0)
	v_mfma_f32_16x16x32_bf16 v[62:65], v[148:151], v[170:173], v[62:65]
	v_mfma_f32_16x16x32_bf16 v[58:61], v[162:165], v[170:173], v[58:61]
	v_mfma_f32_16x16x32_bf16 v[46:49], v[148:151], v[178:181], v[46:49]
	v_mfma_f32_16x16x32_bf16 v[42:45], v[162:165], v[178:181], v[42:45]
	v_mfma_f32_16x16x32_bf16 v[30:33], v[148:151], v[186:189], v[30:33]
	v_mfma_f32_16x16x32_bf16 v[26:29], v[162:165], v[186:189], v[26:29]
	v_mfma_f32_16x16x32_bf16 v[14:17], v[148:151], v[194:197], v[14:17]
	v_mfma_f32_16x16x32_bf16 v[10:13], v[162:165], v[194:197], v[10:13]
	v_mfma_f32_16x16x32_bf16 v[62:65], v[152:155], v[174:177], v[62:65]
	v_mfma_f32_16x16x32_bf16 v[58:61], v[166:169], v[174:177], v[58:61]
	v_mfma_f32_16x16x32_bf16 v[46:49], v[152:155], v[182:185], v[46:49]
	v_mfma_f32_16x16x32_bf16 v[42:45], v[166:169], v[182:185], v[42:45]
	v_mfma_f32_16x16x32_bf16 v[30:33], v[152:155], v[190:193], v[30:33]
	v_mfma_f32_16x16x32_bf16 v[26:29], v[166:169], v[190:193], v[26:29]
	v_mfma_f32_16x16x32_bf16 v[14:17], v[152:155], v[198:201], v[14:17]
	v_mfma_f32_16x16x32_bf16 v[10:13], v[166:169], v[198:201], v[10:13]
	s_nop 0
	s_barrier
; #define PG8_STAGE(bufoff, gbase, voff) do { _Pragma("unroll") for (int _i = 0; _i < 2; ++_i) \
;         __builtin_amdgcn_global_load_lds((const unsigned*)((const char*)(gbase) + (voff)[_i]), (PG8_LAS unsigned*)(lds + (bufoff) + ldsw + _i * 8192), 16, 0, 0); } while (0)
; #define PG8_LDA(dst, b, h) do { _Pragma("unroll") for (int m = 0; m < 4; ++m) _Pragma("unroll") for (int k = 0; k < 2; ++k) dst[m][k] = *(const PG8_LAS bf16x8*)(lds + PG8_SA(b, h) + aoff + m * 2048 + k * 1024); } while (0)
; #define PG8_LDB(dst, b, h) do { _Pragma("unroll") for (int n = 0; n < 2; ++n) _Pragma("unroll") for (int k = 0; k < 2; ++k) dst[n][k] = *(const PG8_LAS bf16x8*)(lds + PG8_SB(b, h) + boff + n * 2048 + k * 1024); } while (0)
; #define PG8_MMA(ai, bj, At, Bt) do { __builtin_amdgcn_s_setprio(1); _Pragma("unroll") for (int m = 0; m < 4; ++m) _Pragma("unroll") for (int n = 0; n < 2; ++n) _Pragma("unroll") for (int k = 0; k < 2; ++k) \
;         acc[ai][bj][m][n] = __builtin_amdgcn_mfma_f32_16x16x32_bf16(Bt[n][k], At[m][k], acc[ai][bj][m][n], 0, 0, 0); __builtin_amdgcn_s_setprio(0); } while (0)
; #define PG8_WAIT_V(n) asm volatile("s_waitcnt vmcnt(" #n ")" ::: "memory")
; #define PG8_WAIT_L(n) asm volatile("s_waitcnt lgkmcnt(" #n ")" ::: "memory")
; #define PG8_BAR __builtin_amdgcn_s_barrier()
; #define PG8_SCHED __builtin_amdgcn_sched_barrier(0)
; template <class Epi>
; __device__ __forceinline__ void gemm_phase(PG8_LAS unsigned char* lds, const Gemm g, const StaticOrder& S, const Epi& E) {
;     ...
;             PG8_STAGE(PG8_SB(0, 1), b2 + hstep, voffB);
;             PG8_WAIT_V(6); PG8_BAR; PG8_MMA(1, 1, At, B1); PG8_BAR;
;             PG8_LDB(B0, 1, 0); PG8_SCHED; PG8_LDA(At, 1, 0); PG8_STAGE(PG8_SA(0, 1), a2 + hstep, voffA);
;             PG8_WAIT_L(8); PG8_BAR; PG8_WAIT_L(0); PG8_MMA(0, 0, At, B0); PG8_BAR; PG8_SCHED;
;             PG8_LDB(B1, 1, 1); PG8_STAGE(PG8_SB(1, 0), b3, voffB);
;             PG8_BAR; PG8_WAIT_L(0); PG8_MMA(0, 1, At, B1); PG8_BAR;
	s_add_u32 s52, s28, 0x80000
	s_addc_u32 s53, s29, 0
	s_add_i32 s51, s47, s36
	v_lshl_add_u64 v[148:149], s[52:53], 0, v[132:133]
	s_mov_b32 m0, s51
	s_nop 0
	global_load_lds_dwordx4 v[148:149], off
	v_lshl_add_u64 v[148:149], s[52:53], 0, v[136:137]
	s_add_i32 m0, s51, 0x2000
	s_nop 0
	global_load_lds_dwordx4 v[148:149], off
	s_waitcnt vmcnt(6)
	s_barrier
	s_nop 0
	v_mfma_f32_16x16x32_bf16 v[54:57], v[202:205], v[170:173], v[54:57]
	v_mfma_f32_16x16x32_bf16 v[50:53], v[210:213], v[170:173], v[50:53]
	v_mfma_f32_16x16x32_bf16 v[38:41], v[202:205], v[178:181], v[38:41]
	v_mfma_f32_16x16x32_bf16 v[34:37], v[210:213], v[178:181], v[34:37]
	v_mfma_f32_16x16x32_bf16 v[22:25], v[202:205], v[186:189], v[22:25]
	v_mfma_f32_16x16x32_bf16 v[18:21], v[210:213], v[186:189], v[18:21]
	v_mfma_f32_16x16x32_bf16 v[6:9], v[202:205], v[194:197], v[6:9]
	v_mfma_f32_16x16x32_bf16 v[2:5], v[210:213], v[194:197], v[2:5]
	v_mfma_f32_16x16x32_bf16 v[54:57], v[206:209], v[174:177], v[54:57]
	v_mfma_f32_16x16x32_bf16 v[50:53], v[214:217], v[174:177], v[50:53]
	v_mfma_f32_16x16x32_bf16 v[38:41], v[206:209], v[182:185], v[38:41]
	v_mfma_f32_16x16x32_bf16 v[34:37], v[214:217], v[182:185], v[34:37]
	v_mfma_f32_16x16x32_bf16 v[22:25], v[206:209], v[190:193], v[22:25]
	v_mfma_f32_16x16x32_bf16 v[18:21], v[214:217], v[190:193], v[18:21]
	v_mfma_f32_16x16x32_bf16 v[6:9], v[206:209], v[198:201], v[6:9]
	v_mfma_f32_16x16x32_bf16 v[2:5], v[214:217], v[198:201], v[2:5]
	s_nop 0
	s_add_i32 s51, 0, 0x18000
	v_add_u32_e32 v138, s51, v156
	s_barrier
	ds_read_b128 v[148:151], v138
	ds_read_b128 v[152:155], v138 offset:1024
	ds_read_b128 v[162:165], v138 offset:2048
	ds_read_b128 v[166:169], v138 offset:3072
	s_add_u32 s30, s30, 0x80000
	s_addc_u32 s31, s31, 0
	s_mov_b32 m0, s39
	v_lshl_add_u64 v[202:203], s[30:31], 0, v[130:131]
	ds_read_b128 v[170:173], v159 offset:32768
	ds_read_b128 v[174:177], v159 offset:33792
	ds_read_b128 v[178:181], v159 offset:34816
	ds_read_b128 v[182:185], v159 offset:35840
	ds_read_b128 v[186:189], v159 offset:36864
	ds_read_b128 v[190:193], v159 offset:37888
	ds_read_b128 v[194:197], v159 offset:38912
	ds_read_b128 v[198:201], v159 offset:39936
	global_load_lds_dwordx4 v[202:203], off
	v_lshl_add_u64 v[202:203], s[30:31], 0, v[134:135]
	s_mov_b32 m0, s40
	s_nop 0
	global_load_lds_dwordx4 v[202:203], off
	s_waitcnt lgkmcnt(8)
	s_barrier
	s_waitcnt lgkmcnt(0)
	s_nop 0
	s_waitcnt lgkmcnt(0)
	v_mfma_f32_16x16x32_bf16 v[126:129], v[148:151], v[170:173], v[126:129]
	v_mfma_f32_16x16x32_bf16 v[122:125], v[162:165], v[170:173], v[122:125]
	v_mfma_f32_16x16x32_bf16 v[110:113], v[148:151], v[178:181], v[110:113]
	v_mfma_f32_16x16x32_bf16 v[106:109], v[162:165], v[178:181], v[106:109]
	v_mfma_f32_16x16x32_bf16 v[94:97], v[148:151], v[186:189], v[94:97]
	v_mfma_f32_16x16x32_bf16 v[90:93], v[162:165], v[186:189], v[90:93]
	v_mfma_f32_16x16x32_bf16 v[78:81], v[148:151], v[194:197], v[78:81]
	v_mfma_f32_16x16x32_bf16 v[74:77], v[162:165], v[194:197], v[74:77]
	v_mfma_f32_16x16x32_bf16 v[126:129], v[152:155], v[174:177], v[126:129]
	v_mfma_f32_16x16x32_bf16 v[122:125], v[166:169], v[174:177], v[122:125]
	v_mfma_f32_16x16x32_bf16 v[110:113], v[152:155], v[182:185], v[110:113]
	v_mfma_f32_16x16x32_bf16 v[106:109], v[166:169], v[182:185], v[106:109]
	v_mfma_f32_16x16x32_bf16 v[94:97], v[152:155], v[190:193], v[94:97]
	v_mfma_f32_16x16x32_bf16 v[90:93], v[166:169], v[190:193], v[90:93]
	v_mfma_f32_16x16x32_bf16 v[78:81], v[152:155], v[198:201], v[78:81]
	v_mfma_f32_16x16x32_bf16 v[74:77], v[166:169], v[198:201], v[74:77]
	s_nop 0
	s_barrier
	s_add_i32 s30, 0, 0x1c000
	s_add_i32 s31, s51, s36
	v_add_u32_e32 v138, s30, v156
	v_lshl_add_u64 v[218:219], v[218:219], 0, s[12:13]
	s_mov_b32 m0, s31
	ds_read_b128 v[202:205], v138
	ds_read_b128 v[206:209], v138 offset:1024
	ds_read_b128 v[210:213], v138 offset:2048
	ds_read_b128 v[214:217], v138 offset:3072
	global_load_lds_dwordx4 v[218:219], off
	v_lshl_add_u64 v[218:219], v[220:221], 0, s[12:13]
	s_add_i32 m0, s31, 0x2000
	s_nop 0
	global_load_lds_dwordx4 v[218:219], off
	s_barrier
; #define PG8_STAGE(bufoff, gbase, voff) do { _Pragma("unroll") for (int _i = 0; _i < 2; ++_i) \
;         __builtin_amdgcn_global_load_lds((const unsigned*)((const char*)(gbase) + (voff)[_i]), (PG8_LAS unsigned*)(lds + (bufoff) + ldsw + _i * 8192), 16, 0, 0); } while (0)
; #define PG8_LDA(dst, b, h) do { _Pragma("unroll") for (int m = 0; m < 4; ++m) _Pragma("unroll") for (int k = 0; k < 2; ++k) dst[m][k] = *(const PG8_LAS bf16x8*)(lds + PG8_SA(b, h) + aoff + m * 2048 + k * 1024); } while (0)
; #define PG8_MMA(ai, bj, At, Bt) do { __builtin_amdgcn_s_setprio(1); _Pragma("unroll") for (int m = 0; m < 4; ++m) _Pragma("unroll") for (int n = 0; n < 2; ++n) _Pragma("unroll") for (int k = 0; k < 2; ++k) \
;         acc[ai][bj][m][n] = __builtin_amdgcn_mfma_f32_16x16x32_bf16(Bt[n][k], At[m][k], acc[ai][bj][m][n], 0, 0, 0); __builtin_amdgcn_s_setprio(0); } while (0)
; #define PG8_WAIT_V(n) asm volatile("s_waitcnt vmcnt(" #n ")" ::: "memory")
; #define PG8_WAIT_L(n) asm volatile("s_waitcnt lgkmcnt(" #n ")" ::: "memory")
; #define PG8_BAR __builtin_amdgcn_s_barrier()
; #define PG8_SCHED __builtin_amdgcn_sched_barrier(0)
; template <class Epi>
; __device__ __forceinline__ void gemm_phase(PG8_LAS unsigned char* lds, const Gemm g, const StaticOrder& S, const Epi& E) {
;     ...
;             PG8_BAR; PG8_WAIT_L(0); PG8_MMA(0, 1, At, B1); PG8_BAR;
;             PG8_LDA(At, 1, 1); PG8_STAGE(PG8_SA(1, 0), a3, voffA);
;             PG8_BAR; PG8_WAIT_L(0); PG8_MMA(1, 0, At, B0); PG8_BAR; PG8_SCHED;
;             PG8_STAGE(PG8_SB(1, 1), b3 + hstep, voffB);
;             PG8_WAIT_V(6); PG8_BAR; PG8_MMA(1, 1, At, B1); PG8_BAR;
;         }
;         E(acc, cur, wr, wc, fr, fq);
;         if (!has_next) break;
	s_waitcnt lgkmcnt(0)
	s_nop 0
	s_waitcnt lgkmcnt(0)
	v_mfma_f32_16x16x32_bf16 v[118:121], v[202:205], v[170:173], v[118:121]
	v_mfma_f32_16x16x32_bf16 v[114:117], v[210:213], v[170:173], v[114:117]
	v_mfma_f32_16x16x32_bf16 v[102:105], v[202:205], v[178:181], v[102:105]
	v_mfma_f32_16x16x32_bf16 v[98:101], v[210:213], v[178:181], v[98:101]
	v_mfma_f32_16x16x32_bf16 v[86:89], v[202:205], v[186:189], v[86:89]
	v_mfma_f32_16x16x32_bf16 v[82:85], v[210:213], v[186:189], v[82:85]
	v_mfma_f32_16x16x32_bf16 v[70:73], v[202:205], v[194:197], v[70:73]
	v_mfma_f32_16x16x32_bf16 v[66:69], v[210:213], v[194:197], v[66:69]
	v_mfma_f32_16x16x32_bf16 v[118:121], v[206:209], v[174:177], v[118:121]
	v_mfma_f32_16x16x32_bf16 v[114:117], v[214:217], v[174:177], v[114:117]
	v_mfma_f32_16x16x32_bf16 v[102:105], v[206:209], v[182:185], v[102:105]
	v_mfma_f32_16x16x32_bf16 v[98:101], v[214:217], v[182:185], v[98:101]
	v_mfma_f32_16x16x32_bf16 v[86:89], v[206:209], v[190:193], v[86:89]
	v_mfma_f32_16x16x32_bf16 v[82:85], v[214:217], v[190:193], v[82:85]
	v_mfma_f32_16x16x32_bf16 v[70:73], v[206:209], v[198:201], v[70:73]
	v_mfma_f32_16x16x32_bf16 v[66:69], v[214:217], v[198:201], v[66:69]
	s_nop 0
	s_mov_b32 m0, s42
	v_lshl_add_u64 v[218:219], v[222:223], 0, s[12:13]
	s_barrier
	ds_read_b128 v[170:173], v159 offset:49152
	ds_read_b128 v[174:177], v159 offset:50176
	ds_read_b128 v[178:181], v159 offset:51200
	ds_read_b128 v[182:185], v159 offset:52224
	ds_read_b128 v[186:189], v159 offset:53248
	ds_read_b128 v[190:193], v159 offset:54272
	ds_read_b128 v[194:197], v159 offset:55296
	ds_read_b128 v[198:201], v159 offset:56320
	global_load_lds_dwordx4 v[218:219], off
	v_lshl_add_u64 v[218:219], v[224:225], 0, s[12:13]
	s_mov_b32 m0, s43
	s_nop 0
	global_load_lds_dwordx4 v[218:219], off
	s_barrier
	s_waitcnt lgkmcnt(0)
	s_nop 0
	s_waitcnt lgkmcnt(0)
	v_mfma_f32_16x16x32_bf16 v[62:65], v[148:151], v[170:173], v[62:65]
	v_mfma_f32_16x16x32_bf16 v[58:61], v[162:165], v[170:173], v[58:61]
	v_mfma_f32_16x16x32_bf16 v[46:49], v[148:151], v[178:181], v[46:49]
	v_mfma_f32_16x16x32_bf16 v[42:45], v[162:165], v[178:181], v[42:45]
	v_mfma_f32_16x16x32_bf16 v[30:33], v[148:151], v[186:189], v[30:33]
	v_mfma_f32_16x16x32_bf16 v[26:29], v[162:165], v[186:189], v[26:29]
	v_mfma_f32_16x16x32_bf16 v[14:17], v[148:151], v[194:197], v[14:17]
	v_mfma_f32_16x16x32_bf16 v[10:13], v[162:165], v[194:197], v[10:13]
	v_mfma_f32_16x16x32_bf16 v[62:65], v[152:155], v[174:177], v[62:65]
	v_mfma_f32_16x16x32_bf16 v[58:61], v[166:169], v[174:177], v[58:61]
	v_mfma_f32_16x16x32_bf16 v[46:49], v[152:155], v[182:185], v[46:49]
	v_mfma_f32_16x16x32_bf16 v[42:45], v[166:169], v[182:185], v[42:45]
	v_mfma_f32_16x16x32_bf16 v[30:33], v[152:155], v[190:193], v[30:33]
	v_mfma_f32_16x16x32_bf16 v[26:29], v[166:169], v[190:193], v[26:29]
	v_mfma_f32_16x16x32_bf16 v[14:17], v[152:155], v[198:201], v[14:17]
	v_mfma_f32_16x16x32_bf16 v[10:13], v[166:169], v[198:201], v[10:13]
	s_nop 0
	s_barrier
	s_add_u32 s28, s28, 0x80080
	s_addc_u32 s29, s29, 0
	s_add_i32 s30, s30, s36
	v_lshl_add_u64 v[148:149], s[28:29], 0, v[132:133]
	s_mov_b32 m0, s30
	s_nop 0
	global_load_lds_dwordx4 v[148:149], off
	v_lshl_add_u64 v[148:149], s[28:29], 0, v[136:137]
	s_add_i32 m0, s30, 0x2000
	s_nop 0
	global_load_lds_dwordx4 v[148:149], off
	s_waitcnt vmcnt(6)
	s_barrier
	s_nop 0
	v_mfma_f32_16x16x32_bf16 v[54:57], v[202:205], v[170:173], v[54:57]
	v_mfma_f32_16x16x32_bf16 v[50:53], v[210:213], v[170:173], v[50:53]
	v_mfma_f32_16x16x32_bf16 v[38:41], v[202:205], v[178:181], v[38:41]
	v_mfma_f32_16x16x32_bf16 v[34:37], v[210:213], v[178:181], v[34:37]
	v_mfma_f32_16x16x32_bf16 v[22:25], v[202:205], v[186:189], v[22:25]
	v_mfma_f32_16x16x32_bf16 v[18:21], v[210:213], v[186:189], v[18:21]
	v_mfma_f32_16x16x32_bf16 v[6:9], v[202:205], v[194:197], v[6:9]
	v_mfma_f32_16x16x32_bf16 v[2:5], v[210:213], v[194:197], v[2:5]
	v_mfma_f32_16x16x32_bf16 v[54:57], v[206:209], v[174:177], v[54:57]
	v_mfma_f32_16x16x32_bf16 v[50:53], v[214:217], v[174:177], v[50:53]
	v_mfma_f32_16x16x32_bf16 v[38:41], v[206:209], v[182:185], v[38:41]
	v_mfma_f32_16x16x32_bf16 v[34:37], v[214:217], v[182:185], v[34:37]
	v_mfma_f32_16x16x32_bf16 v[22:25], v[206:209], v[190:193], v[22:25]
	v_mfma_f32_16x16x32_bf16 v[18:21], v[214:217], v[190:193], v[18:21]
	v_mfma_f32_16x16x32_bf16 v[6:9], v[206:209], v[198:201], v[6:9]
	v_mfma_f32_16x16x32_bf16 v[2:5], v[214:217], v[198:201], v[2:5]
	s_nop 0
	s_add_i32 s50, s50, 2
	s_add_u32 s26, s26, 0x100
	s_addc_u32 s27, s27, 0
	s_add_u32 s48, s48, 0x100
	s_addc_u32 s49, s49, 0
	s_cmp_gt_u32 s50, 29
	s_barrier
	s_cbranch_scc0 .LBB0_56
	s_lshl_b32 s19, s4, 8
	s_ashr_i32 s17, s4, 3
	v_lshl_add_u32 v148, s24, 8, v1
	s_cmpk_gt_u32 s19, 0x7ff
	v_ashrrev_i32_e32 v149, 31, v148
	s_cselect_b64 s[24:25], -1, 0
	v_lshlrev_b64 v[150:151], 12, v[148:149]
	v_lshlrev_b64 v[152:153], 13, v[148:149]
	s_mov_b64 s[4:5], -1
	s_and_b64 vcc, exec, s[24:25]
	s_cbranch_vccz .LBB0_64
	s_mov_b64 s[28:29], -1
	s_mov_b64 s[4:5], 0
	s_cmp_lt_i32 s17, 2
	s_mov_b64 s[26:27], 0
	s_cbranch_scc0 .LBB0_201
	s_and_b64 vcc, exec, s[28:29]
	s_cbranch_vccnz .LBB0_204

; #define PG8_WAIT_V(n) asm volatile("s_waitcnt vmcnt(" #n ")" ::: "memory")
; #define PG8_BAR __builtin_amdgcn_s_barrier()
; template <class Epi>
; __device__ __forceinline__ void gemm_phase(PG8_LAS unsigned char* lds, const Gemm g, const StaticOrder& S, const Epi& E) {
;     ...
;     PG8_WAIT_V(0);
;     if (wr == 0) PG8_BAR;
;     PG8_BAR;
.LBB0_283:
	s_barrier
	s_setprio 0

; #define PG8_STAGE(bufoff, gbase, voff) do { _Pragma("unroll") for (int _i = 0; _i < 2; ++_i) \
;         __builtin_amdgcn_global_load_lds((const unsigned*)((const char*)(gbase) + (voff)[_i]), (PG8_LAS unsigned*)(lds + (bufoff) + ldsw + _i * 8192), 16, 0, 0); } while (0)
; #define PG8_WAIT_V(n) asm volatile("s_waitcnt vmcnt(" #n ")" ::: "memory")
; #define PG8_BAR __builtin_amdgcn_s_barrier()
; template <class Epi>
; __device__ __forceinline__ void gemm_phase(PG8_LAS unsigned char* lds, const Gemm g, const StaticOrder& S, const Epi& E) {
;     ...
;     const char* cA = (const char*)g.A + (size_t)cur.pm * tstep; const char* cB = (const char*)g.Bt + (size_t)cur.pn * tstep;
;     PG8_STAGE(PG8_SB(0, 0), cB, voffB); PG8_STAGE(PG8_SA(0, 0), cA, voffA); PG8_STAGE(PG8_SB(0, 1), cB + hstep, voffB); PG8_STAGE(PG8_SA(0, 1), cA + hstep, voffA);
;     if (wr == 1) PG8_BAR;
;     PG8_WAIT_V(4); PG8_BAR;
.LBB0_643:
	s_ashr_i32 s2, s5, 3
	s_add_u32 s35, s64, 0xc000000
	v_lshrrev_b32_e32 v3, 1, v10
	s_addc_u32 s36, s65, 0
	v_and_b32_e32 v14, 24, v3
	v_lshrrev_b32_e32 v3, 5, v10
	s_add_u32 s37, s64, 0x1e000000
	v_and_b32_e32 v3, 4, v3
	v_bfe_u32 v4, v10, 2, 2
	s_addc_u32 s38, s65, 0
	v_lshlrev_b32_e32 v1, 4, v10
	v_and_b32_e32 v2, 32, v10
	v_bfe_u32 v13, v10, 2, 4
	v_or3_b32 v3, v3, v4, v14
	v_lshrrev_b32_e32 v4, 3, v10
	s_movk_i32 s5, 0x70
	s_add_i32 s2, s4, s2
	v_bitop3_b32 v11, v1, v2, 48 bitop3:0x6c
	v_and_b32_e32 v12, 64, v10
	v_and_or_b32 v5, v4, s5, v13
	s_movk_i32 s5, 0x60
	v_add_u32_e32 v15, 0x2000, v1
	s_ashr_i32 s4, s2, 31
	v_or_b32_e32 v2, v11, v12
	v_and_or_b32 v4, v4, s5, v3
	v_lshrrev_b32_e32 v1, 7, v15
	s_movk_i32 s5, 0xf0
	s_lshr_b32 s4, s4, 26
	v_lshl_or_b32 v132, v4, 13, v2
	v_and_or_b32 v4, v1, s5, v13
	s_movk_i32 s5, 0xe0
	s_add_i32 s4, s2, s4
	v_and_or_b32 v1, v1, s5, v3
	s_ashr_i32 s5, s4, 6
	s_andn2_b32 s4, s4, 63
	s_sub_i32 s4, s2, s4
	s_bfe_i32 s2, s4, 0x80000
	s_bfe_u32 s2, s2, 0x3000c
	s_add_i32 s7, s4, s2
	s_bfe_i32 s2, s7, 0x80000
	s_and_b32 s7, s7, 0xf8
	s_sub_i32 s4, s4, s7
	s_lshl_b32 s5, s5, 3
	s_sext_i32_i16 s2, s2
	s_sext_i32_i8 s4, s4
	s_lshr_b32 s3, s33, 8
	s_lshr_b32 s2, s2, 3
	s_add_i32 s24, s5, s4
	s_lshr_b32 s6, s33, 6
	s_ashr_i32 s25, s24, 31
	s_bfe_i64 s[8:9], s[2:3], 0x100000
	s_lshl_b32 s39, s6, 10
	s_lshl_b64 s[4:5], s[24:25], 21
	s_lshl_b64 s[8:9], s[8:9], 21
	s_add_u32 s28, s37, s8
	s_addc_u32 s29, s38, s9
	s_add_i32 s25, s39, 0
	s_add_i32 m0, s25, 0x10000
	v_lshl_or_b32 v136, v1, 13, v2
	global_load_lds_dwordx4 v132, s[28:29]
	s_add_i32 m0, s25, 0x12000
	s_add_u32 s26, s35, s4
	v_lshl_or_b32 v130, v5, 13, v2
	global_load_lds_dwordx4 v136, s[28:29]
	s_addc_u32 s27, s36, s5
	s_mov_b32 m0, s25
	s_add_i32 s40, s25, 0x2000
	v_lshl_or_b32 v134, v4, 13, v2
	global_load_lds_dwordx4 v130, s[26:27]
	s_mov_b32 m0, s40
	s_add_u32 s4, s28, 0x100000
	global_load_lds_dwordx4 v134, s[26:27]
	s_addc_u32 s5, s29, 0
	s_add_i32 m0, s25, 0x14000
	v_mov_b32_e32 v133, 0
	global_load_lds_dwordx4 v132, s[4:5]
	s_add_i32 m0, s25, 0x16000
	v_mov_b32_e32 v137, v133
	global_load_lds_dwordx4 v136, s[4:5]
	s_add_u32 s4, s26, 0x100000
	s_addc_u32 s5, s27, 0
	s_add_i32 s41, s25, 0x4000
	s_mov_b32 m0, s41
	s_add_i32 s42, s25, 0x6000
	global_load_lds_dwordx4 v130, s[4:5]
	s_mov_b32 m0, s42
	v_mov_b32_e32 v131, v133
	global_load_lds_dwordx4 v134, s[4:5]
	v_mov_b32_e32 v135, v133
	s_mov_b32 s43, 0
	v_lshl_add_u64 v[8:9], s[28:29], 0, v[132:133]
	v_lshl_add_u64 v[6:7], s[28:29], 0, v[136:137]
	v_lshl_add_u64 v[4:5], s[26:27], 0, v[130:131]
	s_cmp_lg_u32 s3, 1
	v_lshl_add_u64 v[2:3], s[26:27], 0, v[134:135]
	s_cbranch_scc1 .LBB0_645
	s_setprio 1
	s_barrier

; #define PG8_STAGE(bufoff, gbase, voff) do { _Pragma("unroll") for (int _i = 0; _i < 2; ++_i) \
;         __builtin_amdgcn_global_load_lds((const unsigned*)((const char*)(gbase) + (voff)[_i]), (PG8_LAS unsigned*)(lds + (bufoff) + ldsw + _i * 8192), 16, 0, 0); } while (0)
; #define PG8_LDA(dst, b, h) do { _Pragma("unroll") for (int m = 0; m < 4; ++m) _Pragma("unroll") for (int k = 0; k < 2; ++k) dst[m][k] = *(const PG8_LAS bf16x8*)(lds + PG8_SA(b, h) + aoff + m * 2048 + k * 1024); } while (0)
; #define PG8_LDB(dst, b, h) do { _Pragma("unroll") for (int n = 0; n < 2; ++n) _Pragma("unroll") for (int k = 0; k < 2; ++k) dst[n][k] = *(const PG8_LAS bf16x8*)(lds + PG8_SB(b, h) + boff + n * 2048 + k * 1024); } while (0)
; #define PG8_MMA(ai, bj, At, Bt) do { __builtin_amdgcn_s_setprio(1); _Pragma("unroll") for (int m = 0; m < 4; ++m) _Pragma("unroll") for (int n = 0; n < 2; ++n) _Pragma("unroll") for (int k = 0; k < 2; ++k) \
;         acc[ai][bj][m][n] = __builtin_amdgcn_mfma_f32_16x16x32_bf16(Bt[n][k], At[m][k], acc[ai][bj][m][n], 0, 0, 0); __builtin_amdgcn_s_setprio(0); } while (0)
; #define PG8_WAIT_V(n) asm volatile("s_waitcnt vmcnt(" #n ")" ::: "memory")
; #define PG8_WAIT_L(n) asm volatile("s_waitcnt lgkmcnt(" #n ")" ::: "memory")
; #define PG8_BAR __builtin_amdgcn_s_barrier()
; #define PG8_SCHED __builtin_amdgcn_sched_barrier(0)
; template <class Epi>
; __device__ __forceinline__ void gemm_phase(PG8_LAS unsigned char* lds, const Gemm g, const StaticOrder& S, const Epi& E) {
;     ...
;             PG8_LDB(B0, 0, 0); PG8_SCHED; PG8_LDA(At, 0, 0); PG8_STAGE(PG8_SA(1, 1), a1 + hstep, voffA);
;             PG8_WAIT_L(8); PG8_BAR; PG8_WAIT_L(0); PG8_MMA(0, 0, At, B0); PG8_BAR; PG8_SCHED;
;             PG8_LDB(B1, 0, 1); PG8_STAGE(PG8_SB(0, 0), b2, voffB);
;             PG8_BAR; PG8_WAIT_L(0); PG8_MMA(0, 1, At, B1); PG8_BAR;
;             PG8_LDA(At, 0, 1); PG8_STAGE(PG8_SA(0, 0), a2, voffA);
;             PG8_BAR; PG8_WAIT_L(0); PG8_MMA(1, 0, At, B0); PG8_BAR; PG8_SCHED;
;             PG8_STAGE(PG8_SB(0, 1), b2 + hstep, voffB);
;             PG8_WAIT_V(6); PG8_BAR; PG8_MMA(1, 1, At, B1); PG8_BAR;
.LBB0_653:
	ds_read_b128 v[154:157], v150
	ds_read_b128 v[158:161], v150 offset:1024
	ds_read_b128 v[162:165], v150 offset:2048
	ds_read_b128 v[166:169], v150 offset:3072
	s_add_u32 s28, s26, 0xfff00080
	s_addc_u32 s29, s27, -1
	s_cmp_eq_u32 s58, 60
	s_cselect_b32 s31, s19, s29
	s_cselect_b32 s30, s54, s28
	s_cselect_b32 s29, s17, s57
	s_cselect_b32 s28, s55, s56
	v_lshl_add_u64 v[146:147], s[26:27], 0, v[138:139]
	s_add_i32 m0, s25, 0xc000
	ds_read_b128 v[170:173], v151
	ds_read_b128 v[174:177], v151 offset:1024
	ds_read_b128 v[178:181], v151 offset:2048
	ds_read_b128 v[182:185], v151 offset:3072
	ds_read_b128 v[186:189], v151 offset:4096
	ds_read_b128 v[190:193], v151 offset:5120
	ds_read_b128 v[194:197], v151 offset:6144
	ds_read_b128 v[198:201], v151 offset:7168
	global_load_lds_dwordx4 v[146:147], off
	v_lshl_add_u64 v[146:147], s[26:27], 0, v[140:141]
	s_add_i32 m0, s25, 0xe000
	s_nop 0
	global_load_lds_dwordx4 v[146:147], off
	s_waitcnt lgkmcnt(8)
	s_barrier
	s_waitcnt lgkmcnt(0)
	s_nop 0
	s_waitcnt lgkmcnt(0)
	v_mfma_f32_16x16x32_bf16 v[126:129], v[154:157], v[170:173], v[126:129]
	v_mfma_f32_16x16x32_bf16 v[122:125], v[162:165], v[170:173], v[122:125]
	v_mfma_f32_16x16x32_bf16 v[114:117], v[154:157], v[178:181], v[114:117]
	v_mfma_f32_16x16x32_bf16 v[106:109], v[162:165], v[178:181], v[106:109]
	v_mfma_f32_16x16x32_bf16 v[98:101], v[154:157], v[186:189], v[98:101]
	v_mfma_f32_16x16x32_bf16 v[90:93], v[162:165], v[186:189], v[90:93]
	v_mfma_f32_16x16x32_bf16 v[82:85], v[154:157], v[194:197], v[82:85]
	v_mfma_f32_16x16x32_bf16 v[74:77], v[162:165], v[194:197], v[74:77]
	v_mfma_f32_16x16x32_bf16 v[126:129], v[158:161], v[174:177], v[126:129]
	v_mfma_f32_16x16x32_bf16 v[122:125], v[166:169], v[174:177], v[122:125]
	v_mfma_f32_16x16x32_bf16 v[114:117], v[158:161], v[182:185], v[114:117]
	v_mfma_f32_16x16x32_bf16 v[106:109], v[166:169], v[182:185], v[106:109]
	v_mfma_f32_16x16x32_bf16 v[98:101], v[158:161], v[190:193], v[98:101]
	v_mfma_f32_16x16x32_bf16 v[90:93], v[166:169], v[190:193], v[90:93]
	v_mfma_f32_16x16x32_bf16 v[82:85], v[158:161], v[198:201], v[82:85]
	v_mfma_f32_16x16x32_bf16 v[74:77], v[166:169], v[198:201], v[74:77]
	s_nop 0
	s_barrier
	s_add_i32 s59, s47, s39
	v_lshl_add_u64 v[146:147], s[28:29], 0, v[132:133]
	s_mov_b32 m0, s59
	ds_read_b128 v[202:205], v152
	ds_read_b128 v[206:209], v152 offset:1024
	ds_read_b128 v[210:213], v152 offset:2048
	ds_read_b128 v[214:217], v152 offset:3072
	global_load_lds_dwordx4 v[146:147], off
	v_lshl_add_u64 v[218:219], s[28:29], 0, v[136:137]
	s_add_i32 m0, s59, 0x2000
	s_nop 0
	global_load_lds_dwordx4 v[218:219], off
	s_barrier
	s_waitcnt lgkmcnt(0)
	s_nop 0
	s_waitcnt lgkmcnt(0)
	v_mfma_f32_16x16x32_bf16 v[118:121], v[202:205], v[170:173], v[118:121]
	v_mfma_f32_16x16x32_bf16 v[110:113], v[210:213], v[170:173], v[110:113]
	v_mfma_f32_16x16x32_bf16 v[102:105], v[202:205], v[178:181], v[102:105]
	v_mfma_f32_16x16x32_bf16 v[94:97], v[210:213], v[178:181], v[94:97]
	v_mfma_f32_16x16x32_bf16 v[86:89], v[202:205], v[186:189], v[86:89]
	v_mfma_f32_16x16x32_bf16 v[78:81], v[210:213], v[186:189], v[78:81]
	v_mfma_f32_16x16x32_bf16 v[70:73], v[202:205], v[194:197], v[70:73]
	v_mfma_f32_16x16x32_bf16 v[66:69], v[210:213], v[194:197], v[66:69]
	v_mfma_f32_16x16x32_bf16 v[118:121], v[206:209], v[174:177], v[118:121]
	v_mfma_f32_16x16x32_bf16 v[110:113], v[214:217], v[174:177], v[110:113]
	v_mfma_f32_16x16x32_bf16 v[102:105], v[206:209], v[182:185], v[102:105]
	v_mfma_f32_16x16x32_bf16 v[94:97], v[214:217], v[182:185], v[94:97]
	v_mfma_f32_16x16x32_bf16 v[86:89], v[206:209], v[190:193], v[86:89]
	v_mfma_f32_16x16x32_bf16 v[78:81], v[214:217], v[190:193], v[78:81]
	v_mfma_f32_16x16x32_bf16 v[70:73], v[206:209], v[198:201], v[70:73]
	v_mfma_f32_16x16x32_bf16 v[66:69], v[214:217], v[198:201], v[66:69]
	s_nop 0
	s_mov_b32 m0, s25
	v_lshl_add_u64 v[220:221], s[30:31], 0, v[130:131]
	s_barrier
	ds_read_b128 v[170:173], v151 offset:16384
	ds_read_b128 v[174:177], v151 offset:17408
	ds_read_b128 v[178:181], v151 offset:18432
	ds_read_b128 v[182:185], v151 offset:19456
	ds_read_b128 v[186:189], v151 offset:20480
	ds_read_b128 v[190:193], v151 offset:21504
	ds_read_b128 v[194:197], v151 offset:22528
	ds_read_b128 v[198:201], v151 offset:23552
	global_load_lds_dwordx4 v[220:221], off
	v_lshl_add_u64 v[222:223], s[30:31], 0, v[134:135]
	s_mov_b32 m0, s40
	s_nop 0
	global_load_lds_dwordx4 v[222:223], off
	s_barrier
	s_waitcnt lgkmcnt(0)
	s_nop 0
	s_waitcnt lgkmcnt(0)
	v_mfma_f32_16x16x32_bf16 v[62:65], v[154:157], v[170:173], v[62:65]
	v_mfma_f32_16x16x32_bf16 v[58:61], v[162:165], v[170:173], v[58:61]
	v_mfma_f32_16x16x32_bf16 v[54:57], v[154:157], v[178:181], v[54:57]
	v_mfma_f32_16x16x32_bf16 v[46:49], v[162:165], v[178:181], v[46:49]
	v_mfma_f32_16x16x32_bf16 v[38:41], v[154:157], v[186:189], v[38:41]
	v_mfma_f32_16x16x32_bf16 v[30:33], v[162:165], v[186:189], v[30:33]
	v_mfma_f32_16x16x32_bf16 v[22:25], v[154:157], v[194:197], v[22:25]
	v_mfma_f32_16x16x32_bf16 v[14:17], v[162:165], v[194:197], v[14:17]
	v_mfma_f32_16x16x32_bf16 v[62:65], v[158:161], v[174:177], v[62:65]
	v_mfma_f32_16x16x32_bf16 v[58:61], v[166:169], v[174:177], v[58:61]
	v_mfma_f32_16x16x32_bf16 v[54:57], v[158:161], v[182:185], v[54:57]
	v_mfma_f32_16x16x32_bf16 v[46:49], v[166:169], v[182:185], v[46:49]
	v_mfma_f32_16x16x32_bf16 v[38:41], v[158:161], v[190:193], v[38:41]
	v_mfma_f32_16x16x32_bf16 v[30:33], v[166:169], v[190:193], v[30:33]
	v_mfma_f32_16x16x32_bf16 v[22:25], v[158:161], v[198:201], v[22:25]
	v_mfma_f32_16x16x32_bf16 v[14:17], v[166:169], v[198:201], v[14:17]
	s_nop 0
	s_barrier
; #define PG8_STAGE(bufoff, gbase, voff) do { _Pragma("unroll") for (int _i = 0; _i < 2; ++_i) \
;         __builtin_amdgcn_global_load_lds((const unsigned*)((const char*)(gbase) + (voff)[_i]), (PG8_LAS unsigned*)(lds + (bufoff) + ldsw + _i * 8192), 16, 0, 0); } while (0)
; #define PG8_LDA(dst, b, h) do { _Pragma("unroll") for (int m = 0; m < 4; ++m) _Pragma("unroll") for (int k = 0; k < 2; ++k) dst[m][k] = *(const PG8_LAS bf16x8*)(lds + PG8_SA(b, h) + aoff + m * 2048 + k * 1024); } while (0)
; #define PG8_LDB(dst, b, h) do { _Pragma("unroll") for (int n = 0; n < 2; ++n) _Pragma("unroll") for (int k = 0; k < 2; ++k) dst[n][k] = *(const PG8_LAS bf16x8*)(lds + PG8_SB(b, h) + boff + n * 2048 + k * 1024); } while (0)
; #define PG8_MMA(ai, bj, At, Bt) do { __builtin_amdgcn_s_setprio(1); _Pragma("unroll") for (int m = 0; m < 4; ++m) _Pragma("unroll") for (int n = 0; n < 2; ++n) _Pragma("unroll") for (int k = 0; k < 2; ++k) \
;         acc[ai][bj][m][n] = __builtin_amdgcn_mfma_f32_16x16x32_bf16(Bt[n][k], At[m][k], acc[ai][bj][m][n], 0, 0, 0); __builtin_amdgcn_s_setprio(0); } while (0)
; #define PG8_WAIT_V(n) asm volatile("s_waitcnt vmcnt(" #n ")" ::: "memory")
; #define PG8_WAIT_L(n) asm volatile("s_waitcnt lgkmcnt(" #n ")" ::: "memory")
; #define PG8_BAR __builtin_amdgcn_s_barrier()
; #define PG8_SCHED __builtin_amdgcn_sched_barrier(0)
; template <class Epi>
; __device__ __forceinline__ void gemm_phase(PG8_LAS unsigned char* lds, const Gemm g, const StaticOrder& S, const Epi& E) {
;     ...
;             PG8_WAIT_V(6); PG8_BAR; PG8_MMA(1, 1, At, B1); PG8_BAR;
;             PG8_LDB(B0, 1, 0); PG8_SCHED; PG8_LDA(At, 1, 0); PG8_STAGE(PG8_SA(0, 1), a2 + hstep, voffA);
;             PG8_WAIT_L(8); PG8_BAR; PG8_WAIT_L(0); PG8_MMA(0, 0, At, B0); PG8_BAR; PG8_SCHED;
;             PG8_LDB(B1, 1, 1); PG8_STAGE(PG8_SB(1, 0), b3, voffB);
;             PG8_BAR; PG8_WAIT_L(0); PG8_MMA(0, 1, At, B1); PG8_BAR;
;             PG8_LDA(At, 1, 1); PG8_STAGE(PG8_SA(1, 0), a3, voffA);
;             PG8_BAR; PG8_WAIT_L(0); PG8_MMA(1, 0, At, B0); PG8_BAR; PG8_SCHED;
	s_add_u32 s60, s28, 0x100000
	s_addc_u32 s61, s29, 0
	s_add_i32 s59, s48, s39
	v_lshl_add_u64 v[154:155], s[60:61], 0, v[132:133]
	s_mov_b32 m0, s59
	s_nop 0
	global_load_lds_dwordx4 v[154:155], off
	v_lshl_add_u64 v[154:155], s[60:61], 0, v[136:137]
	s_add_i32 m0, s59, 0x2000
	s_nop 0
	global_load_lds_dwordx4 v[154:155], off
	s_waitcnt vmcnt(6)
	s_barrier
	s_nop 0
	v_mfma_f32_16x16x32_bf16 v[50:53], v[202:205], v[170:173], v[50:53]
	v_mfma_f32_16x16x32_bf16 v[42:45], v[210:213], v[170:173], v[42:45]
	v_mfma_f32_16x16x32_bf16 v[34:37], v[202:205], v[178:181], v[34:37]
	v_mfma_f32_16x16x32_bf16 v[26:29], v[210:213], v[178:181], v[26:29]
	v_mfma_f32_16x16x32_bf16 v[18:21], v[202:205], v[186:189], v[18:21]
	v_mfma_f32_16x16x32_bf16 v[10:13], v[210:213], v[186:189], v[10:13]
	v_mfma_f32_16x16x32_bf16 v[6:9], v[202:205], v[194:197], v[6:9]
	v_mfma_f32_16x16x32_bf16 v[2:5], v[210:213], v[194:197], v[2:5]
	v_mfma_f32_16x16x32_bf16 v[50:53], v[206:209], v[174:177], v[50:53]
	v_mfma_f32_16x16x32_bf16 v[42:45], v[214:217], v[174:177], v[42:45]
	v_mfma_f32_16x16x32_bf16 v[34:37], v[206:209], v[182:185], v[34:37]
	v_mfma_f32_16x16x32_bf16 v[26:29], v[214:217], v[182:185], v[26:29]
	v_mfma_f32_16x16x32_bf16 v[18:21], v[206:209], v[190:193], v[18:21]
	v_mfma_f32_16x16x32_bf16 v[10:13], v[214:217], v[190:193], v[10:13]
	v_mfma_f32_16x16x32_bf16 v[6:9], v[206:209], v[198:201], v[6:9]
	v_mfma_f32_16x16x32_bf16 v[2:5], v[214:217], v[198:201], v[2:5]
	s_nop 0
	s_add_i32 s59, 0, 0x18000
	v_add_u32_e32 v153, s59, v148
	s_barrier
	ds_read_b128 v[154:157], v153
	ds_read_b128 v[158:161], v153 offset:1024
	ds_read_b128 v[162:165], v153 offset:2048
	ds_read_b128 v[166:169], v153 offset:3072
	s_add_u32 s30, s30, 0x100000
	s_addc_u32 s31, s31, 0
	s_mov_b32 m0, s41
	v_lshl_add_u64 v[202:203], s[30:31], 0, v[130:131]
	ds_read_b128 v[170:173], v151 offset:32768
	ds_read_b128 v[174:177], v151 offset:33792
	ds_read_b128 v[178:181], v151 offset:34816
	ds_read_b128 v[182:185], v151 offset:35840
	ds_read_b128 v[186:189], v151 offset:36864
	ds_read_b128 v[190:193], v151 offset:37888
	ds_read_b128 v[194:197], v151 offset:38912
	ds_read_b128 v[198:201], v151 offset:39936
	global_load_lds_dwordx4 v[202:203], off
	v_lshl_add_u64 v[202:203], s[30:31], 0, v[134:135]
	s_mov_b32 m0, s42
	s_nop 0
	global_load_lds_dwordx4 v[202:203], off
	s_waitcnt lgkmcnt(8)
	s_barrier
	s_waitcnt lgkmcnt(0)
	s_nop 0
	s_waitcnt lgkmcnt(0)
	v_mfma_f32_16x16x32_bf16 v[126:129], v[154:157], v[170:173], v[126:129]
	v_mfma_f32_16x16x32_bf16 v[122:125], v[162:165], v[170:173], v[122:125]
	v_mfma_f32_16x16x32_bf16 v[114:117], v[154:157], v[178:181], v[114:117]
	v_mfma_f32_16x16x32_bf16 v[106:109], v[162:165], v[178:181], v[106:109]
	v_mfma_f32_16x16x32_bf16 v[98:101], v[154:157], v[186:189], v[98:101]
	v_mfma_f32_16x16x32_bf16 v[90:93], v[162:165], v[186:189], v[90:93]
	v_mfma_f32_16x16x32_bf16 v[82:85], v[154:157], v[194:197], v[82:85]
	v_mfma_f32_16x16x32_bf16 v[74:77], v[162:165], v[194:197], v[74:77]
	v_mfma_f32_16x16x32_bf16 v[126:129], v[158:161], v[174:177], v[126:129]
	v_mfma_f32_16x16x32_bf16 v[122:125], v[166:169], v[174:177], v[122:125]
	v_mfma_f32_16x16x32_bf16 v[114:117], v[158:161], v[182:185], v[114:117]
	v_mfma_f32_16x16x32_bf16 v[106:109], v[166:169], v[182:185], v[106:109]
	v_mfma_f32_16x16x32_bf16 v[98:101], v[158:161], v[190:193], v[98:101]
	v_mfma_f32_16x16x32_bf16 v[90:93], v[166:169], v[190:193], v[90:93]
	v_mfma_f32_16x16x32_bf16 v[82:85], v[158:161], v[198:201], v[82:85]
	v_mfma_f32_16x16x32_bf16 v[74:77], v[166:169], v[198:201], v[74:77]
	s_nop 0
	s_barrier
	s_add_i32 s30, 0, 0x1c000
	s_add_i32 s31, s59, s39
	v_add_u32_e32 v153, s30, v148
	v_lshl_add_u64 v[146:147], v[146:147], 0, s[6:7]
	s_mov_b32 m0, s31
	ds_read_b128 v[202:205], v153
	ds_read_b128 v[206:209], v153 offset:1024
	ds_read_b128 v[210:213], v153 offset:2048
	ds_read_b128 v[214:217], v153 offset:3072
	global_load_lds_dwordx4 v[146:147], off
	v_lshl_add_u64 v[146:147], v[218:219], 0, s[6:7]
	s_add_i32 m0, s31, 0x2000
	s_nop 0
	global_load_lds_dwordx4 v[146:147], off
	s_barrier
	s_waitcnt lgkmcnt(0)
	s_nop 0
	s_waitcnt lgkmcnt(0)
	v_mfma_f32_16x16x32_bf16 v[118:121], v[202:205], v[170:173], v[118:121]
	v_mfma_f32_16x16x32_bf16 v[110:113], v[210:213], v[170:173], v[110:113]
	v_mfma_f32_16x16x32_bf16 v[102:105], v[202:205], v[178:181], v[102:105]
	v_mfma_f32_16x16x32_bf16 v[94:97], v[210:213], v[178:181], v[94:97]
	v_mfma_f32_16x16x32_bf16 v[86:89], v[202:205], v[186:189], v[86:89]
	v_mfma_f32_16x16x32_bf16 v[78:81], v[210:213], v[186:189], v[78:81]
	v_mfma_f32_16x16x32_bf16 v[70:73], v[202:205], v[194:197], v[70:73]
	v_mfma_f32_16x16x32_bf16 v[66:69], v[210:213], v[194:197], v[66:69]
	v_mfma_f32_16x16x32_bf16 v[118:121], v[206:209], v[174:177], v[118:121]
	v_mfma_f32_16x16x32_bf16 v[110:113], v[214:217], v[174:177], v[110:113]
	v_mfma_f32_16x16x32_bf16 v[102:105], v[206:209], v[182:185], v[102:105]
	v_mfma_f32_16x16x32_bf16 v[94:97], v[214:217], v[182:185], v[94:97]
	v_mfma_f32_16x16x32_bf16 v[86:89], v[206:209], v[190:193], v[86:89]
	v_mfma_f32_16x16x32_bf16 v[78:81], v[214:217], v[190:193], v[78:81]
	v_mfma_f32_16x16x32_bf16 v[70:73], v[206:209], v[198:201], v[70:73]
	v_mfma_f32_16x16x32_bf16 v[66:69], v[214:217], v[198:201], v[66:69]
	s_nop 0
	s_mov_b32 m0, s44
	v_lshl_add_u64 v[146:147], v[220:221], 0, s[6:7]
	s_barrier
	ds_read_b128 v[170:173], v151 offset:49152
	ds_read_b128 v[174:177], v151 offset:50176
	ds_read_b128 v[178:181], v151 offset:51200
	ds_read_b128 v[182:185], v151 offset:52224
	ds_read_b128 v[186:189], v151 offset:53248
	ds_read_b128 v[190:193], v151 offset:54272
	ds_read_b128 v[194:197], v151 offset:55296
	ds_read_b128 v[198:201], v151 offset:56320
	global_load_lds_dwordx4 v[146:147], off
	v_lshl_add_u64 v[146:147], v[222:223], 0, s[6:7]
	s_mov_b32 m0, s45
	s_nop 0
	global_load_lds_dwordx4 v[146:147], off
	s_barrier
; #define PG8_STAGE(bufoff, gbase, voff) do { _Pragma("unroll") for (int _i = 0; _i < 2; ++_i) \
;         __builtin_amdgcn_global_load_lds((const unsigned*)((const char*)(gbase) + (voff)[_i]), (PG8_LAS unsigned*)(lds + (bufoff) + ldsw + _i * 8192), 16, 0, 0); } while (0)
; #define PG8_MMA(ai, bj, At, Bt) do { __builtin_amdgcn_s_setprio(1); _Pragma("unroll") for (int m = 0; m < 4; ++m) _Pragma("unroll") for (int n = 0; n < 2; ++n) _Pragma("unroll") for (int k = 0; k < 2; ++k) \
;         acc[ai][bj][m][n] = __builtin_amdgcn_mfma_f32_16x16x32_bf16(Bt[n][k], At[m][k], acc[ai][bj][m][n], 0, 0, 0); __builtin_amdgcn_s_setprio(0); } while (0)
; #define PG8_WAIT_V(n) asm volatile("s_waitcnt vmcnt(" #n ")" ::: "memory")
; #define PG8_WAIT_L(n) asm volatile("s_waitcnt lgkmcnt(" #n ")" ::: "memory")
; #define PG8_BAR __builtin_amdgcn_s_barrier()
; #define PG8_SCHED __builtin_amdgcn_sched_barrier(0)
; template <class Epi>
; __device__ __forceinline__ void gemm_phase(PG8_LAS unsigned char* lds, const Gemm g, const StaticOrder& S, const Epi& E) {
;     ...
;             PG8_BAR; PG8_WAIT_L(0); PG8_MMA(1, 0, At, B0); PG8_BAR; PG8_SCHED;
;             PG8_STAGE(PG8_SB(1, 1), b3 + hstep, voffB);
;             PG8_WAIT_V(6); PG8_BAR; PG8_MMA(1, 1, At, B1); PG8_BAR;
	s_waitcnt lgkmcnt(0)
	s_nop 0
	s_waitcnt lgkmcnt(0)
	v_mfma_f32_16x16x32_bf16 v[62:65], v[154:157], v[170:173], v[62:65]
	v_mfma_f32_16x16x32_bf16 v[58:61], v[162:165], v[170:173], v[58:61]
	v_mfma_f32_16x16x32_bf16 v[54:57], v[154:157], v[178:181], v[54:57]
	v_mfma_f32_16x16x32_bf16 v[46:49], v[162:165], v[178:181], v[46:49]
	v_mfma_f32_16x16x32_bf16 v[38:41], v[154:157], v[186:189], v[38:41]
	v_mfma_f32_16x16x32_bf16 v[30:33], v[162:165], v[186:189], v[30:33]
	v_mfma_f32_16x16x32_bf16 v[22:25], v[154:157], v[194:197], v[22:25]
	v_mfma_f32_16x16x32_bf16 v[14:17], v[162:165], v[194:197], v[14:17]
	v_mfma_f32_16x16x32_bf16 v[62:65], v[158:161], v[174:177], v[62:65]
	v_mfma_f32_16x16x32_bf16 v[58:61], v[166:169], v[174:177], v[58:61]
	v_mfma_f32_16x16x32_bf16 v[54:57], v[158:161], v[182:185], v[54:57]
	v_mfma_f32_16x16x32_bf16 v[46:49], v[166:169], v[182:185], v[46:49]
	v_mfma_f32_16x16x32_bf16 v[38:41], v[158:161], v[190:193], v[38:41]
	v_mfma_f32_16x16x32_bf16 v[30:33], v[166:169], v[190:193], v[30:33]
	v_mfma_f32_16x16x32_bf16 v[22:25], v[158:161], v[198:201], v[22:25]
	v_mfma_f32_16x16x32_bf16 v[14:17], v[166:169], v[198:201], v[14:17]
	s_nop 0
	s_barrier
	s_add_u32 s28, s28, 0x100080
	s_addc_u32 s29, s29, 0
	s_add_i32 s30, s30, s39
	v_lshl_add_u64 v[146:147], s[28:29], 0, v[132:133]
	s_mov_b32 m0, s30
	s_nop 0
	global_load_lds_dwordx4 v[146:147], off
	v_lshl_add_u64 v[146:147], s[28:29], 0, v[136:137]
	s_add_i32 m0, s30, 0x2000
	s_nop 0
	global_load_lds_dwordx4 v[146:147], off
	s_waitcnt vmcnt(6)
	s_barrier
	s_nop 0
	v_mfma_f32_16x16x32_bf16 v[50:53], v[202:205], v[170:173], v[50:53]
	v_mfma_f32_16x16x32_bf16 v[42:45], v[210:213], v[170:173], v[42:45]
	v_mfma_f32_16x16x32_bf16 v[34:37], v[202:205], v[178:181], v[34:37]
	v_mfma_f32_16x16x32_bf16 v[26:29], v[210:213], v[178:181], v[26:29]
	v_mfma_f32_16x16x32_bf16 v[18:21], v[202:205], v[186:189], v[18:21]
	v_mfma_f32_16x16x32_bf16 v[10:13], v[210:213], v[186:189], v[10:13]
	v_mfma_f32_16x16x32_bf16 v[6:9], v[202:205], v[194:197], v[6:9]
	v_mfma_f32_16x16x32_bf16 v[2:5], v[210:213], v[194:197], v[2:5]
	v_mfma_f32_16x16x32_bf16 v[50:53], v[206:209], v[174:177], v[50:53]
	v_mfma_f32_16x16x32_bf16 v[42:45], v[214:217], v[174:177], v[42:45]
	v_mfma_f32_16x16x32_bf16 v[34:37], v[206:209], v[182:185], v[34:37]
	v_mfma_f32_16x16x32_bf16 v[26:29], v[214:217], v[182:185], v[26:29]
	v_mfma_f32_16x16x32_bf16 v[18:21], v[206:209], v[190:193], v[18:21]
	v_mfma_f32_16x16x32_bf16 v[10:13], v[214:217], v[190:193], v[10:13]
	v_mfma_f32_16x16x32_bf16 v[6:9], v[206:209], v[198:201], v[6:9]
	v_mfma_f32_16x16x32_bf16 v[2:5], v[214:217], v[198:201], v[2:5]
	s_nop 0
	s_add_i32 s58, s58, 2
	s_add_u32 s26, s26, 0x100
	s_addc_u32 s27, s27, 0
	s_add_u32 s56, s56, 0x100
	s_addc_u32 s57, s57, 0
	s_cmp_gt_u32 s58, 61
	s_barrier
	s_cbranch_scc0 .LBB0_653
;     __device__ __forceinline__ void operator()(const f32x4 (&acc)[2][2][4][2], const Unit& u, int wr, int wc, int fr, int fq) const {
;         const int row0 = u.pm * BM + wr * 64 + fr, col0 = u.pn * BM + wc * 32 + 8 * fq;
; #pragma unroll
;         for (int ai = 0; ai < 2; ++ai)
; #pragma unroll
;             for (int m = 0; m < 4; ++m)
; #pragma unroll
;                 for (int bj = 0; bj < 2; ++bj) f(row0 + ai * HALF + m * 16, col0 + bj * HALF, acc[ai][bj][m][0], acc[ai][bj][m][1]);
	v_lshl_add_u32 v154, s24, 8, v1
	v_lshl_or_b32 v146, s53, 8, v149
	v_ashrrev_i32_e32 v155, 31, v154
	v_lshlrev_b64 v[156:157], 12, v[154:155]
	v_ashrrev_i32_e32 v147, 31, v146
	v_lshl_add_u64 v[156:157], s[4:5], 0, v[156:157]
	v_lshlrev_b64 v[158:159], 1, v[146:147]
	v_lshl_add_u64 v[146:147], v[156:157], 0, v[158:159]
	v_cvt_pk_bf16_f32 v126, v126, v127
	v_cvt_pk_bf16_f32 v127, v128, v129
	v_cvt_pk_bf16_f32 v128, v122, v123
	v_cvt_pk_bf16_f32 v129, v124, v125
	global_store_dwordx4 v[146:147], v[126:129], off
	v_cvt_pk_bf16_f32 v118, v118, v119
	v_cvt_pk_bf16_f32 v119, v120, v121
	v_cvt_pk_bf16_f32 v120, v110, v111
	v_or_b32_e32 v110, 16, v154
	v_ashrrev_i32_e32 v111, 31, v110
	v_lshlrev_b64 v[110:111], 12, v[110:111]
	v_lshl_add_u64 v[110:111], s[4:5], 0, v[110:111]
	v_cvt_pk_bf16_f32 v121, v112, v113
	global_store_dwordx4 v[146:147], v[118:121], off offset:256
	s_mov_b32 s53, s16
	s_mov_b32 s24, s18
	v_lshl_add_u64 v[118:119], v[110:111], 0, v[158:159]
	v_cvt_pk_bf16_f32 v110, v114, v115
	v_cvt_pk_bf16_f32 v111, v116, v117
	v_cvt_pk_bf16_f32 v112, v106, v107
	v_cvt_pk_bf16_f32 v113, v108, v109
	global_store_dwordx4 v[118:119], v[110:113], off
	v_cvt_pk_bf16_f32 v102, v102, v103
	v_cvt_pk_bf16_f32 v103, v104, v105
	v_cvt_pk_bf16_f32 v104, v94, v95
	v_or_b32_e32 v94, 32, v154
	v_ashrrev_i32_e32 v95, 31, v94
	v_lshlrev_b64 v[94:95], 12, v[94:95]
	v_lshl_add_u64 v[94:95], s[4:5], 0, v[94:95]
	v_cvt_pk_bf16_f32 v105, v96, v97
	global_store_dwordx4 v[118:119], v[102:105], off offset:256
	s_mov_b64 s[28:29], s[22:23]
	s_mov_b64 s[26:27], s[20:21]
	v_lshl_add_u64 v[102:103], v[94:95], 0, v[158:159]
	v_cvt_pk_bf16_f32 v94, v98, v99
	v_cvt_pk_bf16_f32 v95, v100, v101
	v_cvt_pk_bf16_f32 v96, v90, v91
	v_cvt_pk_bf16_f32 v97, v92, v93
	global_store_dwordx4 v[102:103], v[94:97], off
	v_cvt_pk_bf16_f32 v86, v86, v87
	v_cvt_pk_bf16_f32 v87, v88, v89
	v_cvt_pk_bf16_f32 v88, v78, v79
	v_or_b32_e32 v78, 48, v154
	v_ashrrev_i32_e32 v79, 31, v78
	v_lshlrev_b64 v[78:79], 12, v[78:79]
	v_lshl_add_u64 v[78:79], s[4:5], 0, v[78:79]
	v_cvt_pk_bf16_f32 v89, v80, v81
	global_store_dwordx4 v[102:103], v[86:89], off offset:256
	s_nop 1
	v_lshl_add_u64 v[86:87], v[78:79], 0, v[158:159]
	v_cvt_pk_bf16_f32 v78, v82, v83
	v_cvt_pk_bf16_f32 v79, v84, v85
	v_cvt_pk_bf16_f32 v80, v74, v75
	v_cvt_pk_bf16_f32 v81, v76, v77
	global_store_dwordx4 v[86:87], v[78:81], off
	v_cvt_pk_bf16_f32 v70, v70, v71
	v_cvt_pk_bf16_f32 v71, v72, v73
	v_cvt_pk_bf16_f32 v72, v66, v67
	v_cvt_pk_bf16_f32 v73, v68, v69
	global_store_dwordx4 v[86:87], v[70:73], off offset:256
	v_cvt_pk_bf16_f32 v62, v62, v63
	v_cvt_pk_bf16_f32 v63, v64, v65
	v_cvt_pk_bf16_f32 v64, v58, v59
	v_add_co_u32_e32 v58, vcc, s49, v146
	v_lshl_add_u64 v[66:67], v[146:147], 0, s[8:9]
	s_nop 0
	v_addc_co_u32_e32 v59, vcc, 0, v147, vcc
	v_cvt_pk_bf16_f32 v65, v60, v61
	global_store_dwordx4 v[58:59], v[62:65], off
	v_cvt_pk_bf16_f32 v50, v50, v51
	v_cvt_pk_bf16_f32 v51, v52, v53
	v_cvt_pk_bf16_f32 v52, v42, v43
	v_cvt_pk_bf16_f32 v53, v44, v45
	global_store_dwordx4 v[66:67], v[50:53], off offset:256
	v_cvt_pk_bf16_f32 v42, v54, v55
	v_cvt_pk_bf16_f32 v43, v56, v57
	v_cvt_pk_bf16_f32 v44, v46, v47
	v_add_co_u32_e32 v46, vcc, s50, v146
	s_nop 0
	v_lshl_add_u64 v[50:51], v[146:147], 0, s[10:11]
	v_addc_co_u32_e32 v47, vcc, 0, v147, vcc
	v_cvt_pk_bf16_f32 v45, v48, v49
	global_store_dwordx4 v[46:47], v[42:45], off
	v_cvt_pk_bf16_f32 v34, v34, v35
	v_cvt_pk_bf16_f32 v35, v36, v37
	v_cvt_pk_bf16_f32 v36, v26, v27
	v_cvt_pk_bf16_f32 v37, v28, v29
	global_store_dwordx4 v[50:51], v[34:37], off offset:256
	v_cvt_pk_bf16_f32 v26, v38, v39
	v_cvt_pk_bf16_f32 v27, v40, v41
	v_cvt_pk_bf16_f32 v28, v30, v31
	v_add_co_u32_e32 v30, vcc, s51, v146
	s_nop 0
	v_lshl_add_u64 v[34:35], v[146:147], 0, s[12:13]
	v_addc_co_u32_e32 v31, vcc, 0, v147, vcc
	v_cvt_pk_bf16_f32 v29, v32, v33
	global_store_dwordx4 v[30:31], v[26:29], off
	v_cvt_pk_bf16_f32 v18, v18, v19
	v_cvt_pk_bf16_f32 v19, v20, v21
	v_cvt_pk_bf16_f32 v20, v10, v11
	v_cvt_pk_bf16_f32 v21, v12, v13
	global_store_dwordx4 v[34:35], v[18:21], off offset:256
	v_cvt_pk_bf16_f32 v10, v22, v23
	v_cvt_pk_bf16_f32 v11, v24, v25
	v_cvt_pk_bf16_f32 v12, v14, v15
	v_add_co_u32_e32 v14, vcc, s52, v146
	s_nop 0
	v_lshl_add_u64 v[18:19], v[146:147], 0, s[14:15]
	v_addc_co_u32_e32 v15, vcc, 0, v147, vcc
	s_and_b64 vcc, exec, s[2:3]
	v_cvt_pk_bf16_f32 v13, v16, v17
	global_store_dwordx4 v[14:15], v[10:13], off
	v_cvt_pk_bf16_f32 v6, v6, v7
	v_cvt_pk_bf16_f32 v7, v8, v9
	v_cvt_pk_bf16_f32 v8, v2, v3
	v_cvt_pk_bf16_f32 v9, v4, v5
	global_store_dwordx4 v[18:19], v[6:9], off offset:256
	s_cbranch_vccz .LBB0_646
	s_waitcnt vmcnt(0)
	s_cmpk_gt_u32 s33, 0xff
	s_cbranch_scc1 .LBB0_657
	s_barrier

; #define PG8_STAGE(bufoff, gbase, voff) do { _Pragma("unroll") for (int _i = 0; _i < 2; ++_i) \
;         __builtin_amdgcn_global_load_lds((const unsigned*)((const char*)(gbase) + (voff)[_i]), (PG8_LAS unsigned*)(lds + (bufoff) + ldsw + _i * 8192), 16, 0, 0); } while (0)
; #define PG8_WAIT_V(n) asm volatile("s_waitcnt vmcnt(" #n ")" ::: "memory")
; #define PG8_BAR __builtin_amdgcn_s_barrier()
; template <class Epi>
; __device__ __forceinline__ void gemm_phase(PG8_LAS unsigned char* lds, const Gemm g, const StaticOrder& S, const Epi& E) {
;     ...
;     const char* cA = (const char*)g.A + (size_t)cur.pm * tstep; const char* cB = (const char*)g.Bt + (size_t)cur.pn * tstep;
;     PG8_STAGE(PG8_SB(0, 0), cB, voffB); PG8_STAGE(PG8_SA(0, 0), cA, voffA); PG8_STAGE(PG8_SB(0, 1), cB + hstep, voffB); PG8_STAGE(PG8_SA(0, 1), cA + hstep, voffA);
;     if (wr == 1) PG8_BAR;
;     PG8_WAIT_V(4); PG8_BAR;
.LBB0_714:
	s_andn2_b64 vcc, exec, s[0:1]
	s_cbranch_vccnz .LBB0_814
	v_lshrrev_b32_e32 v3, 1, v10
	v_and_b32_e32 v15, 24, v3
	v_lshrrev_b32_e32 v3, 5, v10
	v_and_b32_e32 v3, 4, v3
	v_bfe_u32 v4, v10, 2, 2
	v_lshlrev_b32_e32 v1, 4, v10
	v_and_b32_e32 v2, 32, v10
	v_bfe_u32 v13, v10, 2, 4
	v_or3_b32 v3, v3, v4, v15
	v_lshrrev_b32_e32 v4, 3, v10
	s_movk_i32 s1, 0x70
	v_bitop3_b32 v11, v1, v2, 48 bitop3:0x6c
	v_and_b32_e32 v12, 64, v10
	v_and_or_b32 v5, v4, s1, v13
	s_movk_i32 s1, 0x60
	v_add_u32_e32 v14, 0x2000, v1
	v_or_b32_e32 v2, v11, v12
	v_and_or_b32 v4, v4, s1, v3
	v_lshrrev_b32_e32 v1, 7, v14
	s_movk_i32 s1, 0xf0
	s_add_u32 s27, s64, 0x1c000000
	v_lshl_or_b32 v134, v4, 12, v2
	v_and_or_b32 v4, v1, s1, v13
	s_movk_i32 s1, 0xe0
	s_addc_u32 s28, s65, 0
	v_and_or_b32 v1, v1, s1, v3
	s_lshr_b32 s1, s26, 6
	s_ashr_i32 s3, s2, 31
	s_ashr_i32 s5, s4, 31
	s_lshr_b32 s0, s26, 8
	s_lshl_b32 s29, s1, 10
	s_lshl_b64 s[8:9], s[2:3], 20
	s_lshl_b64 s[10:11], s[4:5], 20
	s_add_u32 s22, s27, s10
	s_addc_u32 s23, s28, s11
	s_add_i32 s30, s29, 0
	s_add_i32 m0, s30, 0x10000
	v_lshl_or_b32 v138, v1, 12, v2
	global_load_lds_dwordx4 v134, s[22:23]
	s_add_i32 m0, s30, 0x12000
	s_add_u32 s20, s64, s8
	v_lshl_or_b32 v132, v5, 12, v2
	global_load_lds_dwordx4 v138, s[22:23]
	s_addc_u32 s21, s65, s9
	s_mov_b32 m0, s30
	s_add_i32 s31, s30, 0x2000
	v_lshl_or_b32 v136, v4, 12, v2
	global_load_lds_dwordx4 v132, s[20:21]
	s_mov_b32 m0, s31
	s_add_u32 s8, s22, 0x80000
	global_load_lds_dwordx4 v136, s[20:21]
	s_addc_u32 s9, s23, 0
	s_add_i32 m0, s30, 0x14000
	v_mov_b32_e32 v141, 0
	global_load_lds_dwordx4 v134, s[8:9]
	s_add_i32 m0, s30, 0x16000
	v_mov_b32_e32 v135, v141
	global_load_lds_dwordx4 v138, s[8:9]
	s_add_u32 s8, s20, 0x80000
	s_addc_u32 s9, s21, 0
	s_add_i32 s33, s30, 0x4000
	s_mov_b32 m0, s33
	s_add_i32 s34, s30, 0x6000
	global_load_lds_dwordx4 v132, s[8:9]
	s_mov_b32 m0, s34
	v_mov_b32_e32 v139, v141
	global_load_lds_dwordx4 v136, s[8:9]
	v_mov_b32_e32 v133, v141
	v_mov_b32_e32 v137, v141
	s_mov_b32 s35, 0
	s_waitcnt vmcnt(0)
	v_lshl_add_u64 v[8:9], s[22:23], 0, v[134:135]
	v_lshl_add_u64 v[6:7], s[22:23], 0, v[138:139]
	v_lshl_add_u64 v[4:5], s[20:21], 0, v[132:133]
	s_cmp_lg_u32 s0, 1
	v_lshl_add_u64 v[2:3], s[20:21], 0, v[136:137]
	s_cbranch_scc1 .LBB0_717
	s_setprio 1
	s_barrier

; #define PG8_STAGE(bufoff, gbase, voff) do { _Pragma("unroll") for (int _i = 0; _i < 2; ++_i) \
;         __builtin_amdgcn_global_load_lds((const unsigned*)((const char*)(gbase) + (voff)[_i]), (PG8_LAS unsigned*)(lds + (bufoff) + ldsw + _i * 8192), 16, 0, 0); } while (0)
; #define PG8_LDA(dst, b, h) do { _Pragma("unroll") for (int m = 0; m < 4; ++m) _Pragma("unroll") for (int k = 0; k < 2; ++k) dst[m][k] = *(const PG8_LAS bf16x8*)(lds + PG8_SA(b, h) + aoff + m * 2048 + k * 1024); } while (0)
; #define PG8_LDB(dst, b, h) do { _Pragma("unroll") for (int n = 0; n < 2; ++n) _Pragma("unroll") for (int k = 0; k < 2; ++k) dst[n][k] = *(const PG8_LAS bf16x8*)(lds + PG8_SB(b, h) + boff + n * 2048 + k * 1024); } while (0)
; #define PG8_MMA(ai, bj, At, Bt) do { __builtin_amdgcn_s_setprio(1); _Pragma("unroll") for (int m = 0; m < 4; ++m) _Pragma("unroll") for (int n = 0; n < 2; ++n) _Pragma("unroll") for (int k = 0; k < 2; ++k) \
;         acc[ai][bj][m][n] = __builtin_amdgcn_mfma_f32_16x16x32_bf16(Bt[n][k], At[m][k], acc[ai][bj][m][n], 0, 0, 0); __builtin_amdgcn_s_setprio(0); } while (0)
; #define PG8_WAIT_L(n) asm volatile("s_waitcnt lgkmcnt(" #n ")" ::: "memory")
; #define PG8_BAR __builtin_amdgcn_s_barrier()
; #define PG8_SCHED __builtin_amdgcn_sched_barrier(0)
; template <class Epi>
; __device__ __forceinline__ void gemm_phase(PG8_LAS unsigned char* lds, const Gemm g, const StaticOrder& S, const Epi& E) {
;     ...
;             PG8_LDB(B0, 0, 0); PG8_SCHED; PG8_LDA(At, 0, 0); PG8_STAGE(PG8_SA(1, 1), a1 + hstep, voffA);
;             PG8_WAIT_L(8); PG8_BAR; PG8_WAIT_L(0); PG8_MMA(0, 0, At, B0); PG8_BAR; PG8_SCHED;
;             PG8_LDB(B1, 0, 1); PG8_STAGE(PG8_SB(0, 0), b2, voffB);
;             PG8_BAR; PG8_WAIT_L(0); PG8_MMA(0, 1, At, B1); PG8_BAR;
;             PG8_LDA(At, 0, 1); PG8_STAGE(PG8_SA(0, 0), a2, voffA);
;             PG8_BAR; PG8_WAIT_L(0); PG8_MMA(1, 0, At, B0); PG8_BAR; PG8_SCHED;
.LBB0_722:
	ds_read_b128 v[150:153], v159
	ds_read_b128 v[154:157], v159 offset:1024
	ds_read_b128 v[162:165], v159 offset:2048
	ds_read_b128 v[166:169], v159 offset:3072
	s_add_u32 s22, s20, 0xfff80080
	s_addc_u32 s23, s21, -1
	s_cmp_eq_u32 s50, 28
	s_cselect_b32 s25, s3, s23
	s_cselect_b32 s24, s5, s22
	s_cselect_b32 s23, s13, s49
	s_cselect_b32 s22, s15, s48
	v_lshl_add_u64 v[202:203], s[20:21], 0, v[142:143]
	s_add_i32 m0, s30, 0xc000
	ds_read_b128 v[170:173], v160
	ds_read_b128 v[174:177], v160 offset:1024
	ds_read_b128 v[178:181], v160 offset:2048
	ds_read_b128 v[182:185], v160 offset:3072
	ds_read_b128 v[186:189], v160 offset:4096
	ds_read_b128 v[190:193], v160 offset:5120
	ds_read_b128 v[194:197], v160 offset:6144
	ds_read_b128 v[198:201], v160 offset:7168
	global_load_lds_dwordx4 v[202:203], off
	v_lshl_add_u64 v[202:203], s[20:21], 0, v[144:145]
	s_add_i32 m0, s30, 0xe000
	s_nop 0
	global_load_lds_dwordx4 v[202:203], off
	s_waitcnt lgkmcnt(8)
	s_barrier
	s_waitcnt lgkmcnt(0)
	s_nop 0
	s_waitcnt lgkmcnt(0)
	v_mfma_f32_16x16x32_bf16 v[126:129], v[150:153], v[170:173], v[126:129]
	v_mfma_f32_16x16x32_bf16 v[122:125], v[162:165], v[170:173], v[122:125]
	v_mfma_f32_16x16x32_bf16 v[110:113], v[150:153], v[178:181], v[110:113]
	v_mfma_f32_16x16x32_bf16 v[106:109], v[162:165], v[178:181], v[106:109]
	v_mfma_f32_16x16x32_bf16 v[94:97], v[150:153], v[186:189], v[94:97]
	v_mfma_f32_16x16x32_bf16 v[90:93], v[162:165], v[186:189], v[90:93]
	v_mfma_f32_16x16x32_bf16 v[78:81], v[150:153], v[194:197], v[78:81]
	v_mfma_f32_16x16x32_bf16 v[74:77], v[162:165], v[194:197], v[74:77]
	v_mfma_f32_16x16x32_bf16 v[126:129], v[154:157], v[174:177], v[126:129]
	v_mfma_f32_16x16x32_bf16 v[122:125], v[166:169], v[174:177], v[122:125]
	v_mfma_f32_16x16x32_bf16 v[110:113], v[154:157], v[182:185], v[110:113]
	v_mfma_f32_16x16x32_bf16 v[106:109], v[166:169], v[182:185], v[106:109]
	v_mfma_f32_16x16x32_bf16 v[94:97], v[154:157], v[190:193], v[94:97]
	v_mfma_f32_16x16x32_bf16 v[90:93], v[166:169], v[190:193], v[90:93]
	v_mfma_f32_16x16x32_bf16 v[78:81], v[154:157], v[198:201], v[78:81]
	v_mfma_f32_16x16x32_bf16 v[74:77], v[166:169], v[198:201], v[74:77]
	s_nop 0
	s_barrier
	s_add_i32 s51, s43, s29
	v_lshl_add_u64 v[218:219], s[22:23], 0, v[134:135]
	s_mov_b32 m0, s51
	ds_read_b128 v[202:205], v161
	ds_read_b128 v[206:209], v161 offset:1024
	ds_read_b128 v[210:213], v161 offset:2048
	ds_read_b128 v[214:217], v161 offset:3072
	global_load_lds_dwordx4 v[218:219], off
	v_lshl_add_u64 v[220:221], s[22:23], 0, v[138:139]
	s_add_i32 m0, s51, 0x2000
	s_nop 0
	global_load_lds_dwordx4 v[220:221], off
	s_barrier
	s_waitcnt lgkmcnt(0)
	s_nop 0
	s_waitcnt lgkmcnt(0)
	v_mfma_f32_16x16x32_bf16 v[118:121], v[202:205], v[170:173], v[118:121]
	v_mfma_f32_16x16x32_bf16 v[114:117], v[210:213], v[170:173], v[114:117]
	v_mfma_f32_16x16x32_bf16 v[102:105], v[202:205], v[178:181], v[102:105]
	v_mfma_f32_16x16x32_bf16 v[98:101], v[210:213], v[178:181], v[98:101]
	v_mfma_f32_16x16x32_bf16 v[86:89], v[202:205], v[186:189], v[86:89]
	v_mfma_f32_16x16x32_bf16 v[82:85], v[210:213], v[186:189], v[82:85]
	v_mfma_f32_16x16x32_bf16 v[70:73], v[202:205], v[194:197], v[70:73]
	v_mfma_f32_16x16x32_bf16 v[66:69], v[210:213], v[194:197], v[66:69]
	v_mfma_f32_16x16x32_bf16 v[118:121], v[206:209], v[174:177], v[118:121]
	v_mfma_f32_16x16x32_bf16 v[114:117], v[214:217], v[174:177], v[114:117]
	v_mfma_f32_16x16x32_bf16 v[102:105], v[206:209], v[182:185], v[102:105]
	v_mfma_f32_16x16x32_bf16 v[98:101], v[214:217], v[182:185], v[98:101]
	v_mfma_f32_16x16x32_bf16 v[86:89], v[206:209], v[190:193], v[86:89]
	v_mfma_f32_16x16x32_bf16 v[82:85], v[214:217], v[190:193], v[82:85]
	v_mfma_f32_16x16x32_bf16 v[70:73], v[206:209], v[198:201], v[70:73]
	v_mfma_f32_16x16x32_bf16 v[66:69], v[214:217], v[198:201], v[66:69]
	s_nop 0
	s_mov_b32 m0, s30
	v_lshl_add_u64 v[222:223], s[24:25], 0, v[132:133]
	s_barrier
	ds_read_b128 v[170:173], v160 offset:16384
	ds_read_b128 v[174:177], v160 offset:17408
	ds_read_b128 v[178:181], v160 offset:18432
	ds_read_b128 v[182:185], v160 offset:19456
	ds_read_b128 v[186:189], v160 offset:20480
	ds_read_b128 v[190:193], v160 offset:21504
	ds_read_b128 v[194:197], v160 offset:22528
	ds_read_b128 v[198:201], v160 offset:23552
	global_load_lds_dwordx4 v[222:223], off
	v_lshl_add_u64 v[224:225], s[24:25], 0, v[136:137]
	s_mov_b32 m0, s31
	s_nop 0
	global_load_lds_dwordx4 v[224:225], off
	s_barrier
	s_waitcnt lgkmcnt(0)
	s_nop 0
	s_waitcnt lgkmcnt(0)
	v_mfma_f32_16x16x32_bf16 v[62:65], v[150:153], v[170:173], v[62:65]
	v_mfma_f32_16x16x32_bf16 v[58:61], v[162:165], v[170:173], v[58:61]
	v_mfma_f32_16x16x32_bf16 v[46:49], v[150:153], v[178:181], v[46:49]
	v_mfma_f32_16x16x32_bf16 v[42:45], v[162:165], v[178:181], v[42:45]
	v_mfma_f32_16x16x32_bf16 v[30:33], v[150:153], v[186:189], v[30:33]
	v_mfma_f32_16x16x32_bf16 v[26:29], v[162:165], v[186:189], v[26:29]
	v_mfma_f32_16x16x32_bf16 v[14:17], v[150:153], v[194:197], v[14:17]
	v_mfma_f32_16x16x32_bf16 v[10:13], v[162:165], v[194:197], v[10:13]
	v_mfma_f32_16x16x32_bf16 v[62:65], v[154:157], v[174:177], v[62:65]
	v_mfma_f32_16x16x32_bf16 v[58:61], v[166:169], v[174:177], v[58:61]
	v_mfma_f32_16x16x32_bf16 v[46:49], v[154:157], v[182:185], v[46:49]
	v_mfma_f32_16x16x32_bf16 v[42:45], v[166:169], v[182:185], v[42:45]
	v_mfma_f32_16x16x32_bf16 v[30:33], v[154:157], v[190:193], v[30:33]
	v_mfma_f32_16x16x32_bf16 v[26:29], v[166:169], v[190:193], v[26:29]
	v_mfma_f32_16x16x32_bf16 v[14:17], v[154:157], v[198:201], v[14:17]
	v_mfma_f32_16x16x32_bf16 v[10:13], v[166:169], v[198:201], v[10:13]
	s_nop 0
	s_barrier
; #define PG8_STAGE(bufoff, gbase, voff) do { _Pragma("unroll") for (int _i = 0; _i < 2; ++_i) \
;         __builtin_amdgcn_global_load_lds((const unsigned*)((const char*)(gbase) + (voff)[_i]), (PG8_LAS unsigned*)(lds + (bufoff) + ldsw + _i * 8192), 16, 0, 0); } while (0)
; #define PG8_LDA(dst, b, h) do { _Pragma("unroll") for (int m = 0; m < 4; ++m) _Pragma("unroll") for (int k = 0; k < 2; ++k) dst[m][k] = *(const PG8_LAS bf16x8*)(lds + PG8_SA(b, h) + aoff + m * 2048 + k * 1024); } while (0)
; #define PG8_LDB(dst, b, h) do { _Pragma("unroll") for (int n = 0; n < 2; ++n) _Pragma("unroll") for (int k = 0; k < 2; ++k) dst[n][k] = *(const PG8_LAS bf16x8*)(lds + PG8_SB(b, h) + boff + n * 2048 + k * 1024); } while (0)
; #define PG8_MMA(ai, bj, At, Bt) do { __builtin_amdgcn_s_setprio(1); _Pragma("unroll") for (int m = 0; m < 4; ++m) _Pragma("unroll") for (int n = 0; n < 2; ++n) _Pragma("unroll") for (int k = 0; k < 2; ++k) \
;         acc[ai][bj][m][n] = __builtin_amdgcn_mfma_f32_16x16x32_bf16(Bt[n][k], At[m][k], acc[ai][bj][m][n], 0, 0, 0); __builtin_amdgcn_s_setprio(0); } while (0)
; #define PG8_WAIT_V(n) asm volatile("s_waitcnt vmcnt(" #n ")" ::: "memory")
; #define PG8_WAIT_L(n) asm volatile("s_waitcnt lgkmcnt(" #n ")" ::: "memory")
; #define PG8_BAR __builtin_amdgcn_s_barrier()
; #define PG8_SCHED __builtin_amdgcn_sched_barrier(0)
; template <class Epi>
; __device__ __forceinline__ void gemm_phase(PG8_LAS unsigned char* lds, const Gemm g, const StaticOrder& S, const Epi& E) {
;     ...
;             PG8_BAR; PG8_WAIT_L(0); PG8_MMA(1, 0, At, B0); PG8_BAR; PG8_SCHED;
;             PG8_STAGE(PG8_SB(0, 1), b2 + hstep, voffB);
;             PG8_WAIT_V(6); PG8_BAR; PG8_MMA(1, 1, At, B1); PG8_BAR;
;             PG8_LDB(B0, 1, 0); PG8_SCHED; PG8_LDA(At, 1, 0); PG8_STAGE(PG8_SA(0, 1), a2 + hstep, voffA);
;             PG8_WAIT_L(8); PG8_BAR; PG8_WAIT_L(0); PG8_MMA(0, 0, At, B0); PG8_BAR; PG8_SCHED;
;             PG8_LDB(B1, 1, 1); PG8_STAGE(PG8_SB(1, 0), b3, voffB);
;             PG8_BAR; PG8_WAIT_L(0); PG8_MMA(0, 1, At, B1); PG8_BAR;
	s_add_u32 s52, s22, 0x80000
	s_addc_u32 s53, s23, 0
	s_add_i32 s51, s44, s29
	v_lshl_add_u64 v[150:151], s[52:53], 0, v[134:135]
	s_mov_b32 m0, s51
	s_nop 0
	global_load_lds_dwordx4 v[150:151], off
	v_lshl_add_u64 v[150:151], s[52:53], 0, v[138:139]
	s_add_i32 m0, s51, 0x2000
	s_nop 0
	global_load_lds_dwordx4 v[150:151], off
	s_waitcnt vmcnt(6)
	s_barrier
	s_nop 0
	v_mfma_f32_16x16x32_bf16 v[54:57], v[202:205], v[170:173], v[54:57]
	v_mfma_f32_16x16x32_bf16 v[50:53], v[210:213], v[170:173], v[50:53]
	v_mfma_f32_16x16x32_bf16 v[38:41], v[202:205], v[178:181], v[38:41]
	v_mfma_f32_16x16x32_bf16 v[34:37], v[210:213], v[178:181], v[34:37]
	v_mfma_f32_16x16x32_bf16 v[22:25], v[202:205], v[186:189], v[22:25]
	v_mfma_f32_16x16x32_bf16 v[18:21], v[210:213], v[186:189], v[18:21]
	v_mfma_f32_16x16x32_bf16 v[6:9], v[202:205], v[194:197], v[6:9]
	v_mfma_f32_16x16x32_bf16 v[2:5], v[210:213], v[194:197], v[2:5]
	v_mfma_f32_16x16x32_bf16 v[54:57], v[206:209], v[174:177], v[54:57]
	v_mfma_f32_16x16x32_bf16 v[50:53], v[214:217], v[174:177], v[50:53]
	v_mfma_f32_16x16x32_bf16 v[38:41], v[206:209], v[182:185], v[38:41]
	v_mfma_f32_16x16x32_bf16 v[34:37], v[214:217], v[182:185], v[34:37]
	v_mfma_f32_16x16x32_bf16 v[22:25], v[206:209], v[190:193], v[22:25]
	v_mfma_f32_16x16x32_bf16 v[18:21], v[214:217], v[190:193], v[18:21]
	v_mfma_f32_16x16x32_bf16 v[6:9], v[206:209], v[198:201], v[6:9]
	v_mfma_f32_16x16x32_bf16 v[2:5], v[214:217], v[198:201], v[2:5]
	s_nop 0
	s_add_i32 s51, 0, 0x18000
	v_add_u32_e32 v140, s51, v131
	s_barrier
	ds_read_b128 v[150:153], v140
	ds_read_b128 v[154:157], v140 offset:1024
	ds_read_b128 v[162:165], v140 offset:2048
	ds_read_b128 v[166:169], v140 offset:3072
	s_add_u32 s24, s24, 0x80000
	s_addc_u32 s25, s25, 0
	s_mov_b32 m0, s33
	v_lshl_add_u64 v[202:203], s[24:25], 0, v[132:133]
	ds_read_b128 v[170:173], v160 offset:32768
	ds_read_b128 v[174:177], v160 offset:33792
	ds_read_b128 v[178:181], v160 offset:34816
	ds_read_b128 v[182:185], v160 offset:35840
	ds_read_b128 v[186:189], v160 offset:36864
	ds_read_b128 v[190:193], v160 offset:37888
	ds_read_b128 v[194:197], v160 offset:38912
	ds_read_b128 v[198:201], v160 offset:39936
	global_load_lds_dwordx4 v[202:203], off
	v_lshl_add_u64 v[202:203], s[24:25], 0, v[136:137]
	s_mov_b32 m0, s34
	s_nop 0
	global_load_lds_dwordx4 v[202:203], off
	s_waitcnt lgkmcnt(8)
	s_barrier
	s_waitcnt lgkmcnt(0)
	s_nop 0
	s_waitcnt lgkmcnt(0)
	v_mfma_f32_16x16x32_bf16 v[126:129], v[150:153], v[170:173], v[126:129]
	v_mfma_f32_16x16x32_bf16 v[122:125], v[162:165], v[170:173], v[122:125]
	v_mfma_f32_16x16x32_bf16 v[110:113], v[150:153], v[178:181], v[110:113]
	v_mfma_f32_16x16x32_bf16 v[106:109], v[162:165], v[178:181], v[106:109]
	v_mfma_f32_16x16x32_bf16 v[94:97], v[150:153], v[186:189], v[94:97]
	v_mfma_f32_16x16x32_bf16 v[90:93], v[162:165], v[186:189], v[90:93]
	v_mfma_f32_16x16x32_bf16 v[78:81], v[150:153], v[194:197], v[78:81]
	v_mfma_f32_16x16x32_bf16 v[74:77], v[162:165], v[194:197], v[74:77]
	v_mfma_f32_16x16x32_bf16 v[126:129], v[154:157], v[174:177], v[126:129]
	v_mfma_f32_16x16x32_bf16 v[122:125], v[166:169], v[174:177], v[122:125]
	v_mfma_f32_16x16x32_bf16 v[110:113], v[154:157], v[182:185], v[110:113]
	v_mfma_f32_16x16x32_bf16 v[106:109], v[166:169], v[182:185], v[106:109]
	v_mfma_f32_16x16x32_bf16 v[94:97], v[154:157], v[190:193], v[94:97]
	v_mfma_f32_16x16x32_bf16 v[90:93], v[166:169], v[190:193], v[90:93]
	v_mfma_f32_16x16x32_bf16 v[78:81], v[154:157], v[198:201], v[78:81]
	v_mfma_f32_16x16x32_bf16 v[74:77], v[166:169], v[198:201], v[74:77]
	s_nop 0
	s_barrier
	s_add_i32 s24, 0, 0x1c000
	s_add_i32 s25, s51, s29
	v_add_u32_e32 v140, s24, v131
	v_lshl_add_u64 v[218:219], v[218:219], 0, s[10:11]
	s_mov_b32 m0, s25
	ds_read_b128 v[202:205], v140
	ds_read_b128 v[206:209], v140 offset:1024
	ds_read_b128 v[210:213], v140 offset:2048
	ds_read_b128 v[214:217], v140 offset:3072
	global_load_lds_dwordx4 v[218:219], off
	v_lshl_add_u64 v[218:219], v[220:221], 0, s[10:11]
	s_add_i32 m0, s25, 0x2000
	s_nop 0
	global_load_lds_dwordx4 v[218:219], off
	s_barrier
	s_waitcnt lgkmcnt(0)
	s_nop 0
	s_waitcnt lgkmcnt(0)
	v_mfma_f32_16x16x32_bf16 v[118:121], v[202:205], v[170:173], v[118:121]
	v_mfma_f32_16x16x32_bf16 v[114:117], v[210:213], v[170:173], v[114:117]
	v_mfma_f32_16x16x32_bf16 v[102:105], v[202:205], v[178:181], v[102:105]
	v_mfma_f32_16x16x32_bf16 v[98:101], v[210:213], v[178:181], v[98:101]
	v_mfma_f32_16x16x32_bf16 v[86:89], v[202:205], v[186:189], v[86:89]
	v_mfma_f32_16x16x32_bf16 v[82:85], v[210:213], v[186:189], v[82:85]
	v_mfma_f32_16x16x32_bf16 v[70:73], v[202:205], v[194:197], v[70:73]
	v_mfma_f32_16x16x32_bf16 v[66:69], v[210:213], v[194:197], v[66:69]
	v_mfma_f32_16x16x32_bf16 v[118:121], v[206:209], v[174:177], v[118:121]
	v_mfma_f32_16x16x32_bf16 v[114:117], v[214:217], v[174:177], v[114:117]
	v_mfma_f32_16x16x32_bf16 v[102:105], v[206:209], v[182:185], v[102:105]
	v_mfma_f32_16x16x32_bf16 v[98:101], v[214:217], v[182:185], v[98:101]
	v_mfma_f32_16x16x32_bf16 v[86:89], v[206:209], v[190:193], v[86:89]
	v_mfma_f32_16x16x32_bf16 v[82:85], v[214:217], v[190:193], v[82:85]
	v_mfma_f32_16x16x32_bf16 v[70:73], v[206:209], v[198:201], v[70:73]
	v_mfma_f32_16x16x32_bf16 v[66:69], v[214:217], v[198:201], v[66:69]
	s_nop 0
	s_mov_b32 m0, s38
	v_lshl_add_u64 v[218:219], v[222:223], 0, s[10:11]
	s_barrier
; #define PG8_STAGE(bufoff, gbase, voff) do { _Pragma("unroll") for (int _i = 0; _i < 2; ++_i) \
;         __builtin_amdgcn_global_load_lds((const unsigned*)((const char*)(gbase) + (voff)[_i]), (PG8_LAS unsigned*)(lds + (bufoff) + ldsw + _i * 8192), 16, 0, 0); } while (0)
; #define PG8_LDA(dst, b, h) do { _Pragma("unroll") for (int m = 0; m < 4; ++m) _Pragma("unroll") for (int k = 0; k < 2; ++k) dst[m][k] = *(const PG8_LAS bf16x8*)(lds + PG8_SA(b, h) + aoff + m * 2048 + k * 1024); } while (0)
; #define PG8_MMA(ai, bj, At, Bt) do { __builtin_amdgcn_s_setprio(1); _Pragma("unroll") for (int m = 0; m < 4; ++m) _Pragma("unroll") for (int n = 0; n < 2; ++n) _Pragma("unroll") for (int k = 0; k < 2; ++k) \
;         acc[ai][bj][m][n] = __builtin_amdgcn_mfma_f32_16x16x32_bf16(Bt[n][k], At[m][k], acc[ai][bj][m][n], 0, 0, 0); __builtin_amdgcn_s_setprio(0); } while (0)
; #define PG8_WAIT_V(n) asm volatile("s_waitcnt vmcnt(" #n ")" ::: "memory")
; #define PG8_WAIT_L(n) asm volatile("s_waitcnt lgkmcnt(" #n ")" ::: "memory")
; #define PG8_BAR __builtin_amdgcn_s_barrier()
; #define PG8_SCHED __builtin_amdgcn_sched_barrier(0)
; template <class Epi>
; __device__ __forceinline__ void gemm_phase(PG8_LAS unsigned char* lds, const Gemm g, const StaticOrder& S, const Epi& E) {
;     ...
;             PG8_BAR; PG8_WAIT_L(0); PG8_MMA(0, 1, At, B1); PG8_BAR;
;             PG8_LDA(At, 1, 1); PG8_STAGE(PG8_SA(1, 0), a3, voffA);
;             PG8_BAR; PG8_WAIT_L(0); PG8_MMA(1, 0, At, B0); PG8_BAR; PG8_SCHED;
;             PG8_STAGE(PG8_SB(1, 1), b3 + hstep, voffB);
;             PG8_WAIT_V(6); PG8_BAR; PG8_MMA(1, 1, At, B1); PG8_BAR;
;         }
;         E(acc, cur, wr, wc, fr, fq);
	ds_read_b128 v[170:173], v160 offset:49152
	ds_read_b128 v[174:177], v160 offset:50176
	ds_read_b128 v[178:181], v160 offset:51200
	ds_read_b128 v[182:185], v160 offset:52224
	ds_read_b128 v[186:189], v160 offset:53248
	ds_read_b128 v[190:193], v160 offset:54272
	ds_read_b128 v[194:197], v160 offset:55296
	ds_read_b128 v[198:201], v160 offset:56320
	global_load_lds_dwordx4 v[218:219], off
	v_lshl_add_u64 v[218:219], v[224:225], 0, s[10:11]
	s_mov_b32 m0, s39
	s_nop 0
	global_load_lds_dwordx4 v[218:219], off
	s_barrier
	s_waitcnt lgkmcnt(0)
	s_nop 0
	s_waitcnt lgkmcnt(0)
	v_mfma_f32_16x16x32_bf16 v[62:65], v[150:153], v[170:173], v[62:65]
	v_mfma_f32_16x16x32_bf16 v[58:61], v[162:165], v[170:173], v[58:61]
	v_mfma_f32_16x16x32_bf16 v[46:49], v[150:153], v[178:181], v[46:49]
	v_mfma_f32_16x16x32_bf16 v[42:45], v[162:165], v[178:181], v[42:45]
	v_mfma_f32_16x16x32_bf16 v[30:33], v[150:153], v[186:189], v[30:33]
	v_mfma_f32_16x16x32_bf16 v[26:29], v[162:165], v[186:189], v[26:29]
	v_mfma_f32_16x16x32_bf16 v[14:17], v[150:153], v[194:197], v[14:17]
	v_mfma_f32_16x16x32_bf16 v[10:13], v[162:165], v[194:197], v[10:13]
	v_mfma_f32_16x16x32_bf16 v[62:65], v[154:157], v[174:177], v[62:65]
	v_mfma_f32_16x16x32_bf16 v[58:61], v[166:169], v[174:177], v[58:61]
	v_mfma_f32_16x16x32_bf16 v[46:49], v[154:157], v[182:185], v[46:49]
	v_mfma_f32_16x16x32_bf16 v[42:45], v[166:169], v[182:185], v[42:45]
	v_mfma_f32_16x16x32_bf16 v[30:33], v[154:157], v[190:193], v[30:33]
	v_mfma_f32_16x16x32_bf16 v[26:29], v[166:169], v[190:193], v[26:29]
	v_mfma_f32_16x16x32_bf16 v[14:17], v[154:157], v[198:201], v[14:17]
	v_mfma_f32_16x16x32_bf16 v[10:13], v[166:169], v[198:201], v[10:13]
	s_nop 0
	s_barrier
	s_add_u32 s22, s22, 0x80080
	s_addc_u32 s23, s23, 0
	s_add_i32 s24, s24, s29
	v_lshl_add_u64 v[150:151], s[22:23], 0, v[134:135]
	s_mov_b32 m0, s24
	s_nop 0
	global_load_lds_dwordx4 v[150:151], off
	v_lshl_add_u64 v[150:151], s[22:23], 0, v[138:139]
	s_add_i32 m0, s24, 0x2000
	s_nop 0
	global_load_lds_dwordx4 v[150:151], off
	s_waitcnt vmcnt(6)
	s_barrier
	s_nop 0
	v_mfma_f32_16x16x32_bf16 v[54:57], v[202:205], v[170:173], v[54:57]
	v_mfma_f32_16x16x32_bf16 v[50:53], v[210:213], v[170:173], v[50:53]
	v_mfma_f32_16x16x32_bf16 v[38:41], v[202:205], v[178:181], v[38:41]
	v_mfma_f32_16x16x32_bf16 v[34:37], v[210:213], v[178:181], v[34:37]
	v_mfma_f32_16x16x32_bf16 v[22:25], v[202:205], v[186:189], v[22:25]
	v_mfma_f32_16x16x32_bf16 v[18:21], v[210:213], v[186:189], v[18:21]
	v_mfma_f32_16x16x32_bf16 v[6:9], v[202:205], v[194:197], v[6:9]
	v_mfma_f32_16x16x32_bf16 v[2:5], v[210:213], v[194:197], v[2:5]
	v_mfma_f32_16x16x32_bf16 v[54:57], v[206:209], v[174:177], v[54:57]
	v_mfma_f32_16x16x32_bf16 v[50:53], v[214:217], v[174:177], v[50:53]
	v_mfma_f32_16x16x32_bf16 v[38:41], v[206:209], v[182:185], v[38:41]
	v_mfma_f32_16x16x32_bf16 v[34:37], v[214:217], v[182:185], v[34:37]
	v_mfma_f32_16x16x32_bf16 v[22:25], v[206:209], v[190:193], v[22:25]
	v_mfma_f32_16x16x32_bf16 v[18:21], v[214:217], v[190:193], v[18:21]
	v_mfma_f32_16x16x32_bf16 v[6:9], v[206:209], v[198:201], v[6:9]
	v_mfma_f32_16x16x32_bf16 v[2:5], v[214:217], v[198:201], v[2:5]
	s_nop 0
	s_add_i32 s50, s50, 2
	s_add_u32 s20, s20, 0x100
	s_addc_u32 s21, s21, 0
	s_add_u32 s48, s48, 0x100
	s_addc_u32 s49, s49, 0
	s_cmp_gt_u32 s50, 29
	s_barrier
	s_cbranch_scc0 .LBB0_722
	v_lshl_add_u32 v152, s2, 8, v1
	s_lshl_b32 s13, s4, 8
	v_or_b32_e32 v150, s13, v158
	v_mad_i64_i32 v[154:155], s[2:3], v152, s45, 0
	v_cmp_lt_i32_e64 s[2:3], s46, v150
	s_and_saveexec_b64 s[20:21], s[2:3]
	s_xor_b64 s[20:21], exec, s[20:21]
	s_cbranch_execz .LBB0_726
	s_cmpk_gt_u32 s13, 0x317f
	s_cbranch_scc1 .LBB0_726
	v_lshl_add_u64 v[156:157], s[8:9], 0, v[154:155]
	v_mov_b32_e32 v151, v141
	v_lshl_add_u64 v[156:157], v[150:151], 1, v[156:157]
	v_add_co_u32_e32 v156, vcc, 0xffffa000, v156
	v_cvt_pk_bf16_f32 v162, v126, v127
	v_cvt_pk_bf16_f32 v163, v128, v129
	v_cvt_pk_bf16_f32 v164, v122, v123
	v_cvt_pk_bf16_f32 v165, v124, v125
	s_nop 1
	v_addc_co_u32_e32 v157, vcc, -1, v157, vcc
	global_store_dwordx4 v[156:157], v[162:165], off

; #define PG8_STAGE(bufoff, gbase, voff) do { _Pragma("unroll") for (int _i = 0; _i < 2; ++_i) \
;         __builtin_amdgcn_global_load_lds((const unsigned*)((const char*)(gbase) + (voff)[_i]), (PG8_LAS unsigned*)(lds + (bufoff) + ldsw + _i * 8192), 16, 0, 0); } while (0)
; #define PG8_WAIT_V(n) asm volatile("s_waitcnt vmcnt(" #n ")" ::: "memory")
; #define PG8_BAR __builtin_amdgcn_s_barrier()
; template <class Epi>
; __device__ __forceinline__ void gemm_phase(PG8_LAS unsigned char* lds, const Gemm g, const StaticOrder& S, const Epi& E) {
;     ...
;     const char* cA = (const char*)g.A + (size_t)cur.pm * tstep; const char* cB = (const char*)g.Bt + (size_t)cur.pn * tstep;
;     PG8_STAGE(PG8_SB(0, 0), cB, voffB); PG8_STAGE(PG8_SA(0, 0), cA, voffA); PG8_STAGE(PG8_SB(0, 1), cB + hstep, voffB); PG8_STAGE(PG8_SA(0, 1), cA + hstep, voffA);
;     if (wr == 1) PG8_BAR;
;     PG8_WAIT_V(4); PG8_BAR;
.LBB0_1046:
	s_waitcnt vmcnt(0)
	v_lshrrev_b32_e32 v3, 1, v10
	s_ashr_i32 s0, s3, 3
	v_and_b32_e32 v14, 24, v3
	v_lshrrev_b32_e32 v3, 5, v10
	s_add_u32 s35, s64, 0x1c000000
	v_and_b32_e32 v3, 4, v3
	v_bfe_u32 v4, v10, 2, 2
	s_addc_u32 s36, s65, 0
	v_lshlrev_b32_e32 v1, 4, v10
	v_and_b32_e32 v2, 32, v10
	v_bfe_u32 v13, v10, 2, 4
	v_or3_b32 v3, v3, v4, v14
	v_lshrrev_b32_e32 v4, 3, v10
	s_movk_i32 s3, 0x70
	s_add_i32 s0, s2, s0
	v_bitop3_b32 v11, v1, v2, 48 bitop3:0x6c
	v_and_b32_e32 v12, 64, v10
	v_and_or_b32 v5, v4, s3, v13
	s_movk_i32 s3, 0x60
	v_add_u32_e32 v15, 0x2000, v1
	s_ashr_i32 s2, s0, 31
	v_or_b32_e32 v2, v11, v12
	v_and_or_b32 v4, v4, s3, v3
	v_lshrrev_b32_e32 v1, 7, v15
	s_movk_i32 s3, 0xf0
	s_lshr_b32 s2, s2, 25
	v_lshl_or_b32 v134, v4, 12, v2
	v_and_or_b32 v4, v1, s3, v13
	s_movk_i32 s3, 0xe0
	s_add_i32 s2, s0, s2
	v_and_or_b32 v1, v1, s3, v3
	s_ashr_i32 s3, s2, 7
	s_and_b32 s2, s2, 0xffffff80
	s_sub_i32 s2, s0, s2
	s_bfe_i32 s0, s2, 0x80000
	s_bfe_u32 s0, s0, 0x3000c
	s_add_i32 s4, s2, s0
	s_bfe_i32 s0, s4, 0x80000
	s_and_b32 s4, s4, 0xf8
	s_sub_i32 s2, s2, s4
	s_lshl_b32 s3, s3, 3
	s_sext_i32_i16 s0, s0
	s_sext_i32_i8 s2, s2
	s_lshr_b32 s1, s33, 8
	s_lshr_b32 s0, s0, 3
	s_add_i32 s2, s3, s2
	s_lshr_b32 s12, s33, 6
	s_ashr_i32 s3, s2, 31
	s_bfe_i64 s[6:7], s[0:1], 0x100000
	s_lshl_b32 s37, s12, 10
	s_lshl_b64 s[4:5], s[2:3], 20
	s_lshl_b64 s[6:7], s[6:7], 20
	s_add_u32 s6, s35, s6
	s_addc_u32 s7, s36, s7
	s_add_i32 s38, s37, 0
	s_add_i32 m0, s38, 0x10000
	v_lshl_or_b32 v138, v1, 12, v2
	global_load_lds_dwordx4 v134, s[6:7]
	s_add_i32 m0, s38, 0x12000
	s_add_u32 s4, s64, s4
	v_lshl_or_b32 v132, v5, 12, v2
	global_load_lds_dwordx4 v138, s[6:7]
	s_addc_u32 s5, s65, s5
	s_mov_b32 m0, s38
	s_add_i32 s39, s38, 0x2000
	v_lshl_or_b32 v136, v4, 12, v2
	global_load_lds_dwordx4 v132, s[4:5]
	s_mov_b32 m0, s39
	s_add_u32 s10, s6, 0x80000
	global_load_lds_dwordx4 v136, s[4:5]
	s_addc_u32 s11, s7, 0
	s_add_i32 m0, s38, 0x14000
	v_mov_b32_e32 v135, 0
	global_load_lds_dwordx4 v134, s[10:11]
	s_add_i32 m0, s38, 0x16000
	v_mov_b32_e32 v139, v135
	global_load_lds_dwordx4 v138, s[10:11]
	s_add_u32 s10, s4, 0x80000
	s_addc_u32 s11, s5, 0
	s_add_i32 s40, s38, 0x4000
	s_mov_b32 m0, s40
	s_add_i32 s41, s38, 0x6000
	global_load_lds_dwordx4 v132, s[10:11]
	s_mov_b32 m0, s41
	v_mov_b32_e32 v133, v135
	global_load_lds_dwordx4 v136, s[10:11]
	v_mov_b32_e32 v137, v135
	s_mov_b32 s42, 0
	v_lshl_add_u64 v[8:9], s[6:7], 0, v[134:135]
	v_lshl_add_u64 v[6:7], s[6:7], 0, v[138:139]
	v_lshl_add_u64 v[4:5], s[4:5], 0, v[132:133]
	s_cmp_lg_u32 s1, 1
	v_lshl_add_u64 v[2:3], s[4:5], 0, v[136:137]
	s_cbranch_scc1 .LBB0_1048
	s_setprio 1
	s_barrier

; #define PG8_STAGE(bufoff, gbase, voff) do { _Pragma("unroll") for (int _i = 0; _i < 2; ++_i) \
;         __builtin_amdgcn_global_load_lds((const unsigned*)((const char*)(gbase) + (voff)[_i]), (PG8_LAS unsigned*)(lds + (bufoff) + ldsw + _i * 8192), 16, 0, 0); } while (0)
; #define PG8_LDA(dst, b, h) do { _Pragma("unroll") for (int m = 0; m < 4; ++m) _Pragma("unroll") for (int k = 0; k < 2; ++k) dst[m][k] = *(const PG8_LAS bf16x8*)(lds + PG8_SA(b, h) + aoff + m * 2048 + k * 1024); } while (0)
; #define PG8_LDB(dst, b, h) do { _Pragma("unroll") for (int n = 0; n < 2; ++n) _Pragma("unroll") for (int k = 0; k < 2; ++k) dst[n][k] = *(const PG8_LAS bf16x8*)(lds + PG8_SB(b, h) + boff + n * 2048 + k * 1024); } while (0)
; #define PG8_MMA(ai, bj, At, Bt) do { __builtin_amdgcn_s_setprio(1); _Pragma("unroll") for (int m = 0; m < 4; ++m) _Pragma("unroll") for (int n = 0; n < 2; ++n) _Pragma("unroll") for (int k = 0; k < 2; ++k) \
;         acc[ai][bj][m][n] = __builtin_amdgcn_mfma_f32_16x16x32_bf16(Bt[n][k], At[m][k], acc[ai][bj][m][n], 0, 0, 0); __builtin_amdgcn_s_setprio(0); } while (0)
; #define PG8_WAIT_L(n) asm volatile("s_waitcnt lgkmcnt(" #n ")" ::: "memory")
; #define PG8_BAR __builtin_amdgcn_s_barrier()
; #define PG8_SCHED __builtin_amdgcn_sched_barrier(0)
; template <class Epi>
; __device__ __forceinline__ void gemm_phase(PG8_LAS unsigned char* lds, const Gemm g, const StaticOrder& S, const Epi& E) {
;     ...
;             PG8_LDB(B0, 0, 0); PG8_SCHED; PG8_LDA(At, 0, 0); PG8_STAGE(PG8_SA(1, 1), a1 + hstep, voffA);
;             PG8_WAIT_L(8); PG8_BAR; PG8_WAIT_L(0); PG8_MMA(0, 0, At, B0); PG8_BAR; PG8_SCHED;
;             PG8_LDB(B1, 0, 1); PG8_STAGE(PG8_SB(0, 0), b2, voffB);
;             PG8_BAR; PG8_WAIT_L(0); PG8_MMA(0, 1, At, B1); PG8_BAR;
;             PG8_LDA(At, 0, 1); PG8_STAGE(PG8_SA(0, 0), a2, voffA);
;             PG8_BAR; PG8_WAIT_L(0); PG8_MMA(1, 0, At, B0); PG8_BAR; PG8_SCHED;
.LBB0_1056:
	ds_read_b128 v[148:151], v155
	ds_read_b128 v[158:161], v155 offset:1024
	ds_read_b128 v[162:165], v155 offset:2048
	ds_read_b128 v[166:169], v155 offset:3072
	s_add_u32 s6, s4, 0xfff80080
	s_addc_u32 s7, s5, -1
	s_cmp_eq_u32 s56, 28
	s_cselect_b32 s31, s25, s7
	s_cselect_b32 s30, s52, s6
	s_cselect_b32 s7, s23, s55
	s_cselect_b32 s6, s53, s54
	v_lshl_add_u64 v[152:153], s[4:5], 0, v[140:141]
	s_add_i32 m0, s38, 0xc000
	ds_read_b128 v[170:173], v156
	ds_read_b128 v[174:177], v156 offset:1024
	ds_read_b128 v[178:181], v156 offset:2048
	ds_read_b128 v[182:185], v156 offset:3072
	ds_read_b128 v[186:189], v156 offset:4096
	ds_read_b128 v[190:193], v156 offset:5120
	ds_read_b128 v[194:197], v156 offset:6144
	ds_read_b128 v[198:201], v156 offset:7168
	global_load_lds_dwordx4 v[152:153], off
	v_lshl_add_u64 v[152:153], s[4:5], 0, v[142:143]
	s_add_i32 m0, s38, 0xe000
	s_nop 0
	global_load_lds_dwordx4 v[152:153], off
	s_waitcnt lgkmcnt(8)
	s_barrier
	s_waitcnt lgkmcnt(0)
	s_nop 0
	s_waitcnt lgkmcnt(0)
	v_mfma_f32_16x16x32_bf16 v[126:129], v[148:151], v[170:173], v[126:129]
	v_mfma_f32_16x16x32_bf16 v[122:125], v[162:165], v[170:173], v[122:125]
	v_mfma_f32_16x16x32_bf16 v[110:113], v[148:151], v[178:181], v[110:113]
	v_mfma_f32_16x16x32_bf16 v[106:109], v[162:165], v[178:181], v[106:109]
	v_mfma_f32_16x16x32_bf16 v[94:97], v[148:151], v[186:189], v[94:97]
	v_mfma_f32_16x16x32_bf16 v[90:93], v[162:165], v[186:189], v[90:93]
	v_mfma_f32_16x16x32_bf16 v[78:81], v[148:151], v[194:197], v[78:81]
	v_mfma_f32_16x16x32_bf16 v[74:77], v[162:165], v[194:197], v[74:77]
	v_mfma_f32_16x16x32_bf16 v[126:129], v[158:161], v[174:177], v[126:129]
	v_mfma_f32_16x16x32_bf16 v[122:125], v[166:169], v[174:177], v[122:125]
	v_mfma_f32_16x16x32_bf16 v[110:113], v[158:161], v[182:185], v[110:113]
	v_mfma_f32_16x16x32_bf16 v[106:109], v[166:169], v[182:185], v[106:109]
	v_mfma_f32_16x16x32_bf16 v[94:97], v[158:161], v[190:193], v[94:97]
	v_mfma_f32_16x16x32_bf16 v[90:93], v[166:169], v[190:193], v[90:93]
	v_mfma_f32_16x16x32_bf16 v[78:81], v[158:161], v[198:201], v[78:81]
	v_mfma_f32_16x16x32_bf16 v[74:77], v[166:169], v[198:201], v[74:77]
	s_nop 0
	s_barrier
	s_add_i32 s57, s46, s37
	v_lshl_add_u64 v[152:153], s[6:7], 0, v[134:135]
	s_mov_b32 m0, s57
	ds_read_b128 v[202:205], v157
	ds_read_b128 v[206:209], v157 offset:1024
	ds_read_b128 v[210:213], v157 offset:2048
	ds_read_b128 v[214:217], v157 offset:3072
	global_load_lds_dwordx4 v[152:153], off
	v_lshl_add_u64 v[218:219], s[6:7], 0, v[138:139]
	s_add_i32 m0, s57, 0x2000
	s_nop 0
	global_load_lds_dwordx4 v[218:219], off
	s_barrier
	s_waitcnt lgkmcnt(0)
	s_nop 0
	s_waitcnt lgkmcnt(0)
	v_mfma_f32_16x16x32_bf16 v[118:121], v[202:205], v[170:173], v[118:121]
	v_mfma_f32_16x16x32_bf16 v[114:117], v[210:213], v[170:173], v[114:117]
	v_mfma_f32_16x16x32_bf16 v[102:105], v[202:205], v[178:181], v[102:105]
	v_mfma_f32_16x16x32_bf16 v[98:101], v[210:213], v[178:181], v[98:101]
	v_mfma_f32_16x16x32_bf16 v[86:89], v[202:205], v[186:189], v[86:89]
	v_mfma_f32_16x16x32_bf16 v[82:85], v[210:213], v[186:189], v[82:85]
	v_mfma_f32_16x16x32_bf16 v[70:73], v[202:205], v[194:197], v[70:73]
	v_mfma_f32_16x16x32_bf16 v[66:69], v[210:213], v[194:197], v[66:69]
	v_mfma_f32_16x16x32_bf16 v[118:121], v[206:209], v[174:177], v[118:121]
	v_mfma_f32_16x16x32_bf16 v[114:117], v[214:217], v[174:177], v[114:117]
	v_mfma_f32_16x16x32_bf16 v[102:105], v[206:209], v[182:185], v[102:105]
	v_mfma_f32_16x16x32_bf16 v[98:101], v[214:217], v[182:185], v[98:101]
	v_mfma_f32_16x16x32_bf16 v[86:89], v[206:209], v[190:193], v[86:89]
	v_mfma_f32_16x16x32_bf16 v[82:85], v[214:217], v[190:193], v[82:85]
	v_mfma_f32_16x16x32_bf16 v[70:73], v[206:209], v[198:201], v[70:73]
	v_mfma_f32_16x16x32_bf16 v[66:69], v[214:217], v[198:201], v[66:69]
	s_nop 0
	s_mov_b32 m0, s38
	v_lshl_add_u64 v[220:221], s[30:31], 0, v[132:133]
	s_barrier
	ds_read_b128 v[170:173], v156 offset:16384
	ds_read_b128 v[174:177], v156 offset:17408
	ds_read_b128 v[178:181], v156 offset:18432
	ds_read_b128 v[182:185], v156 offset:19456
	ds_read_b128 v[186:189], v156 offset:20480
	ds_read_b128 v[190:193], v156 offset:21504
	ds_read_b128 v[194:197], v156 offset:22528
	ds_read_b128 v[198:201], v156 offset:23552
	global_load_lds_dwordx4 v[220:221], off
	v_lshl_add_u64 v[222:223], s[30:31], 0, v[136:137]
	s_mov_b32 m0, s39
	s_nop 0
	global_load_lds_dwordx4 v[222:223], off
	s_barrier
	s_waitcnt lgkmcnt(0)
	s_nop 0
	s_waitcnt lgkmcnt(0)
	v_mfma_f32_16x16x32_bf16 v[62:65], v[148:151], v[170:173], v[62:65]
	v_mfma_f32_16x16x32_bf16 v[58:61], v[162:165], v[170:173], v[58:61]
	v_mfma_f32_16x16x32_bf16 v[46:49], v[148:151], v[178:181], v[46:49]
	v_mfma_f32_16x16x32_bf16 v[42:45], v[162:165], v[178:181], v[42:45]
	v_mfma_f32_16x16x32_bf16 v[30:33], v[148:151], v[186:189], v[30:33]
	v_mfma_f32_16x16x32_bf16 v[26:29], v[162:165], v[186:189], v[26:29]
	v_mfma_f32_16x16x32_bf16 v[14:17], v[148:151], v[194:197], v[14:17]
	v_mfma_f32_16x16x32_bf16 v[10:13], v[162:165], v[194:197], v[10:13]
	v_mfma_f32_16x16x32_bf16 v[62:65], v[158:161], v[174:177], v[62:65]
	v_mfma_f32_16x16x32_bf16 v[58:61], v[166:169], v[174:177], v[58:61]
	v_mfma_f32_16x16x32_bf16 v[46:49], v[158:161], v[182:185], v[46:49]
	v_mfma_f32_16x16x32_bf16 v[42:45], v[166:169], v[182:185], v[42:45]
	v_mfma_f32_16x16x32_bf16 v[30:33], v[158:161], v[190:193], v[30:33]
	v_mfma_f32_16x16x32_bf16 v[26:29], v[166:169], v[190:193], v[26:29]
	v_mfma_f32_16x16x32_bf16 v[14:17], v[158:161], v[198:201], v[14:17]
	v_mfma_f32_16x16x32_bf16 v[10:13], v[166:169], v[198:201], v[10:13]
	s_nop 0
	s_barrier
; #define PG8_STAGE(bufoff, gbase, voff) do { _Pragma("unroll") for (int _i = 0; _i < 2; ++_i) \
;         __builtin_amdgcn_global_load_lds((const unsigned*)((const char*)(gbase) + (voff)[_i]), (PG8_LAS unsigned*)(lds + (bufoff) + ldsw + _i * 8192), 16, 0, 0); } while (0)
; #define PG8_LDA(dst, b, h) do { _Pragma("unroll") for (int m = 0; m < 4; ++m) _Pragma("unroll") for (int k = 0; k < 2; ++k) dst[m][k] = *(const PG8_LAS bf16x8*)(lds + PG8_SA(b, h) + aoff + m * 2048 + k * 1024); } while (0)
; #define PG8_LDB(dst, b, h) do { _Pragma("unroll") for (int n = 0; n < 2; ++n) _Pragma("unroll") for (int k = 0; k < 2; ++k) dst[n][k] = *(const PG8_LAS bf16x8*)(lds + PG8_SB(b, h) + boff + n * 2048 + k * 1024); } while (0)
; #define PG8_MMA(ai, bj, At, Bt) do { __builtin_amdgcn_s_setprio(1); _Pragma("unroll") for (int m = 0; m < 4; ++m) _Pragma("unroll") for (int n = 0; n < 2; ++n) _Pragma("unroll") for (int k = 0; k < 2; ++k) \
;         acc[ai][bj][m][n] = __builtin_amdgcn_mfma_f32_16x16x32_bf16(Bt[n][k], At[m][k], acc[ai][bj][m][n], 0, 0, 0); __builtin_amdgcn_s_setprio(0); } while (0)
; #define PG8_WAIT_V(n) asm volatile("s_waitcnt vmcnt(" #n ")" ::: "memory")
; #define PG8_WAIT_L(n) asm volatile("s_waitcnt lgkmcnt(" #n ")" ::: "memory")
; #define PG8_BAR __builtin_amdgcn_s_barrier()
; #define PG8_SCHED __builtin_amdgcn_sched_barrier(0)
; template <class Epi>
; __device__ __forceinline__ void gemm_phase(PG8_LAS unsigned char* lds, const Gemm g, const StaticOrder& S, const Epi& E) {
;     ...
;             PG8_STAGE(PG8_SB(0, 1), b2 + hstep, voffB);
;             PG8_WAIT_V(6); PG8_BAR; PG8_MMA(1, 1, At, B1); PG8_BAR;
;             PG8_LDB(B0, 1, 0); PG8_SCHED; PG8_LDA(At, 1, 0); PG8_STAGE(PG8_SA(0, 1), a2 + hstep, voffA);
;             PG8_WAIT_L(8); PG8_BAR; PG8_WAIT_L(0); PG8_MMA(0, 0, At, B0); PG8_BAR; PG8_SCHED;
;             PG8_LDB(B1, 1, 1); PG8_STAGE(PG8_SB(1, 0), b3, voffB);
;             PG8_BAR; PG8_WAIT_L(0); PG8_MMA(0, 1, At, B1); PG8_BAR;
	s_add_u32 s58, s6, 0x80000
	s_addc_u32 s59, s7, 0
	s_add_i32 s57, s47, s37
	v_lshl_add_u64 v[148:149], s[58:59], 0, v[134:135]
	s_mov_b32 m0, s57
	s_nop 0
	global_load_lds_dwordx4 v[148:149], off
	v_lshl_add_u64 v[148:149], s[58:59], 0, v[138:139]
	s_add_i32 m0, s57, 0x2000
	s_nop 0
	global_load_lds_dwordx4 v[148:149], off
	s_waitcnt vmcnt(6)
	s_barrier
	s_nop 0
	v_mfma_f32_16x16x32_bf16 v[54:57], v[202:205], v[170:173], v[54:57]
	v_mfma_f32_16x16x32_bf16 v[50:53], v[210:213], v[170:173], v[50:53]
	v_mfma_f32_16x16x32_bf16 v[38:41], v[202:205], v[178:181], v[38:41]
	v_mfma_f32_16x16x32_bf16 v[34:37], v[210:213], v[178:181], v[34:37]
	v_mfma_f32_16x16x32_bf16 v[22:25], v[202:205], v[186:189], v[22:25]
	v_mfma_f32_16x16x32_bf16 v[18:21], v[210:213], v[186:189], v[18:21]
	v_mfma_f32_16x16x32_bf16 v[6:9], v[202:205], v[194:197], v[6:9]
	v_mfma_f32_16x16x32_bf16 v[2:5], v[210:213], v[194:197], v[2:5]
	v_mfma_f32_16x16x32_bf16 v[54:57], v[206:209], v[174:177], v[54:57]
	v_mfma_f32_16x16x32_bf16 v[50:53], v[214:217], v[174:177], v[50:53]
	v_mfma_f32_16x16x32_bf16 v[38:41], v[206:209], v[182:185], v[38:41]
	v_mfma_f32_16x16x32_bf16 v[34:37], v[214:217], v[182:185], v[34:37]
	v_mfma_f32_16x16x32_bf16 v[22:25], v[206:209], v[190:193], v[22:25]
	v_mfma_f32_16x16x32_bf16 v[18:21], v[214:217], v[190:193], v[18:21]
	v_mfma_f32_16x16x32_bf16 v[6:9], v[206:209], v[198:201], v[6:9]
	v_mfma_f32_16x16x32_bf16 v[2:5], v[214:217], v[198:201], v[2:5]
	s_nop 0
	s_add_i32 s57, 0, 0x18000
	v_add_u32_e32 v166, s57, v131
	s_barrier
	ds_read_b128 v[148:151], v166
	ds_read_b128 v[158:161], v166 offset:1024
	ds_read_b128 v[162:165], v166 offset:2048
	ds_read_b128 v[166:169], v166 offset:3072
	s_add_u32 s30, s30, 0x80000
	s_addc_u32 s31, s31, 0
	s_mov_b32 m0, s40
	v_lshl_add_u64 v[202:203], s[30:31], 0, v[132:133]
	ds_read_b128 v[170:173], v156 offset:32768
	ds_read_b128 v[174:177], v156 offset:33792
	ds_read_b128 v[178:181], v156 offset:34816
	ds_read_b128 v[182:185], v156 offset:35840
	ds_read_b128 v[186:189], v156 offset:36864
	ds_read_b128 v[190:193], v156 offset:37888
	ds_read_b128 v[194:197], v156 offset:38912
	ds_read_b128 v[198:201], v156 offset:39936
	global_load_lds_dwordx4 v[202:203], off
	v_lshl_add_u64 v[202:203], s[30:31], 0, v[136:137]
	s_mov_b32 m0, s41
	s_nop 0
	global_load_lds_dwordx4 v[202:203], off
	s_waitcnt lgkmcnt(8)
	s_barrier
	s_waitcnt lgkmcnt(0)
	s_nop 0
	s_waitcnt lgkmcnt(0)
	v_mfma_f32_16x16x32_bf16 v[126:129], v[148:151], v[170:173], v[126:129]
	v_mfma_f32_16x16x32_bf16 v[122:125], v[162:165], v[170:173], v[122:125]
	v_mfma_f32_16x16x32_bf16 v[110:113], v[148:151], v[178:181], v[110:113]
	v_mfma_f32_16x16x32_bf16 v[106:109], v[162:165], v[178:181], v[106:109]
	v_mfma_f32_16x16x32_bf16 v[94:97], v[148:151], v[186:189], v[94:97]
	v_mfma_f32_16x16x32_bf16 v[90:93], v[162:165], v[186:189], v[90:93]
	v_mfma_f32_16x16x32_bf16 v[78:81], v[148:151], v[194:197], v[78:81]
	v_mfma_f32_16x16x32_bf16 v[74:77], v[162:165], v[194:197], v[74:77]
	v_mfma_f32_16x16x32_bf16 v[126:129], v[158:161], v[174:177], v[126:129]
	v_mfma_f32_16x16x32_bf16 v[122:125], v[166:169], v[174:177], v[122:125]
	v_mfma_f32_16x16x32_bf16 v[110:113], v[158:161], v[182:185], v[110:113]
	v_mfma_f32_16x16x32_bf16 v[106:109], v[166:169], v[182:185], v[106:109]
	v_mfma_f32_16x16x32_bf16 v[94:97], v[158:161], v[190:193], v[94:97]
	v_mfma_f32_16x16x32_bf16 v[90:93], v[166:169], v[190:193], v[90:93]
	v_mfma_f32_16x16x32_bf16 v[78:81], v[158:161], v[198:201], v[78:81]
	v_mfma_f32_16x16x32_bf16 v[74:77], v[166:169], v[198:201], v[74:77]
	s_nop 0
	s_barrier
	s_add_i32 s30, 0, 0x1c000
	s_add_i32 s31, s57, s37
	v_add_u32_e32 v214, s30, v131
	v_lshl_add_u64 v[152:153], v[152:153], 0, s[12:13]
	s_mov_b32 m0, s31
	ds_read_b128 v[202:205], v214
	ds_read_b128 v[206:209], v214 offset:1024
	ds_read_b128 v[210:213], v214 offset:2048
	ds_read_b128 v[214:217], v214 offset:3072
	global_load_lds_dwordx4 v[152:153], off
	v_lshl_add_u64 v[152:153], v[218:219], 0, s[12:13]
	s_add_i32 m0, s31, 0x2000
	s_nop 0
	global_load_lds_dwordx4 v[152:153], off
	s_barrier
	s_waitcnt lgkmcnt(0)
	s_nop 0
	s_waitcnt lgkmcnt(0)
	v_mfma_f32_16x16x32_bf16 v[118:121], v[202:205], v[170:173], v[118:121]
	v_mfma_f32_16x16x32_bf16 v[114:117], v[210:213], v[170:173], v[114:117]
	v_mfma_f32_16x16x32_bf16 v[102:105], v[202:205], v[178:181], v[102:105]
	v_mfma_f32_16x16x32_bf16 v[98:101], v[210:213], v[178:181], v[98:101]
	v_mfma_f32_16x16x32_bf16 v[86:89], v[202:205], v[186:189], v[86:89]
	v_mfma_f32_16x16x32_bf16 v[82:85], v[210:213], v[186:189], v[82:85]
	v_mfma_f32_16x16x32_bf16 v[70:73], v[202:205], v[194:197], v[70:73]
	v_mfma_f32_16x16x32_bf16 v[66:69], v[210:213], v[194:197], v[66:69]
	v_mfma_f32_16x16x32_bf16 v[118:121], v[206:209], v[174:177], v[118:121]
	v_mfma_f32_16x16x32_bf16 v[114:117], v[214:217], v[174:177], v[114:117]
	v_mfma_f32_16x16x32_bf16 v[102:105], v[206:209], v[182:185], v[102:105]
	v_mfma_f32_16x16x32_bf16 v[98:101], v[214:217], v[182:185], v[98:101]
	v_mfma_f32_16x16x32_bf16 v[86:89], v[206:209], v[190:193], v[86:89]
	v_mfma_f32_16x16x32_bf16 v[82:85], v[214:217], v[190:193], v[82:85]
	v_mfma_f32_16x16x32_bf16 v[70:73], v[206:209], v[198:201], v[70:73]
	v_mfma_f32_16x16x32_bf16 v[66:69], v[214:217], v[198:201], v[66:69]
	s_nop 0
	s_mov_b32 m0, s43
	v_lshl_add_u64 v[152:153], v[220:221], 0, s[12:13]
	s_barrier
	ds_read_b128 v[170:173], v156 offset:49152
	ds_read_b128 v[174:177], v156 offset:50176
	ds_read_b128 v[178:181], v156 offset:51200
	ds_read_b128 v[182:185], v156 offset:52224
	ds_read_b128 v[186:189], v156 offset:53248
	ds_read_b128 v[190:193], v156 offset:54272
	ds_read_b128 v[194:197], v156 offset:55296
	ds_read_b128 v[198:201], v156 offset:56320
	global_load_lds_dwordx4 v[152:153], off
	v_lshl_add_u64 v[152:153], v[222:223], 0, s[12:13]
	s_mov_b32 m0, s44
	s_nop 0
	global_load_lds_dwordx4 v[152:153], off
	s_barrier
; #define PG8_STAGE(bufoff, gbase, voff) do { _Pragma("unroll") for (int _i = 0; _i < 2; ++_i) \
;         __builtin_amdgcn_global_load_lds((const unsigned*)((const char*)(gbase) + (voff)[_i]), (PG8_LAS unsigned*)(lds + (bufoff) + ldsw + _i * 8192), 16, 0, 0); } while (0)
; #define PG8_LDA(dst, b, h) do { _Pragma("unroll") for (int m = 0; m < 4; ++m) _Pragma("unroll") for (int k = 0; k < 2; ++k) dst[m][k] = *(const PG8_LAS bf16x8*)(lds + PG8_SA(b, h) + aoff + m * 2048 + k * 1024); } while (0)
; #define PG8_MMA(ai, bj, At, Bt) do { __builtin_amdgcn_s_setprio(1); _Pragma("unroll") for (int m = 0; m < 4; ++m) _Pragma("unroll") for (int n = 0; n < 2; ++n) _Pragma("unroll") for (int k = 0; k < 2; ++k) \
;         acc[ai][bj][m][n] = __builtin_amdgcn_mfma_f32_16x16x32_bf16(Bt[n][k], At[m][k], acc[ai][bj][m][n], 0, 0, 0); __builtin_amdgcn_s_setprio(0); } while (0)
; #define PG8_WAIT_V(n) asm volatile("s_waitcnt vmcnt(" #n ")" ::: "memory")
; #define PG8_WAIT_L(n) asm volatile("s_waitcnt lgkmcnt(" #n ")" ::: "memory")
; #define PG8_BAR __builtin_amdgcn_s_barrier()
; #define PG8_SCHED __builtin_amdgcn_sched_barrier(0)
; template <class Epi>
; __device__ __forceinline__ void gemm_phase(PG8_LAS unsigned char* lds, const Gemm g, const StaticOrder& S, const Epi& E) {
;     ...
;             PG8_BAR; PG8_WAIT_L(0); PG8_MMA(0, 1, At, B1); PG8_BAR;
;             PG8_LDA(At, 1, 1); PG8_STAGE(PG8_SA(1, 0), a3, voffA);
;             PG8_BAR; PG8_WAIT_L(0); PG8_MMA(1, 0, At, B0); PG8_BAR; PG8_SCHED;
;             PG8_STAGE(PG8_SB(1, 1), b3 + hstep, voffB);
;             PG8_WAIT_V(6); PG8_BAR; PG8_MMA(1, 1, At, B1); PG8_BAR;
	s_waitcnt lgkmcnt(0)
	s_nop 0
	s_waitcnt lgkmcnt(0)
	v_mfma_f32_16x16x32_bf16 v[62:65], v[148:151], v[170:173], v[62:65]
	v_mfma_f32_16x16x32_bf16 v[58:61], v[162:165], v[170:173], v[58:61]
	v_mfma_f32_16x16x32_bf16 v[46:49], v[148:151], v[178:181], v[46:49]
	v_mfma_f32_16x16x32_bf16 v[42:45], v[162:165], v[178:181], v[42:45]
	v_mfma_f32_16x16x32_bf16 v[30:33], v[148:151], v[186:189], v[30:33]
	v_mfma_f32_16x16x32_bf16 v[26:29], v[162:165], v[186:189], v[26:29]
	v_mfma_f32_16x16x32_bf16 v[14:17], v[148:151], v[194:197], v[14:17]
	v_mfma_f32_16x16x32_bf16 v[10:13], v[162:165], v[194:197], v[10:13]
	v_mfma_f32_16x16x32_bf16 v[62:65], v[158:161], v[174:177], v[62:65]
	v_mfma_f32_16x16x32_bf16 v[58:61], v[166:169], v[174:177], v[58:61]
	v_mfma_f32_16x16x32_bf16 v[46:49], v[158:161], v[182:185], v[46:49]
	v_mfma_f32_16x16x32_bf16 v[42:45], v[166:169], v[182:185], v[42:45]
	v_mfma_f32_16x16x32_bf16 v[30:33], v[158:161], v[190:193], v[30:33]
	v_mfma_f32_16x16x32_bf16 v[26:29], v[166:169], v[190:193], v[26:29]
	v_mfma_f32_16x16x32_bf16 v[14:17], v[158:161], v[198:201], v[14:17]
	v_mfma_f32_16x16x32_bf16 v[10:13], v[166:169], v[198:201], v[10:13]
	s_nop 0
	s_barrier
	s_add_u32 s6, s6, 0x80080
	s_addc_u32 s7, s7, 0
	s_add_i32 s30, s30, s37
	v_lshl_add_u64 v[148:149], s[6:7], 0, v[134:135]
	s_mov_b32 m0, s30
	s_nop 0
	global_load_lds_dwordx4 v[148:149], off
	v_lshl_add_u64 v[148:149], s[6:7], 0, v[138:139]
	s_add_i32 m0, s30, 0x2000
	s_nop 0
	global_load_lds_dwordx4 v[148:149], off
	s_waitcnt vmcnt(6)
	s_barrier
	s_nop 0
	v_mfma_f32_16x16x32_bf16 v[54:57], v[202:205], v[170:173], v[54:57]
	v_mfma_f32_16x16x32_bf16 v[50:53], v[210:213], v[170:173], v[50:53]
	v_mfma_f32_16x16x32_bf16 v[38:41], v[202:205], v[178:181], v[38:41]
	v_mfma_f32_16x16x32_bf16 v[34:37], v[210:213], v[178:181], v[34:37]
	v_mfma_f32_16x16x32_bf16 v[22:25], v[202:205], v[186:189], v[22:25]
	v_mfma_f32_16x16x32_bf16 v[18:21], v[210:213], v[186:189], v[18:21]
	v_mfma_f32_16x16x32_bf16 v[6:9], v[202:205], v[194:197], v[6:9]
	v_mfma_f32_16x16x32_bf16 v[2:5], v[210:213], v[194:197], v[2:5]
	v_mfma_f32_16x16x32_bf16 v[54:57], v[206:209], v[174:177], v[54:57]
	v_mfma_f32_16x16x32_bf16 v[50:53], v[214:217], v[174:177], v[50:53]
	v_mfma_f32_16x16x32_bf16 v[38:41], v[206:209], v[182:185], v[38:41]
	v_mfma_f32_16x16x32_bf16 v[34:37], v[214:217], v[182:185], v[34:37]
	v_mfma_f32_16x16x32_bf16 v[22:25], v[206:209], v[190:193], v[22:25]
	v_mfma_f32_16x16x32_bf16 v[18:21], v[214:217], v[190:193], v[18:21]
	v_mfma_f32_16x16x32_bf16 v[6:9], v[206:209], v[198:201], v[6:9]
	v_mfma_f32_16x16x32_bf16 v[2:5], v[214:217], v[198:201], v[2:5]
	s_nop 0
	s_add_i32 s56, s56, 2
	s_add_u32 s4, s4, 0x100
	s_addc_u32 s5, s5, 0
	s_add_u32 s54, s54, 0x100
	s_addc_u32 s55, s55, 0
	s_cmp_gt_u32 s56, 29
	s_barrier
	s_cbranch_scc0 .LBB0_1056
	v_lshl_add_u32 v150, s2, 8, v1
	v_lshl_or_b32 v148, s3, 8, v154
	v_ashrrev_i32_e32 v151, 31, v150
	v_lshlrev_b64 v[152:153], 13, v[150:151]
	v_ashrrev_i32_e32 v149, 31, v148
	v_lshl_add_u64 v[158:159], s[10:11], 0, v[152:153]
	v_lshlrev_b64 v[152:153], 1, v[148:149]
	v_lshl_add_u64 v[148:149], v[158:159], 0, v[152:153]
	s_mov_b64 s[98:99], 0x20000
	global_load_dwordx4 v[186:189], v[148:149], off
	global_load_dwordx4 v[190:193], v[148:149], off offset:256
	v_lshl_add_u64 v[252:253], v[148:149], 0, s[98:99]
	global_load_dwordx4 v[194:197], v[252:253], off
	global_load_dwordx4 v[198:201], v[252:253], off offset:256
	v_lshl_add_u64 v[254:255], v[252:253], 0, s[98:99]
	global_load_dwordx4 v[202:205], v[254:255], off
	global_load_dwordx4 v[206:209], v[254:255], off offset:256
	v_lshl_add_u64 v[252:253], v[254:255], 0, s[98:99]
	global_load_dwordx4 v[210:213], v[252:253], off
	global_load_dwordx4 v[214:217], v[252:253], off offset:256
	v_lshl_add_u64 v[254:255], v[148:149], 0, s[14:15]
	global_load_dwordx4 v[218:221], v[254:255], off
	global_load_dwordx4 v[222:225], v[254:255], off offset:256
	v_lshl_add_u64 v[252:253], v[148:149], 0, s[16:17]
	global_load_dwordx4 v[226:229], v[252:253], off
	global_load_dwordx4 v[230:233], v[252:253], off offset:256
	v_lshl_add_u64 v[254:255], v[148:149], 0, s[18:19]
	global_load_dwordx4 v[234:237], v[254:255], off
	global_load_dwordx4 v[238:241], v[254:255], off offset:256
	v_lshl_add_u64 v[252:253], v[148:149], 0, s[20:21]
	global_load_dwordx4 v[242:245], v[252:253], off
	global_load_dwordx4 v[246:249], v[252:253], off offset:256
	v_mul_f32_e32 v151, 0xbfb8aa3b, v126
	v_mul_f32_e32 v162, 0xbfb8aa3b, v122
	v_exp_f32_e32 v151, v151
	v_mul_f32_e32 v163, 0xbfb8aa3b, v127
	v_exp_f32_e32 v162, v162
	v_exp_f32_e32 v163, v163
	v_add_f32_e32 v151, 1.0, v151
	v_div_scale_f32 v166, s[2:3], v151, v151, v126
	v_add_f32_e32 v162, 1.0, v162
	v_add_f32_e32 v163, 1.0, v163
	v_div_scale_f32 v168, s[2:3], v162, v162, v122
	v_rcp_f32_e32 v174, v166
	v_mul_f32_e32 v164, 0xbfb8aa3b, v123
	v_div_scale_f32 v170, s[4:5], v163, v163, v127
	v_rcp_f32_e32 v175, v168
	v_exp_f32_e32 v164, v164
	v_rcp_f32_e32 v176, v170
	v_fma_f32 v178, -v166, v174, 1.0
	v_div_scale_f32 v167, vcc, v126, v151, v126
	v_fma_f32 v179, -v168, v175, 1.0
	v_fmac_f32_e32 v174, v178, v174
	v_add_f32_e32 v164, 1.0, v164
	v_div_scale_f32 v169, s[2:3], v122, v162, v122
	v_fma_f32 v180, -v170, v176, 1.0
	v_fmac_f32_e32 v175, v179, v175
	v_mul_f32_e32 v178, v167, v174
	v_div_scale_f32 v171, s[4:5], v127, v163, v127
	v_div_scale_f32 v172, s[6:7], v164, v164, v123
	v_fmac_f32_e32 v176, v180, v176
	v_mul_f32_e32 v179, v169, v175
	v_fma_f32 v182, -v166, v178, v167
	v_rcp_f32_e32 v177, v172
	v_mul_f32_e32 v180, v171, v176
	v_fma_f32 v183, -v168, v179, v169
	v_fmac_f32_e32 v178, v182, v174
	v_mul_f32_e32 v165, 0xbfb8aa3b, v128
	v_fma_f32 v184, -v170, v180, v171
	v_fmac_f32_e32 v179, v183, v175
	v_fma_f32 v166, -v166, v178, v167
	v_exp_f32_e32 v165, v165
	v_fmac_f32_e32 v180, v184, v176
	v_fma_f32 v167, -v168, v179, v169
	v_div_fmas_f32 v166, v166, v174, v178
	s_mov_b64 vcc, s[2:3]
	v_fma_f32 v168, -v170, v180, v171
	v_div_fixup_f32 v126, v166, v151, v126
	v_div_fmas_f32 v151, v167, v175, v179
	s_mov_b64 vcc, s[4:5]
	v_fma_f32 v181, -v172, v177, 1.0
	v_div_fixup_f32 v122, v151, v162, v122
	v_div_fmas_f32 v151, v168, v176, v180
	v_div_scale_f32 v173, s[6:7], v123, v164, v123
	v_fmac_f32_e32 v177, v181, v177
	v_div_fixup_f32 v127, v151, v163, v127
	v_mul_f32_e32 v181, v173, v177
	v_fma_f32 v185, -v172, v181, v173
	v_fmac_f32_e32 v181, v185, v177
	v_fma_f32 v169, -v172, v181, v173
	s_mov_b64 vcc, s[6:7]
	s_mov_b64 s[6:7], s[28:29]
	s_mov_b64 s[4:5], s[26:27]
	s_waitcnt vmcnt(14)
	v_mov_b32_e32 v158, v186
	v_mov_b32_e32 v159, v187
	v_mov_b32_e32 v160, v188
	v_mov_b32_e32 v161, v189
	v_lshlrev_b32_e32 v151, 16, v158
	v_and_b32_e32 v158, 0xffff0000, v158
	v_lshlrev_b32_e32 v163, 16, v160
	v_mul_f32_e32 v126, v126, v151
	v_mul_f32_e32 v151, v122, v163
	v_mul_f32_e32 v122, v127, v158
	v_add_f32_e32 v127, 1.0, v165
	v_div_scale_f32 v158, s[2:3], v127, v127, v128
	v_rcp_f32_e32 v163, v158
	v_div_fmas_f32 v165, v169, v177, v181
	v_and_b32_e32 v160, 0xffff0000, v160
	v_div_fixup_f32 v123, v165, v164, v123
	v_mul_f32_e32 v160, v123, v160
	v_fma_f32 v123, -v158, v163, 1.0
	v_mul_f32_e32 v165, 0xbfb8aa3b, v124
	v_fmac_f32_e32 v163, v123, v163
	v_div_scale_f32 v123, vcc, v128, v127, v128
	v_exp_f32_e32 v165, v165
	v_mul_f32_e32 v164, v123, v163
	v_fma_f32 v167, -v158, v164, v123
	v_fmac_f32_e32 v164, v167, v163
	v_fma_f32 v123, -v158, v164, v123
	v_add_f32_e32 v158, 1.0, v165
	v_div_scale_f32 v165, s[2:3], v158, v158, v124
	v_rcp_f32_e32 v167, v165
	v_div_fmas_f32 v123, v123, v163, v164
	v_lshlrev_b32_e32 v162, 16, v159
	v_div_fixup_f32 v123, v123, v127, v128
	v_mul_f32_e32 v123, v123, v162
	v_mul_f32_e32 v162, 0xbfb8aa3b, v129
	v_exp_f32_e32 v162, v162
	v_fma_f32 v127, -v165, v167, 1.0
	v_fmac_f32_e32 v167, v127, v167
	v_div_scale_f32 v127, vcc, v124, v158, v124
	v_mul_f32_e32 v128, v127, v167
	v_fma_f32 v163, -v165, v128, v127
	v_add_f32_e32 v162, 1.0, v162
	v_fmac_f32_e32 v128, v163, v167
	v_div_scale_f32 v163, s[2:3], v162, v162, v129
	v_rcp_f32_e32 v164, v163
	v_fma_f32 v127, -v165, v128, v127
	v_div_fmas_f32 v127, v127, v167, v128
	v_lshlrev_b32_e32 v166, 16, v161
	v_div_fixup_f32 v124, v127, v158, v124
	v_mul_f32_e32 v158, 0xbfb8aa3b, v125
	v_mul_f32_e32 v127, v124, v166
	v_fma_f32 v124, -v163, v164, 1.0
	v_exp_f32_e32 v158, v158
	v_fmac_f32_e32 v164, v124, v164
	v_div_scale_f32 v124, vcc, v129, v162, v129
	v_mul_f32_e32 v128, v124, v164
	v_fma_f32 v165, -v163, v128, v124
	v_fmac_f32_e32 v128, v165, v164
	v_add_f32_e32 v158, 1.0, v158
	v_fma_f32 v124, -v163, v128, v124
	v_div_scale_f32 v163, s[2:3], v158, v158, v125
	v_rcp_f32_e32 v165, v163
	v_div_fmas_f32 v124, v124, v164, v128
	v_and_b32_e32 v159, 0xffff0000, v159
	v_div_fixup_f32 v124, v124, v162, v129
	v_fma_f32 v128, -v163, v165, 1.0
	v_fmac_f32_e32 v165, v128, v165
	v_div_scale_f32 v128, vcc, v125, v158, v125
	v_mul_f32_e32 v129, v128, v165
	v_mul_f32_e32 v124, v124, v159
	v_fma_f32 v159, -v163, v129, v128
	v_fmac_f32_e32 v129, v159, v165
	v_fma_f32 v128, -v163, v129, v128
	v_div_fmas_f32 v128, v128, v165, v129
	v_and_b32_e32 v161, 0xffff0000, v161
	v_div_fixup_f32 v125, v128, v158, v125
	v_mul_f32_e32 v125, v125, v161
	v_cvt_pk_bf16_f32 v122, v126, v122
	v_cvt_pk_bf16_f32 v123, v123, v124
	v_cvt_pk_bf16_f32 v124, v151, v160
	v_cvt_pk_bf16_f32 v125, v127, v125
	v_mul_f32_e32 v162, 0xbfb8aa3b, v114
	global_store_dwordx4 v[148:149], v[122:125], off
	v_exp_f32_e32 v162, v162
	s_waitcnt vmcnt(14)
	v_mov_b32_e32 v126, v190
	v_mov_b32_e32 v127, v191
	v_mov_b32_e32 v128, v192
	v_mov_b32_e32 v129, v193
	v_lshlrev_b32_e32 v159, 16, v129
	v_mul_f32_e32 v124, 0xbfb8aa3b, v118
	v_exp_f32_e32 v124, v124
	v_lshlrev_b32_e32 v122, 16, v126
	v_and_b32_e32 v123, 0xffff0000, v126
	v_lshlrev_b32_e32 v125, 16, v127
	v_add_f32_e32 v124, 1.0, v124
	v_div_scale_f32 v151, s[2:3], v124, v124, v118
	v_rcp_f32_e32 v158, v151
	v_and_b32_e32 v126, 0xffff0000, v127
	v_lshlrev_b32_e32 v127, 16, v128
	v_and_b32_e32 v128, 0xffff0000, v128
	v_fma_f32 v160, -v151, v158, 1.0
	v_fmac_f32_e32 v158, v160, v158
	v_div_scale_f32 v160, vcc, v118, v124, v118
	v_mul_f32_e32 v161, v160, v158
	v_fma_f32 v163, -v151, v161, v160
	v_fmac_f32_e32 v161, v163, v158
	v_fma_f32 v151, -v151, v161, v160
	v_add_f32_e32 v160, 1.0, v162
	v_div_scale_f32 v162, s[2:3], v160, v160, v114
	v_rcp_f32_e32 v163, v162
	v_div_fmas_f32 v151, v151, v158, v161
	v_div_fixup_f32 v118, v151, v124, v118
	v_mul_f32_e32 v151, 0xbfb8aa3b, v119
	v_exp_f32_e32 v151, v151
	v_mul_f32_e32 v118, v118, v122
	v_fma_f32 v122, -v162, v163, 1.0
	v_fmac_f32_e32 v163, v122, v163
	v_div_scale_f32 v122, vcc, v114, v160, v114
	v_mul_f32_e32 v124, v122, v163
	v_fma_f32 v158, -v162, v124, v122
	v_add_f32_e32 v151, 1.0, v151
	v_fmac_f32_e32 v124, v158, v163
	v_div_scale_f32 v158, s[2:3], v151, v151, v119
	v_fma_f32 v122, -v162, v124, v122
	v_rcp_f32_e32 v161, v158
	v_div_fmas_f32 v122, v122, v163, v124
	v_div_fixup_f32 v114, v122, v160, v114
	v_mul_f32_e32 v114, v114, v127
	v_mul_f32_e32 v127, 0xbfb8aa3b, v115
	v_fma_f32 v122, -v158, v161, 1.0
	v_exp_f32_e32 v127, v127
	v_fmac_f32_e32 v161, v122, v161
	v_div_scale_f32 v122, vcc, v119, v151, v119
	v_mul_f32_e32 v124, v122, v161
	v_fma_f32 v160, -v158, v124, v122
	v_fmac_f32_e32 v124, v160, v161
	v_add_f32_e32 v127, 1.0, v127
	v_fma_f32 v122, -v158, v124, v122
	v_div_scale_f32 v158, s[2:3], v127, v127, v115
	v_rcp_f32_e32 v160, v158
	v_div_fmas_f32 v122, v122, v161, v124
	v_mul_f32_e32 v124, 0xbfb8aa3b, v120
	v_exp_f32_e32 v124, v124
	v_div_fixup_f32 v119, v122, v151, v119
	v_fma_f32 v122, -v158, v160, 1.0
	v_fmac_f32_e32 v160, v122, v160
	v_div_scale_f32 v122, vcc, v115, v127, v115
	v_mul_f32_e32 v119, v119, v123
	v_mul_f32_e32 v123, v122, v160
	v_fma_f32 v151, -v158, v123, v122
	v_add_f32_e32 v124, 1.0, v124
	v_fmac_f32_e32 v123, v151, v160
	v_div_scale_f32 v151, s[2:3], v124, v124, v120
	v_fma_f32 v122, -v158, v123, v122
	v_rcp_f32_e32 v158, v151
	v_div_fmas_f32 v122, v122, v160, v123
	v_div_fixup_f32 v115, v122, v127, v115
	v_mul_f32_e32 v127, 0xbfb8aa3b, v116
	v_exp_f32_e32 v127, v127
	v_fma_f32 v122, -v151, v158, 1.0
	v_fmac_f32_e32 v158, v122, v158
	v_div_scale_f32 v122, vcc, v120, v124, v120
	v_mul_f32_e32 v123, v122, v158
	v_mul_f32_e32 v115, v115, v128
	v_fma_f32 v128, -v151, v123, v122
	v_add_f32_e32 v127, 1.0, v127
	v_fmac_f32_e32 v123, v128, v158
	v_div_scale_f32 v128, s[2:3], v127, v127, v116
	v_fma_f32 v122, -v151, v123, v122
	v_rcp_f32_e32 v151, v128
	v_div_fmas_f32 v122, v122, v158, v123
	v_div_fixup_f32 v120, v122, v124, v120
	v_mul_f32_e32 v124, 0xbfb8aa3b, v121
	v_exp_f32_e32 v124, v124
	v_fma_f32 v122, -v128, v151, 1.0
	v_fmac_f32_e32 v151, v122, v151
	v_div_scale_f32 v122, vcc, v116, v127, v116
	v_mul_f32_e32 v123, v122, v151
	v_mul_f32_e32 v120, v120, v125
	v_fma_f32 v125, -v128, v123, v122
	v_add_f32_e32 v124, 1.0, v124
	v_fmac_f32_e32 v123, v125, v151
	v_div_scale_f32 v125, s[2:3], v124, v124, v121
	v_fma_f32 v122, -v128, v123, v122
	v_rcp_f32_e32 v128, v125
	v_div_fmas_f32 v122, v122, v151, v123
	v_div_fixup_f32 v116, v122, v127, v116
	v_mul_f32_e32 v122, v116, v159
	v_fma_f32 v116, -v125, v128, 1.0
	v_mul_f32_e32 v127, 0xbfb8aa3b, v117
	v_fmac_f32_e32 v128, v116, v128
	v_div_scale_f32 v116, vcc, v121, v124, v121
	v_exp_f32_e32 v127, v127
	v_mul_f32_e32 v123, v116, v128
	v_fma_f32 v151, -v125, v123, v116
	v_fmac_f32_e32 v123, v151, v128
	v_fma_f32 v116, -v125, v123, v116
	v_add_f32_e32 v125, 1.0, v127
	v_div_scale_f32 v127, s[2:3], v125, v125, v117
	v_rcp_f32_e32 v151, v127
	v_div_fmas_f32 v116, v116, v128, v123
	v_div_fixup_f32 v116, v116, v124, v121
	v_mul_f32_e32 v121, v116, v126
	v_fma_f32 v116, -v127, v151, 1.0
	v_fmac_f32_e32 v151, v116, v151
	v_div_scale_f32 v116, vcc, v117, v125, v117
	v_mul_f32_e32 v123, v116, v151
	v_fma_f32 v124, -v127, v123, v116
	v_fmac_f32_e32 v123, v124, v151
	v_fma_f32 v116, -v127, v123, v116
	v_div_fmas_f32 v116, v116, v151, v123
	v_and_b32_e32 v129, 0xffff0000, v129
	v_div_fixup_f32 v116, v116, v125, v117
	v_mul_f32_e32 v123, v116, v129
	v_cvt_pk_bf16_f32 v116, v118, v119
	v_cvt_pk_bf16_f32 v117, v120, v121
	v_cvt_pk_bf16_f32 v118, v114, v115
	v_or_b32_e32 v114, 16, v150
	v_ashrrev_i32_e32 v115, 31, v114
	v_lshlrev_b64 v[114:115], 13, v[114:115]
	v_lshl_add_u64 v[114:115], s[10:11], 0, v[114:115]
	v_lshl_add_u64 v[114:115], v[114:115], 0, v[152:153]
	v_cvt_pk_bf16_f32 v119, v122, v123
	v_mul_f32_e32 v129, 0xbfb8aa3b, v106
	global_store_dwordx4 v[148:149], v[116:119], off offset:256
	v_exp_f32_e32 v129, v129
	s_waitcnt vmcnt(14)
	v_mov_b32_e32 v120, v194
	v_mov_b32_e32 v121, v195
	v_mov_b32_e32 v122, v196
	v_mov_b32_e32 v123, v197
	v_lshlrev_b32_e32 v126, 16, v123
	v_mul_f32_e32 v118, 0xbfb8aa3b, v110
	v_exp_f32_e32 v118, v118
	v_lshlrev_b32_e32 v116, 16, v120
	v_and_b32_e32 v117, 0xffff0000, v120
	v_lshlrev_b32_e32 v119, 16, v121
	v_add_f32_e32 v118, 1.0, v118
	v_div_scale_f32 v124, s[2:3], v118, v118, v110
	v_rcp_f32_e32 v125, v124
	v_and_b32_e32 v120, 0xffff0000, v121
	v_lshlrev_b32_e32 v121, 16, v122
	v_and_b32_e32 v122, 0xffff0000, v122
	v_fma_f32 v127, -v124, v125, 1.0
	v_fmac_f32_e32 v125, v127, v125
	v_div_scale_f32 v127, vcc, v110, v118, v110
	v_mul_f32_e32 v128, v127, v125
	v_fma_f32 v151, -v124, v128, v127
	v_fmac_f32_e32 v128, v151, v125
	v_fma_f32 v124, -v124, v128, v127
	v_add_f32_e32 v127, 1.0, v129
	v_div_scale_f32 v129, s[2:3], v127, v127, v106
	v_rcp_f32_e32 v151, v129
	v_div_fmas_f32 v124, v124, v125, v128
	v_div_fixup_f32 v110, v124, v118, v110
	v_mul_f32_e32 v124, 0xbfb8aa3b, v111
	v_exp_f32_e32 v124, v124
	v_mul_f32_e32 v110, v110, v116
	v_fma_f32 v116, -v129, v151, 1.0
	v_fmac_f32_e32 v151, v116, v151
	v_div_scale_f32 v116, vcc, v106, v127, v106
	v_mul_f32_e32 v118, v116, v151
	v_fma_f32 v125, -v129, v118, v116
	v_add_f32_e32 v124, 1.0, v124
	v_fmac_f32_e32 v118, v125, v151
	v_div_scale_f32 v125, s[2:3], v124, v124, v111
	v_fma_f32 v116, -v129, v118, v116
	v_rcp_f32_e32 v128, v125
	v_div_fmas_f32 v116, v116, v151, v118
	v_div_fixup_f32 v106, v116, v127, v106
	v_mul_f32_e32 v116, v106, v121
	v_mul_f32_e32 v121, 0xbfb8aa3b, v107
	v_fma_f32 v106, -v125, v128, 1.0
	v_exp_f32_e32 v121, v121
	v_fmac_f32_e32 v128, v106, v128
	v_div_scale_f32 v106, vcc, v111, v124, v111
	v_mul_f32_e32 v118, v106, v128
	v_fma_f32 v127, -v125, v118, v106
	v_fmac_f32_e32 v118, v127, v128
	v_add_f32_e32 v121, 1.0, v121
	v_fma_f32 v106, -v125, v118, v106
	v_div_scale_f32 v125, s[2:3], v121, v121, v107
	v_rcp_f32_e32 v127, v125
	v_div_fmas_f32 v106, v106, v128, v118
	v_mul_f32_e32 v118, 0xbfb8aa3b, v112
	v_exp_f32_e32 v118, v118
	v_div_fixup_f32 v106, v106, v124, v111
	v_fma_f32 v111, -v125, v127, 1.0
	v_fmac_f32_e32 v127, v111, v127
	v_div_scale_f32 v111, vcc, v107, v121, v107
	v_mul_f32_e32 v106, v106, v117
	v_mul_f32_e32 v117, v111, v127
	v_fma_f32 v124, -v125, v117, v111
	v_add_f32_e32 v118, 1.0, v118
	v_fmac_f32_e32 v117, v124, v127
	v_div_scale_f32 v124, s[2:3], v118, v118, v112
	v_fma_f32 v111, -v125, v117, v111
	v_rcp_f32_e32 v125, v124
	v_div_fmas_f32 v111, v111, v127, v117
	v_div_fixup_f32 v107, v111, v121, v107
	v_mul_f32_e32 v121, 0xbfb8aa3b, v108
	v_exp_f32_e32 v121, v121
	v_mul_f32_e32 v111, v107, v122
	v_fma_f32 v107, -v124, v125, 1.0
	v_fmac_f32_e32 v125, v107, v125
	v_div_scale_f32 v107, vcc, v112, v118, v112
	v_mul_f32_e32 v117, v107, v125
	v_fma_f32 v122, -v124, v117, v107
	v_add_f32_e32 v121, 1.0, v121
	v_fmac_f32_e32 v117, v122, v125
	v_div_scale_f32 v122, s[2:3], v121, v121, v108
	v_fma_f32 v107, -v124, v117, v107
	v_rcp_f32_e32 v124, v122
	v_div_fmas_f32 v107, v107, v125, v117
	v_div_fixup_f32 v107, v107, v118, v112
	v_mul_f32_e32 v118, 0xbfb8aa3b, v113
	v_exp_f32_e32 v118, v118
	v_fma_f32 v112, -v122, v124, 1.0
	v_fmac_f32_e32 v124, v112, v124
	v_div_scale_f32 v112, vcc, v108, v121, v108
	v_mul_f32_e32 v117, v112, v124
	v_mul_f32_e32 v107, v107, v119
	v_fma_f32 v119, -v122, v117, v112
	v_add_f32_e32 v118, 1.0, v118
	v_fmac_f32_e32 v117, v119, v124
	v_div_scale_f32 v119, s[2:3], v118, v118, v113
	v_fma_f32 v112, -v122, v117, v112
	v_rcp_f32_e32 v122, v119
	v_div_fmas_f32 v112, v112, v124, v117
	v_div_fixup_f32 v108, v112, v121, v108
	v_mul_f32_e32 v112, v108, v126
	v_fma_f32 v108, -v119, v122, 1.0
	v_mul_f32_e32 v121, 0xbfb8aa3b, v109
	v_fmac_f32_e32 v122, v108, v122
	v_div_scale_f32 v108, vcc, v113, v118, v113
	v_exp_f32_e32 v121, v121
	v_mul_f32_e32 v117, v108, v122
	v_fma_f32 v124, -v119, v117, v108
	v_fmac_f32_e32 v117, v124, v122
	v_fma_f32 v108, -v119, v117, v108
	v_add_f32_e32 v119, 1.0, v121
	v_div_scale_f32 v121, s[2:3], v119, v119, v109
	v_rcp_f32_e32 v124, v121
	v_div_fmas_f32 v108, v108, v122, v117
	v_div_fixup_f32 v108, v108, v118, v113
	v_and_b32_e32 v123, 0xffff0000, v123
	v_fma_f32 v113, -v121, v124, 1.0
	v_fmac_f32_e32 v124, v113, v124
	v_div_scale_f32 v113, vcc, v109, v119, v109
	v_mul_f32_e32 v117, v113, v124
	v_fma_f32 v118, -v121, v117, v113
	v_fmac_f32_e32 v117, v118, v124
	v_fma_f32 v113, -v121, v117, v113
	v_div_fmas_f32 v113, v113, v124, v117
	v_div_fixup_f32 v109, v113, v119, v109
	v_mul_f32_e32 v108, v108, v120
	v_mul_f32_e32 v109, v109, v123
	v_cvt_pk_bf16_f32 v106, v110, v106
	v_cvt_pk_bf16_f32 v107, v107, v108
	v_cvt_pk_bf16_f32 v108, v116, v111
	v_cvt_pk_bf16_f32 v109, v112, v109
	v_mul_f32_e32 v121, 0xbfb8aa3b, v98
	global_store_dwordx4 v[114:115], v[106:109], off
	v_exp_f32_e32 v121, v121
	s_waitcnt vmcnt(14)
	v_mov_b32_e32 v110, v198
	v_mov_b32_e32 v111, v199
	v_mov_b32_e32 v112, v200
	v_mov_b32_e32 v113, v201
	v_lshlrev_b32_e32 v118, 16, v113
	v_mul_f32_e32 v108, 0xbfb8aa3b, v102
	v_exp_f32_e32 v108, v108
	v_lshlrev_b32_e32 v106, 16, v110
	v_and_b32_e32 v107, 0xffff0000, v110
	v_lshlrev_b32_e32 v109, 16, v111
	v_add_f32_e32 v108, 1.0, v108
	v_div_scale_f32 v116, s[2:3], v108, v108, v102
	v_rcp_f32_e32 v117, v116
	v_and_b32_e32 v110, 0xffff0000, v111
	v_lshlrev_b32_e32 v111, 16, v112
	v_and_b32_e32 v112, 0xffff0000, v112
	v_fma_f32 v119, -v116, v117, 1.0
	v_fmac_f32_e32 v117, v119, v117
	v_div_scale_f32 v119, vcc, v102, v108, v102
	v_mul_f32_e32 v120, v119, v117
	v_fma_f32 v122, -v116, v120, v119
	v_fmac_f32_e32 v120, v122, v117
	v_fma_f32 v116, -v116, v120, v119
	v_add_f32_e32 v119, 1.0, v121
	v_div_scale_f32 v121, s[2:3], v119, v119, v98
	v_rcp_f32_e32 v122, v121
	v_div_fmas_f32 v116, v116, v117, v120
	v_div_fixup_f32 v102, v116, v108, v102
	v_mul_f32_e32 v116, 0xbfb8aa3b, v103
	v_exp_f32_e32 v116, v116
	v_mul_f32_e32 v102, v102, v106
	v_fma_f32 v106, -v121, v122, 1.0
	v_fmac_f32_e32 v122, v106, v122
	v_div_scale_f32 v106, vcc, v98, v119, v98
	v_mul_f32_e32 v108, v106, v122
	v_fma_f32 v117, -v121, v108, v106
	v_add_f32_e32 v116, 1.0, v116
	v_fmac_f32_e32 v108, v117, v122
	v_div_scale_f32 v117, s[2:3], v116, v116, v103
	v_fma_f32 v106, -v121, v108, v106
	v_rcp_f32_e32 v120, v117
	v_div_fmas_f32 v106, v106, v122, v108
	v_div_fixup_f32 v98, v106, v119, v98
	v_mul_f32_e32 v98, v98, v111
	v_mul_f32_e32 v111, 0xbfb8aa3b, v99
	v_fma_f32 v106, -v117, v120, 1.0
	v_exp_f32_e32 v111, v111
	v_fmac_f32_e32 v120, v106, v120
	v_div_scale_f32 v106, vcc, v103, v116, v103
	v_mul_f32_e32 v108, v106, v120
	v_fma_f32 v119, -v117, v108, v106
	v_fmac_f32_e32 v108, v119, v120
	v_add_f32_e32 v111, 1.0, v111
	v_fma_f32 v106, -v117, v108, v106
	v_div_scale_f32 v117, s[2:3], v111, v111, v99
	v_rcp_f32_e32 v119, v117
	v_div_fmas_f32 v106, v106, v120, v108
	v_mul_f32_e32 v108, 0xbfb8aa3b, v104
	v_exp_f32_e32 v108, v108
	v_div_fixup_f32 v103, v106, v116, v103
	v_fma_f32 v106, -v117, v119, 1.0
	v_fmac_f32_e32 v119, v106, v119
	v_div_scale_f32 v106, vcc, v99, v111, v99
	v_mul_f32_e32 v103, v103, v107
	v_mul_f32_e32 v107, v106, v119
	v_fma_f32 v116, -v117, v107, v106
	v_add_f32_e32 v108, 1.0, v108
	v_fmac_f32_e32 v107, v116, v119
	v_div_scale_f32 v116, s[2:3], v108, v108, v104
	v_fma_f32 v106, -v117, v107, v106
	v_rcp_f32_e32 v117, v116
	v_div_fmas_f32 v106, v106, v119, v107
	v_div_fixup_f32 v99, v106, v111, v99
	v_mul_f32_e32 v111, 0xbfb8aa3b, v100
	v_exp_f32_e32 v111, v111
	v_fma_f32 v106, -v116, v117, 1.0
	v_fmac_f32_e32 v117, v106, v117
	v_div_scale_f32 v106, vcc, v104, v108, v104
	v_mul_f32_e32 v107, v106, v117
	v_mul_f32_e32 v99, v99, v112
	v_fma_f32 v112, -v116, v107, v106
	v_add_f32_e32 v111, 1.0, v111
	v_fmac_f32_e32 v107, v112, v117
	v_div_scale_f32 v112, s[2:3], v111, v111, v100
	v_fma_f32 v106, -v116, v107, v106
	v_rcp_f32_e32 v116, v112
	v_div_fmas_f32 v106, v106, v117, v107
	v_div_fixup_f32 v104, v106, v108, v104
	v_mul_f32_e32 v108, 0xbfb8aa3b, v105
	v_exp_f32_e32 v108, v108
	v_fma_f32 v106, -v112, v116, 1.0
	v_fmac_f32_e32 v116, v106, v116
	v_div_scale_f32 v106, vcc, v100, v111, v100
	v_mul_f32_e32 v107, v106, v116
	v_mul_f32_e32 v104, v104, v109
	v_fma_f32 v109, -v112, v107, v106
	v_add_f32_e32 v108, 1.0, v108
	v_fmac_f32_e32 v107, v109, v116
	v_div_scale_f32 v109, s[2:3], v108, v108, v105
	v_fma_f32 v106, -v112, v107, v106
	v_rcp_f32_e32 v112, v109
	v_div_fmas_f32 v106, v106, v116, v107
	v_div_fixup_f32 v100, v106, v111, v100
	v_mul_f32_e32 v106, v100, v118
	v_fma_f32 v100, -v109, v112, 1.0
	v_mul_f32_e32 v111, 0xbfb8aa3b, v101
	v_fmac_f32_e32 v112, v100, v112
	v_div_scale_f32 v100, vcc, v105, v108, v105
	v_exp_f32_e32 v111, v111
	v_mul_f32_e32 v107, v100, v112
	v_fma_f32 v116, -v109, v107, v100
	v_fmac_f32_e32 v107, v116, v112
	v_fma_f32 v100, -v109, v107, v100
	v_add_f32_e32 v109, 1.0, v111
	v_div_scale_f32 v111, s[2:3], v109, v109, v101
	v_rcp_f32_e32 v116, v111
	v_div_fmas_f32 v100, v100, v112, v107
	v_div_fixup_f32 v100, v100, v108, v105
	v_mul_f32_e32 v105, v100, v110
	v_fma_f32 v100, -v111, v116, 1.0
	v_fmac_f32_e32 v116, v100, v116
	v_div_scale_f32 v100, vcc, v101, v109, v101
	v_mul_f32_e32 v107, v100, v116
	v_fma_f32 v108, -v111, v107, v100
	v_fmac_f32_e32 v107, v108, v116
	v_fma_f32 v100, -v111, v107, v100
	v_div_fmas_f32 v100, v100, v116, v107
	v_and_b32_e32 v113, 0xffff0000, v113
	v_div_fixup_f32 v100, v100, v109, v101
	v_mul_f32_e32 v107, v100, v113
	v_cvt_pk_bf16_f32 v100, v102, v103
	v_cvt_pk_bf16_f32 v101, v104, v105
	v_cvt_pk_bf16_f32 v102, v98, v99
	v_or_b32_e32 v98, 32, v150
	v_ashrrev_i32_e32 v99, 31, v98
	v_lshlrev_b64 v[98:99], 13, v[98:99]
	v_lshl_add_u64 v[98:99], s[10:11], 0, v[98:99]
	v_lshl_add_u64 v[98:99], v[98:99], 0, v[152:153]
	v_cvt_pk_bf16_f32 v103, v106, v107
	v_mul_f32_e32 v113, 0xbfb8aa3b, v90
	global_store_dwordx4 v[114:115], v[100:103], off offset:256
	v_exp_f32_e32 v113, v113
	s_waitcnt vmcnt(14)
	v_mov_b32_e32 v104, v202
	v_mov_b32_e32 v105, v203
	v_mov_b32_e32 v106, v204
	v_mov_b32_e32 v107, v205
	v_lshlrev_b32_e32 v110, 16, v107
	v_mul_f32_e32 v102, 0xbfb8aa3b, v94
	v_exp_f32_e32 v102, v102
	v_lshlrev_b32_e32 v100, 16, v104
	v_and_b32_e32 v101, 0xffff0000, v104
	v_lshlrev_b32_e32 v103, 16, v105
	v_add_f32_e32 v102, 1.0, v102
	v_div_scale_f32 v108, s[2:3], v102, v102, v94
	v_rcp_f32_e32 v109, v108
	v_and_b32_e32 v104, 0xffff0000, v105
	v_lshlrev_b32_e32 v105, 16, v106
	v_and_b32_e32 v106, 0xffff0000, v106
	v_fma_f32 v111, -v108, v109, 1.0
	v_fmac_f32_e32 v109, v111, v109
	v_div_scale_f32 v111, vcc, v94, v102, v94
	v_mul_f32_e32 v112, v111, v109
	v_fma_f32 v114, -v108, v112, v111
	v_fmac_f32_e32 v112, v114, v109
	v_fma_f32 v108, -v108, v112, v111
	v_add_f32_e32 v111, 1.0, v113
	v_div_scale_f32 v113, s[2:3], v111, v111, v90
	v_rcp_f32_e32 v114, v113
	v_div_fmas_f32 v108, v108, v109, v112
	v_div_fixup_f32 v94, v108, v102, v94
	v_mul_f32_e32 v108, 0xbfb8aa3b, v95
	v_exp_f32_e32 v108, v108
	v_mul_f32_e32 v94, v94, v100
	v_fma_f32 v100, -v113, v114, 1.0
	v_fmac_f32_e32 v114, v100, v114
	v_div_scale_f32 v100, vcc, v90, v111, v90
	v_mul_f32_e32 v102, v100, v114
	v_fma_f32 v109, -v113, v102, v100
	v_add_f32_e32 v108, 1.0, v108
	v_fmac_f32_e32 v102, v109, v114
	v_div_scale_f32 v109, s[2:3], v108, v108, v95
	v_fma_f32 v100, -v113, v102, v100
	v_rcp_f32_e32 v112, v109
	v_div_fmas_f32 v100, v100, v114, v102
	v_div_fixup_f32 v90, v100, v111, v90
	v_mul_f32_e32 v100, v90, v105
	v_mul_f32_e32 v105, 0xbfb8aa3b, v91
	v_fma_f32 v90, -v109, v112, 1.0
	v_exp_f32_e32 v105, v105
	v_fmac_f32_e32 v112, v90, v112
	v_div_scale_f32 v90, vcc, v95, v108, v95
	v_mul_f32_e32 v102, v90, v112
	v_fma_f32 v111, -v109, v102, v90
	v_fmac_f32_e32 v102, v111, v112
	v_add_f32_e32 v105, 1.0, v105
	v_fma_f32 v90, -v109, v102, v90
	v_div_scale_f32 v109, s[2:3], v105, v105, v91
	v_rcp_f32_e32 v111, v109
	v_div_fmas_f32 v90, v90, v112, v102
	v_mul_f32_e32 v102, 0xbfb8aa3b, v96
	v_exp_f32_e32 v102, v102
	v_div_fixup_f32 v90, v90, v108, v95
	v_fma_f32 v95, -v109, v111, 1.0
	v_fmac_f32_e32 v111, v95, v111
	v_div_scale_f32 v95, vcc, v91, v105, v91
	v_mul_f32_e32 v90, v90, v101
	v_mul_f32_e32 v101, v95, v111
	v_fma_f32 v108, -v109, v101, v95
	v_add_f32_e32 v102, 1.0, v102
	v_fmac_f32_e32 v101, v108, v111
	v_div_scale_f32 v108, s[2:3], v102, v102, v96
	v_fma_f32 v95, -v109, v101, v95
	v_rcp_f32_e32 v109, v108
	v_div_fmas_f32 v95, v95, v111, v101
	v_div_fixup_f32 v91, v95, v105, v91
	v_mul_f32_e32 v105, 0xbfb8aa3b, v92
	v_exp_f32_e32 v105, v105
	v_mul_f32_e32 v95, v91, v106
	v_fma_f32 v91, -v108, v109, 1.0
	v_fmac_f32_e32 v109, v91, v109
	v_div_scale_f32 v91, vcc, v96, v102, v96
	v_mul_f32_e32 v101, v91, v109
	v_fma_f32 v106, -v108, v101, v91
	v_add_f32_e32 v105, 1.0, v105
	v_fmac_f32_e32 v101, v106, v109
	v_div_scale_f32 v106, s[2:3], v105, v105, v92
	v_fma_f32 v91, -v108, v101, v91
	v_rcp_f32_e32 v108, v106
	v_div_fmas_f32 v91, v91, v109, v101
	v_div_fixup_f32 v91, v91, v102, v96
	v_mul_f32_e32 v102, 0xbfb8aa3b, v97
	v_exp_f32_e32 v102, v102
	v_fma_f32 v96, -v106, v108, 1.0
	v_fmac_f32_e32 v108, v96, v108
	v_div_scale_f32 v96, vcc, v92, v105, v92
	v_mul_f32_e32 v101, v96, v108
	v_mul_f32_e32 v91, v91, v103
	v_fma_f32 v103, -v106, v101, v96
	v_add_f32_e32 v102, 1.0, v102
	v_fmac_f32_e32 v101, v103, v108
	v_div_scale_f32 v103, s[2:3], v102, v102, v97
	v_fma_f32 v96, -v106, v101, v96
	v_rcp_f32_e32 v106, v103
	v_div_fmas_f32 v96, v96, v108, v101
	v_div_fixup_f32 v92, v96, v105, v92
	v_mul_f32_e32 v96, v92, v110
	v_fma_f32 v92, -v103, v106, 1.0
	v_mul_f32_e32 v105, 0xbfb8aa3b, v93
	v_fmac_f32_e32 v106, v92, v106
	v_div_scale_f32 v92, vcc, v97, v102, v97
	v_exp_f32_e32 v105, v105
	v_mul_f32_e32 v101, v92, v106
	v_fma_f32 v108, -v103, v101, v92
	v_fmac_f32_e32 v101, v108, v106
	v_fma_f32 v92, -v103, v101, v92
	v_add_f32_e32 v103, 1.0, v105
	v_div_scale_f32 v105, s[2:3], v103, v103, v93
	v_rcp_f32_e32 v108, v105
	v_div_fmas_f32 v92, v92, v106, v101
	v_div_fixup_f32 v92, v92, v102, v97
	v_and_b32_e32 v107, 0xffff0000, v107
	v_fma_f32 v97, -v105, v108, 1.0
	v_fmac_f32_e32 v108, v97, v108
	v_div_scale_f32 v97, vcc, v93, v103, v93
	v_mul_f32_e32 v101, v97, v108
	v_fma_f32 v102, -v105, v101, v97
	v_fmac_f32_e32 v101, v102, v108
	v_fma_f32 v97, -v105, v101, v97
	v_div_fmas_f32 v97, v97, v108, v101
	v_div_fixup_f32 v93, v97, v103, v93
	v_mul_f32_e32 v92, v92, v104
	v_mul_f32_e32 v93, v93, v107
	v_cvt_pk_bf16_f32 v90, v94, v90
	v_cvt_pk_bf16_f32 v91, v91, v92
	v_cvt_pk_bf16_f32 v92, v100, v95
	v_cvt_pk_bf16_f32 v93, v96, v93
	v_mul_f32_e32 v105, 0xbfb8aa3b, v82
	global_store_dwordx4 v[98:99], v[90:93], off
	v_exp_f32_e32 v105, v105
	s_waitcnt vmcnt(14)
;     __device__ __forceinline__ void operator()(const f32x4 (&acc)[2][2][4][2], const Unit& u, int wr, int wc, int fr, int fq) const {
;     ...
;         for (int ai = 0; ai < 2; ++ai)
; #pragma unroll
;             for (int m = 0; m < 4; ++m)
; #pragma unroll
;                 for (int bj = 0; bj < 2; ++bj) f(row0 + ai * HALF + m * 16, col0 + bj * HALF, acc[ai][bj][m][0], acc[ai][bj][m][1]);
	v_mov_b32_e32 v94, v206
	v_mov_b32_e32 v95, v207
	v_mov_b32_e32 v96, v208
	v_mov_b32_e32 v97, v209
	v_lshlrev_b32_e32 v102, 16, v97
	v_mul_f32_e32 v92, 0xbfb8aa3b, v86
	v_exp_f32_e32 v92, v92
	v_lshlrev_b32_e32 v90, 16, v94
	v_and_b32_e32 v91, 0xffff0000, v94
	v_lshlrev_b32_e32 v93, 16, v95
	v_add_f32_e32 v92, 1.0, v92
	v_div_scale_f32 v100, s[2:3], v92, v92, v86
	v_rcp_f32_e32 v101, v100
	v_and_b32_e32 v94, 0xffff0000, v95
	v_lshlrev_b32_e32 v95, 16, v96
	v_and_b32_e32 v96, 0xffff0000, v96
	v_fma_f32 v103, -v100, v101, 1.0
	v_fmac_f32_e32 v101, v103, v101
	v_div_scale_f32 v103, vcc, v86, v92, v86
	v_mul_f32_e32 v104, v103, v101
	v_fma_f32 v106, -v100, v104, v103
	v_fmac_f32_e32 v104, v106, v101
	v_fma_f32 v100, -v100, v104, v103
	v_add_f32_e32 v103, 1.0, v105
	v_div_scale_f32 v105, s[2:3], v103, v103, v82
	v_rcp_f32_e32 v106, v105
	v_div_fmas_f32 v100, v100, v101, v104
	v_div_fixup_f32 v86, v100, v92, v86
	v_mul_f32_e32 v100, 0xbfb8aa3b, v87
	v_exp_f32_e32 v100, v100
	v_mul_f32_e32 v86, v86, v90
	v_fma_f32 v90, -v105, v106, 1.0
	v_fmac_f32_e32 v106, v90, v106
	v_div_scale_f32 v90, vcc, v82, v103, v82
	v_mul_f32_e32 v92, v90, v106
	v_fma_f32 v101, -v105, v92, v90
	v_add_f32_e32 v100, 1.0, v100
	v_fmac_f32_e32 v92, v101, v106
	v_div_scale_f32 v101, s[2:3], v100, v100, v87
	v_fma_f32 v90, -v105, v92, v90
	v_rcp_f32_e32 v104, v101
	v_div_fmas_f32 v90, v90, v106, v92
	v_div_fixup_f32 v82, v90, v103, v82
	v_mul_f32_e32 v82, v82, v95
	v_mul_f32_e32 v95, 0xbfb8aa3b, v83
	v_fma_f32 v90, -v101, v104, 1.0
	v_exp_f32_e32 v95, v95
	v_fmac_f32_e32 v104, v90, v104
	v_div_scale_f32 v90, vcc, v87, v100, v87
	v_mul_f32_e32 v92, v90, v104
	v_fma_f32 v103, -v101, v92, v90
	v_fmac_f32_e32 v92, v103, v104
	v_add_f32_e32 v95, 1.0, v95
	v_fma_f32 v90, -v101, v92, v90
	v_div_scale_f32 v101, s[2:3], v95, v95, v83
	v_rcp_f32_e32 v103, v101
	v_div_fmas_f32 v90, v90, v104, v92
	v_mul_f32_e32 v92, 0xbfb8aa3b, v88
	v_exp_f32_e32 v92, v92
	v_div_fixup_f32 v87, v90, v100, v87
	v_fma_f32 v90, -v101, v103, 1.0
	v_fmac_f32_e32 v103, v90, v103
	v_div_scale_f32 v90, vcc, v83, v95, v83
	v_mul_f32_e32 v87, v87, v91
	v_mul_f32_e32 v91, v90, v103
	v_fma_f32 v100, -v101, v91, v90
	v_add_f32_e32 v92, 1.0, v92
	v_fmac_f32_e32 v91, v100, v103
	v_div_scale_f32 v100, s[2:3], v92, v92, v88
	v_fma_f32 v90, -v101, v91, v90
	v_rcp_f32_e32 v101, v100
	v_div_fmas_f32 v90, v90, v103, v91
	v_div_fixup_f32 v83, v90, v95, v83
	v_mul_f32_e32 v95, 0xbfb8aa3b, v84
	v_exp_f32_e32 v95, v95
	v_fma_f32 v90, -v100, v101, 1.0
	v_fmac_f32_e32 v101, v90, v101
	v_div_scale_f32 v90, vcc, v88, v92, v88
	v_mul_f32_e32 v91, v90, v101
	v_mul_f32_e32 v83, v83, v96
	v_fma_f32 v96, -v100, v91, v90
	v_add_f32_e32 v95, 1.0, v95
	v_fmac_f32_e32 v91, v96, v101
	v_div_scale_f32 v96, s[2:3], v95, v95, v84
	v_fma_f32 v90, -v100, v91, v90
	v_rcp_f32_e32 v100, v96
	v_div_fmas_f32 v90, v90, v101, v91
	v_div_fixup_f32 v88, v90, v92, v88
	v_mul_f32_e32 v92, 0xbfb8aa3b, v89
	v_exp_f32_e32 v92, v92
	v_fma_f32 v90, -v96, v100, 1.0
	v_fmac_f32_e32 v100, v90, v100
	v_div_scale_f32 v90, vcc, v84, v95, v84
	v_mul_f32_e32 v91, v90, v100
	v_mul_f32_e32 v88, v88, v93
	v_fma_f32 v93, -v96, v91, v90
	v_add_f32_e32 v92, 1.0, v92
	v_fmac_f32_e32 v91, v93, v100
	v_div_scale_f32 v93, s[2:3], v92, v92, v89
	v_fma_f32 v90, -v96, v91, v90
	v_rcp_f32_e32 v96, v93
	v_div_fmas_f32 v90, v90, v100, v91
	v_div_fixup_f32 v84, v90, v95, v84
	v_mul_f32_e32 v90, v84, v102
	v_fma_f32 v84, -v93, v96, 1.0
	v_mul_f32_e32 v95, 0xbfb8aa3b, v85
	v_fmac_f32_e32 v96, v84, v96
	v_div_scale_f32 v84, vcc, v89, v92, v89
	v_exp_f32_e32 v95, v95
	v_mul_f32_e32 v91, v84, v96
	v_fma_f32 v100, -v93, v91, v84
	v_fmac_f32_e32 v91, v100, v96
	v_fma_f32 v84, -v93, v91, v84
	v_add_f32_e32 v93, 1.0, v95
	v_div_scale_f32 v95, s[2:3], v93, v93, v85
	v_rcp_f32_e32 v100, v95
	v_div_fmas_f32 v84, v84, v96, v91
	v_div_fixup_f32 v84, v84, v92, v89
	v_mul_f32_e32 v89, v84, v94
	v_fma_f32 v84, -v95, v100, 1.0
	v_fmac_f32_e32 v100, v84, v100
	v_div_scale_f32 v84, vcc, v85, v93, v85
	v_mul_f32_e32 v91, v84, v100
	v_fma_f32 v92, -v95, v91, v84
	v_fmac_f32_e32 v91, v92, v100
	v_fma_f32 v84, -v95, v91, v84
	v_div_fmas_f32 v84, v84, v100, v91
	v_and_b32_e32 v97, 0xffff0000, v97
	v_div_fixup_f32 v84, v84, v93, v85
	v_mul_f32_e32 v91, v84, v97
	v_cvt_pk_bf16_f32 v84, v86, v87
	v_cvt_pk_bf16_f32 v85, v88, v89
	v_cvt_pk_bf16_f32 v86, v82, v83
	v_or_b32_e32 v82, 48, v150
	v_ashrrev_i32_e32 v83, 31, v82
	v_lshlrev_b64 v[82:83], 13, v[82:83]
	v_lshl_add_u64 v[82:83], s[10:11], 0, v[82:83]
	v_lshl_add_u64 v[82:83], v[82:83], 0, v[152:153]
	v_cvt_pk_bf16_f32 v87, v90, v91
	v_mul_f32_e32 v97, 0xbfb8aa3b, v74
	global_store_dwordx4 v[98:99], v[84:87], off offset:256
	v_exp_f32_e32 v97, v97
	s_waitcnt vmcnt(14)
;     __device__ __forceinline__ void operator()(const f32x4 (&acc)[2][2][4][2], const Unit& u, int wr, int wc, int fr, int fq) const {
;     ...
;         for (int ai = 0; ai < 2; ++ai)
; #pragma unroll
;             for (int m = 0; m < 4; ++m)
; #pragma unroll
;                 for (int bj = 0; bj < 2; ++bj) f(row0 + ai * HALF + m * 16, col0 + bj * HALF, acc[ai][bj][m][0], acc[ai][bj][m][1]);
	v_mov_b32_e32 v88, v210
	v_mov_b32_e32 v89, v211
	v_mov_b32_e32 v90, v212
	v_mov_b32_e32 v91, v213
	v_lshlrev_b32_e32 v94, 16, v91
	v_mul_f32_e32 v86, 0xbfb8aa3b, v78
	v_exp_f32_e32 v86, v86
	v_lshlrev_b32_e32 v84, 16, v88
	v_and_b32_e32 v85, 0xffff0000, v88
	v_lshlrev_b32_e32 v87, 16, v89
	v_add_f32_e32 v86, 1.0, v86
	v_div_scale_f32 v92, s[2:3], v86, v86, v78
	v_rcp_f32_e32 v93, v92
	v_and_b32_e32 v88, 0xffff0000, v89
	v_lshlrev_b32_e32 v89, 16, v90
	v_and_b32_e32 v90, 0xffff0000, v90
	v_fma_f32 v95, -v92, v93, 1.0
	v_fmac_f32_e32 v93, v95, v93
	v_div_scale_f32 v95, vcc, v78, v86, v78
	v_mul_f32_e32 v96, v95, v93
	v_fma_f32 v98, -v92, v96, v95
	v_fmac_f32_e32 v96, v98, v93
	v_fma_f32 v92, -v92, v96, v95
	v_add_f32_e32 v95, 1.0, v97
	v_div_scale_f32 v97, s[2:3], v95, v95, v74
	v_rcp_f32_e32 v98, v97
	v_div_fmas_f32 v92, v92, v93, v96
	v_div_fixup_f32 v78, v92, v86, v78
	v_mul_f32_e32 v92, 0xbfb8aa3b, v79
	v_exp_f32_e32 v92, v92
	v_mul_f32_e32 v78, v78, v84
	v_fma_f32 v84, -v97, v98, 1.0
	v_fmac_f32_e32 v98, v84, v98
	v_div_scale_f32 v84, vcc, v74, v95, v74
	v_mul_f32_e32 v86, v84, v98
	v_fma_f32 v93, -v97, v86, v84
	v_add_f32_e32 v92, 1.0, v92
	v_fmac_f32_e32 v86, v93, v98
	v_div_scale_f32 v93, s[2:3], v92, v92, v79
	v_fma_f32 v84, -v97, v86, v84
	v_rcp_f32_e32 v96, v93
	v_div_fmas_f32 v84, v84, v98, v86
	v_div_fixup_f32 v74, v84, v95, v74
	v_mul_f32_e32 v84, v74, v89
	v_mul_f32_e32 v89, 0xbfb8aa3b, v75
	v_fma_f32 v74, -v93, v96, 1.0
	v_exp_f32_e32 v89, v89
	v_fmac_f32_e32 v96, v74, v96
	v_div_scale_f32 v74, vcc, v79, v92, v79
	v_mul_f32_e32 v86, v74, v96
	v_fma_f32 v95, -v93, v86, v74
	v_fmac_f32_e32 v86, v95, v96
	v_add_f32_e32 v89, 1.0, v89
	v_fma_f32 v74, -v93, v86, v74
	v_div_scale_f32 v93, s[2:3], v89, v89, v75
	v_rcp_f32_e32 v95, v93
	v_div_fmas_f32 v74, v74, v96, v86
	v_mul_f32_e32 v86, 0xbfb8aa3b, v80
	v_exp_f32_e32 v86, v86
	v_div_fixup_f32 v74, v74, v92, v79
	v_fma_f32 v79, -v93, v95, 1.0
	v_fmac_f32_e32 v95, v79, v95
	v_div_scale_f32 v79, vcc, v75, v89, v75
	v_mul_f32_e32 v74, v74, v85
	v_mul_f32_e32 v85, v79, v95
	v_fma_f32 v92, -v93, v85, v79
	v_add_f32_e32 v86, 1.0, v86
	v_fmac_f32_e32 v85, v92, v95
	v_div_scale_f32 v92, s[2:3], v86, v86, v80
	v_fma_f32 v79, -v93, v85, v79
	v_rcp_f32_e32 v93, v92
	v_div_fmas_f32 v79, v79, v95, v85
	v_div_fixup_f32 v75, v79, v89, v75
	v_mul_f32_e32 v89, 0xbfb8aa3b, v76
	v_exp_f32_e32 v89, v89
	v_mul_f32_e32 v79, v75, v90
	v_fma_f32 v75, -v92, v93, 1.0
	v_fmac_f32_e32 v93, v75, v93
	v_div_scale_f32 v75, vcc, v80, v86, v80
	v_mul_f32_e32 v85, v75, v93
	v_fma_f32 v90, -v92, v85, v75
	v_add_f32_e32 v89, 1.0, v89
	v_fmac_f32_e32 v85, v90, v93
	v_div_scale_f32 v90, s[2:3], v89, v89, v76
	v_fma_f32 v75, -v92, v85, v75
	v_rcp_f32_e32 v92, v90
	v_div_fmas_f32 v75, v75, v93, v85
	v_div_fixup_f32 v75, v75, v86, v80
	v_mul_f32_e32 v86, 0xbfb8aa3b, v81
	v_exp_f32_e32 v86, v86
	v_fma_f32 v80, -v90, v92, 1.0
	v_fmac_f32_e32 v92, v80, v92
	v_div_scale_f32 v80, vcc, v76, v89, v76
	v_mul_f32_e32 v85, v80, v92
	v_mul_f32_e32 v75, v75, v87
	v_fma_f32 v87, -v90, v85, v80
	v_add_f32_e32 v86, 1.0, v86
	v_fmac_f32_e32 v85, v87, v92
	v_div_scale_f32 v87, s[2:3], v86, v86, v81
	v_fma_f32 v80, -v90, v85, v80
	v_rcp_f32_e32 v90, v87
	v_div_fmas_f32 v80, v80, v92, v85
	v_div_fixup_f32 v76, v80, v89, v76
	v_mul_f32_e32 v80, v76, v94
	v_fma_f32 v76, -v87, v90, 1.0
	v_mul_f32_e32 v89, 0xbfb8aa3b, v77
	v_fmac_f32_e32 v90, v76, v90
	v_div_scale_f32 v76, vcc, v81, v86, v81
	v_exp_f32_e32 v89, v89
	v_mul_f32_e32 v85, v76, v90
	v_fma_f32 v92, -v87, v85, v76
	v_fmac_f32_e32 v85, v92, v90
	v_fma_f32 v76, -v87, v85, v76
	v_add_f32_e32 v87, 1.0, v89
	v_div_scale_f32 v89, s[2:3], v87, v87, v77
	v_rcp_f32_e32 v92, v89
	v_div_fmas_f32 v76, v76, v90, v85
	v_div_fixup_f32 v76, v76, v86, v81
	v_and_b32_e32 v91, 0xffff0000, v91
	v_fma_f32 v81, -v89, v92, 1.0
	v_fmac_f32_e32 v92, v81, v92
	v_div_scale_f32 v81, vcc, v77, v87, v77
	v_mul_f32_e32 v85, v81, v92
	v_fma_f32 v86, -v89, v85, v81
	v_fmac_f32_e32 v85, v86, v92
	v_fma_f32 v81, -v89, v85, v81
	v_div_fmas_f32 v81, v81, v92, v85
	v_div_fixup_f32 v77, v81, v87, v77
	v_mul_f32_e32 v76, v76, v88
	v_mul_f32_e32 v77, v77, v91
	v_cvt_pk_bf16_f32 v74, v78, v74
	v_cvt_pk_bf16_f32 v75, v75, v76
	v_cvt_pk_bf16_f32 v76, v84, v79
	v_cvt_pk_bf16_f32 v77, v80, v77
	v_mul_f32_e32 v89, 0xbfb8aa3b, v66
	global_store_dwordx4 v[82:83], v[74:77], off
	v_exp_f32_e32 v89, v89
	s_waitcnt vmcnt(14)
;     __device__ __forceinline__ void operator()(const f32x4 (&acc)[2][2][4][2], const Unit& u, int wr, int wc, int fr, int fq) const {
;     ...
;         for (int ai = 0; ai < 2; ++ai)
; #pragma unroll
;             for (int m = 0; m < 4; ++m)
; #pragma unroll
;                 for (int bj = 0; bj < 2; ++bj) f(row0 + ai * HALF + m * 16, col0 + bj * HALF, acc[ai][bj][m][0], acc[ai][bj][m][1]);
	v_mov_b32_e32 v78, v214
	v_mov_b32_e32 v79, v215
	v_mov_b32_e32 v80, v216
	v_mov_b32_e32 v81, v217
	v_lshlrev_b32_e32 v86, 16, v81
	v_mul_f32_e32 v76, 0xbfb8aa3b, v70
	v_exp_f32_e32 v76, v76
	v_lshlrev_b32_e32 v74, 16, v78
	v_and_b32_e32 v75, 0xffff0000, v78
	v_lshlrev_b32_e32 v77, 16, v79
	v_add_f32_e32 v76, 1.0, v76
	v_div_scale_f32 v84, s[2:3], v76, v76, v70
	v_rcp_f32_e32 v85, v84
	v_and_b32_e32 v78, 0xffff0000, v79
	v_lshlrev_b32_e32 v79, 16, v80
	v_and_b32_e32 v80, 0xffff0000, v80
	v_fma_f32 v87, -v84, v85, 1.0
	v_fmac_f32_e32 v85, v87, v85
	v_div_scale_f32 v87, vcc, v70, v76, v70
	v_mul_f32_e32 v88, v87, v85
	v_fma_f32 v90, -v84, v88, v87
	v_fmac_f32_e32 v88, v90, v85
	v_fma_f32 v84, -v84, v88, v87
	v_add_f32_e32 v87, 1.0, v89
	v_div_scale_f32 v89, s[2:3], v87, v87, v66
	v_rcp_f32_e32 v90, v89
	v_div_fmas_f32 v84, v84, v85, v88
	v_div_fixup_f32 v70, v84, v76, v70
	v_mul_f32_e32 v84, 0xbfb8aa3b, v71
	v_exp_f32_e32 v84, v84
	v_mul_f32_e32 v70, v70, v74
	v_fma_f32 v74, -v89, v90, 1.0
	v_fmac_f32_e32 v90, v74, v90
	v_div_scale_f32 v74, vcc, v66, v87, v66
	v_mul_f32_e32 v76, v74, v90
	v_fma_f32 v85, -v89, v76, v74
	v_add_f32_e32 v84, 1.0, v84
	v_fmac_f32_e32 v76, v85, v90
	v_div_scale_f32 v85, s[2:3], v84, v84, v71
	v_fma_f32 v74, -v89, v76, v74
	v_rcp_f32_e32 v88, v85
	v_div_fmas_f32 v74, v74, v90, v76
	v_div_fixup_f32 v66, v74, v87, v66
	v_mul_f32_e32 v74, v66, v79
	v_mul_f32_e32 v79, 0xbfb8aa3b, v67
	v_fma_f32 v66, -v85, v88, 1.0
	v_exp_f32_e32 v79, v79
	v_fmac_f32_e32 v88, v66, v88
	v_div_scale_f32 v66, vcc, v71, v84, v71
	v_mul_f32_e32 v76, v66, v88
	v_fma_f32 v87, -v85, v76, v66
	v_fmac_f32_e32 v76, v87, v88
	v_add_f32_e32 v79, 1.0, v79
	v_fma_f32 v66, -v85, v76, v66
	v_div_scale_f32 v85, s[2:3], v79, v79, v67
	v_rcp_f32_e32 v87, v85
	v_div_fmas_f32 v66, v66, v88, v76
	v_mul_f32_e32 v76, 0xbfb8aa3b, v72
	v_exp_f32_e32 v76, v76
	v_div_fixup_f32 v66, v66, v84, v71
	v_fma_f32 v71, -v85, v87, 1.0
	v_fmac_f32_e32 v87, v71, v87
	v_div_scale_f32 v71, vcc, v67, v79, v67
	v_mul_f32_e32 v66, v66, v75
	v_mul_f32_e32 v75, v71, v87
	v_fma_f32 v84, -v85, v75, v71
	v_add_f32_e32 v76, 1.0, v76
	v_fmac_f32_e32 v75, v84, v87
	v_div_scale_f32 v84, s[2:3], v76, v76, v72
	v_fma_f32 v71, -v85, v75, v71
	v_rcp_f32_e32 v85, v84
	v_div_fmas_f32 v71, v71, v87, v75
	v_div_fixup_f32 v67, v71, v79, v67
	v_mul_f32_e32 v79, 0xbfb8aa3b, v68
	v_exp_f32_e32 v79, v79
	v_mul_f32_e32 v71, v67, v80
	v_fma_f32 v67, -v84, v85, 1.0
	v_fmac_f32_e32 v85, v67, v85
	v_div_scale_f32 v67, vcc, v72, v76, v72
	v_mul_f32_e32 v75, v67, v85
	v_fma_f32 v80, -v84, v75, v67
	v_add_f32_e32 v79, 1.0, v79
	v_fmac_f32_e32 v75, v80, v85
	v_div_scale_f32 v80, s[2:3], v79, v79, v68
	v_fma_f32 v67, -v84, v75, v67
	v_rcp_f32_e32 v84, v80
	v_div_fmas_f32 v67, v67, v85, v75
	v_div_fixup_f32 v67, v67, v76, v72
	v_mul_f32_e32 v76, 0xbfb8aa3b, v73
	v_exp_f32_e32 v76, v76
	v_fma_f32 v72, -v80, v84, 1.0
	v_fmac_f32_e32 v84, v72, v84
	v_div_scale_f32 v72, vcc, v68, v79, v68
	v_mul_f32_e32 v75, v72, v84
	v_mul_f32_e32 v67, v67, v77
	v_fma_f32 v77, -v80, v75, v72
	v_add_f32_e32 v76, 1.0, v76
	v_fmac_f32_e32 v75, v77, v84
	v_div_scale_f32 v77, s[2:3], v76, v76, v73
	v_fma_f32 v72, -v80, v75, v72
	v_rcp_f32_e32 v80, v77
	v_div_fmas_f32 v72, v72, v84, v75
	v_div_fixup_f32 v68, v72, v79, v68
	v_mul_f32_e32 v72, v68, v86
	v_fma_f32 v68, -v77, v80, 1.0
	v_mul_f32_e32 v79, 0xbfb8aa3b, v69
	v_fmac_f32_e32 v80, v68, v80
	v_div_scale_f32 v68, vcc, v73, v76, v73
	v_exp_f32_e32 v79, v79
	v_mul_f32_e32 v75, v68, v80
	v_fma_f32 v84, -v77, v75, v68
	v_fmac_f32_e32 v75, v84, v80
	v_fma_f32 v68, -v77, v75, v68
	v_add_f32_e32 v77, 1.0, v79
	v_div_scale_f32 v79, s[2:3], v77, v77, v69
	v_rcp_f32_e32 v84, v79
	v_div_fmas_f32 v68, v68, v80, v75
	v_div_fixup_f32 v68, v68, v76, v73
	v_mul_f32_e32 v68, v68, v78
	v_fma_f32 v73, -v79, v84, 1.0
	v_fmac_f32_e32 v84, v73, v84
	v_div_scale_f32 v73, vcc, v69, v77, v69
	v_mul_f32_e32 v75, v73, v84
	v_fma_f32 v76, -v79, v75, v73
	v_fmac_f32_e32 v75, v76, v84
	v_fma_f32 v73, -v79, v75, v73
	v_div_fmas_f32 v73, v73, v84, v75
	v_and_b32_e32 v81, 0xffff0000, v81
	v_div_fixup_f32 v69, v73, v77, v69
	v_cvt_pk_bf16_f32 v66, v70, v66
	v_cvt_pk_bf16_f32 v67, v67, v68
	v_cvt_pk_bf16_f32 v68, v74, v71
	v_add_co_u32_e32 v74, vcc, s48, v148
	v_mul_f32_e32 v69, v69, v81
	s_nop 0
	v_addc_co_u32_e32 v75, vcc, 0, v149, vcc
	v_cvt_pk_bf16_f32 v69, v72, v69
	s_waitcnt vmcnt(14)
;     __device__ __forceinline__ void operator()(const f32x4 (&acc)[2][2][4][2], const Unit& u, int wr, int wc, int fr, int fq) const {
;     ...
;         for (int ai = 0; ai < 2; ++ai)
; #pragma unroll
;             for (int m = 0; m < 4; ++m)
; #pragma unroll
;                 for (int bj = 0; bj < 2; ++bj) f(row0 + ai * HALF + m * 16, col0 + bj * HALF, acc[ai][bj][m][0], acc[ai][bj][m][1]);
	v_mov_b32_e32 v70, v218
	v_mov_b32_e32 v71, v219
	v_mov_b32_e32 v72, v220
	v_mov_b32_e32 v73, v221
	v_lshlrev_b32_e32 v77, 16, v72
	global_store_dwordx4 v[82:83], v[66:69], off offset:256
	v_mul_f32_e32 v83, 0xbfb8aa3b, v58
	v_exp_f32_e32 v83, v83
	v_lshlrev_b32_e32 v68, 16, v70
	v_and_b32_e32 v69, 0xffff0000, v70
	v_mul_f32_e32 v70, 0xbfb8aa3b, v62
	v_exp_f32_e32 v70, v70
	v_and_b32_e32 v72, 0xffff0000, v72
	v_lshlrev_b32_e32 v76, 16, v71
	v_lshlrev_b32_e32 v80, 16, v73
	v_add_f32_e32 v70, 1.0, v70
	v_div_scale_f32 v78, s[2:3], v70, v70, v62
	v_rcp_f32_e32 v79, v78
	v_and_b32_e32 v71, 0xffff0000, v71
	v_and_b32_e32 v73, 0xffff0000, v73
	v_lshl_add_u64 v[66:67], v[148:149], 0, s[14:15]
	v_fma_f32 v81, -v78, v79, 1.0
	v_fmac_f32_e32 v79, v81, v79
	v_div_scale_f32 v81, vcc, v62, v70, v62
	v_mul_f32_e32 v82, v81, v79
	v_fma_f32 v84, -v78, v82, v81
	v_fmac_f32_e32 v82, v84, v79
	v_fma_f32 v78, -v78, v82, v81
	v_add_f32_e32 v81, 1.0, v83
	v_div_scale_f32 v83, s[2:3], v81, v81, v58
	v_rcp_f32_e32 v84, v83
	v_div_fmas_f32 v78, v78, v79, v82
	v_div_fixup_f32 v62, v78, v70, v62
	v_mul_f32_e32 v78, 0xbfb8aa3b, v63
	v_exp_f32_e32 v78, v78
	v_mul_f32_e32 v62, v62, v68
	v_fma_f32 v68, -v83, v84, 1.0
	v_fmac_f32_e32 v84, v68, v84
	v_div_scale_f32 v68, vcc, v58, v81, v58
	v_mul_f32_e32 v70, v68, v84
	v_fma_f32 v79, -v83, v70, v68
	v_add_f32_e32 v78, 1.0, v78
	v_fmac_f32_e32 v70, v79, v84
	v_div_scale_f32 v79, s[2:3], v78, v78, v63
	v_fma_f32 v68, -v83, v70, v68
	v_rcp_f32_e32 v82, v79
	v_div_fmas_f32 v68, v68, v84, v70
	v_div_fixup_f32 v58, v68, v81, v58
	v_mul_f32_e32 v68, v58, v77
	v_mul_f32_e32 v77, 0xbfb8aa3b, v59
	v_fma_f32 v58, -v79, v82, 1.0
	v_exp_f32_e32 v77, v77
	v_fmac_f32_e32 v82, v58, v82
	v_div_scale_f32 v58, vcc, v63, v78, v63
	v_mul_f32_e32 v70, v58, v82
	v_fma_f32 v81, -v79, v70, v58
	v_fmac_f32_e32 v70, v81, v82
	v_add_f32_e32 v77, 1.0, v77
	v_fma_f32 v58, -v79, v70, v58
	v_div_scale_f32 v79, s[2:3], v77, v77, v59
	v_rcp_f32_e32 v81, v79
	v_div_fmas_f32 v58, v58, v82, v70
	v_mul_f32_e32 v70, 0xbfb8aa3b, v64
	v_div_fixup_f32 v58, v58, v78, v63
	v_fma_f32 v63, -v79, v81, 1.0
	v_exp_f32_e32 v70, v70
	v_fmac_f32_e32 v81, v63, v81
	v_div_scale_f32 v63, vcc, v59, v77, v59
	v_mul_f32_e32 v58, v58, v69
	v_mul_f32_e32 v69, v63, v81
	v_fma_f32 v78, -v79, v69, v63
	v_fmac_f32_e32 v69, v78, v81
	v_add_f32_e32 v70, 1.0, v70
	v_fma_f32 v63, -v79, v69, v63
	v_div_scale_f32 v78, s[2:3], v70, v70, v64
	v_rcp_f32_e32 v79, v78
	v_div_fmas_f32 v63, v63, v81, v69
	v_div_fixup_f32 v59, v63, v77, v59
	v_mul_f32_e32 v63, v59, v72
	v_mul_f32_e32 v72, 0xbfb8aa3b, v60
	v_exp_f32_e32 v72, v72
	v_fma_f32 v59, -v78, v79, 1.0
	v_fmac_f32_e32 v79, v59, v79
	v_div_scale_f32 v59, vcc, v64, v70, v64
	v_mul_f32_e32 v69, v59, v79
	v_fma_f32 v77, -v78, v69, v59
	v_add_f32_e32 v72, 1.0, v72
	v_fmac_f32_e32 v69, v77, v79
	v_div_scale_f32 v77, s[2:3], v72, v72, v60
	v_fma_f32 v59, -v78, v69, v59
	v_rcp_f32_e32 v78, v77
	v_div_fmas_f32 v59, v59, v79, v69
	v_div_fixup_f32 v59, v59, v70, v64
	v_mul_f32_e32 v70, 0xbfb8aa3b, v65
	v_exp_f32_e32 v70, v70
	v_fma_f32 v64, -v77, v78, 1.0
	v_fmac_f32_e32 v78, v64, v78
	v_div_scale_f32 v64, vcc, v60, v72, v60
	v_mul_f32_e32 v69, v64, v78
	v_mul_f32_e32 v59, v59, v76
	v_fma_f32 v76, -v77, v69, v64
	v_add_f32_e32 v70, 1.0, v70
	v_fmac_f32_e32 v69, v76, v78
	v_div_scale_f32 v76, s[2:3], v70, v70, v65
	v_fma_f32 v64, -v77, v69, v64
	v_rcp_f32_e32 v77, v76
	v_div_fmas_f32 v64, v64, v78, v69
	v_div_fixup_f32 v60, v64, v72, v60
	v_mul_f32_e32 v72, 0xbfb8aa3b, v61
	v_mul_f32_e32 v64, v60, v80
	v_fma_f32 v60, -v76, v77, 1.0
	v_exp_f32_e32 v72, v72
	v_fmac_f32_e32 v77, v60, v77
	v_div_scale_f32 v60, vcc, v65, v70, v65
	v_mul_f32_e32 v69, v60, v77
	v_fma_f32 v78, -v76, v69, v60
	v_fmac_f32_e32 v69, v78, v77
	v_add_f32_e32 v72, 1.0, v72
	v_fma_f32 v60, -v76, v69, v60
	v_div_scale_f32 v76, s[2:3], v72, v72, v61
	v_rcp_f32_e32 v78, v76
	v_div_fmas_f32 v60, v60, v77, v69
	v_div_fixup_f32 v60, v60, v70, v65
	v_mul_f32_e32 v60, v60, v71
	v_fma_f32 v65, -v76, v78, 1.0
	v_fmac_f32_e32 v78, v65, v78
	v_div_scale_f32 v65, vcc, v61, v72, v61
	v_mul_f32_e32 v69, v65, v78
	v_fma_f32 v70, -v76, v69, v65
	v_fmac_f32_e32 v69, v70, v78
	v_fma_f32 v65, -v76, v69, v65
	v_div_fmas_f32 v65, v65, v78, v69
	v_div_fixup_f32 v61, v65, v72, v61
	v_mul_f32_e32 v61, v61, v73
	v_cvt_pk_bf16_f32 v58, v62, v58
	v_cvt_pk_bf16_f32 v59, v59, v60
	v_cvt_pk_bf16_f32 v60, v68, v63
	v_cvt_pk_bf16_f32 v61, v64, v61
	v_mul_f32_e32 v73, 0xbfb8aa3b, v50
	global_store_dwordx4 v[74:75], v[58:61], off
	v_exp_f32_e32 v73, v73
	s_waitcnt vmcnt(14)
;     __device__ __forceinline__ void operator()(const f32x4 (&acc)[2][2][4][2], const Unit& u, int wr, int wc, int fr, int fq) const {
;     ...
;         for (int ai = 0; ai < 2; ++ai)
; #pragma unroll
;             for (int m = 0; m < 4; ++m)
; #pragma unroll
;                 for (int bj = 0; bj < 2; ++bj) f(row0 + ai * HALF + m * 16, col0 + bj * HALF, acc[ai][bj][m][0], acc[ai][bj][m][1]);
	v_mov_b32_e32 v62, v222
	v_mov_b32_e32 v63, v223
	v_mov_b32_e32 v64, v224
	v_mov_b32_e32 v65, v225
	v_lshlrev_b32_e32 v70, 16, v65
	v_mul_f32_e32 v60, 0xbfb8aa3b, v54
	v_exp_f32_e32 v60, v60
	v_lshlrev_b32_e32 v58, 16, v62
	v_and_b32_e32 v59, 0xffff0000, v62
	v_lshlrev_b32_e32 v61, 16, v63
	v_add_f32_e32 v60, 1.0, v60
	v_div_scale_f32 v68, s[2:3], v60, v60, v54
	v_rcp_f32_e32 v69, v68
	v_and_b32_e32 v62, 0xffff0000, v63
	v_lshlrev_b32_e32 v63, 16, v64
	v_and_b32_e32 v64, 0xffff0000, v64
	v_fma_f32 v71, -v68, v69, 1.0
	v_fmac_f32_e32 v69, v71, v69
	v_div_scale_f32 v71, vcc, v54, v60, v54
	v_mul_f32_e32 v72, v71, v69
	v_fma_f32 v74, -v68, v72, v71
	v_fmac_f32_e32 v72, v74, v69
	v_fma_f32 v68, -v68, v72, v71
	v_add_f32_e32 v71, 1.0, v73
	v_div_scale_f32 v73, s[2:3], v71, v71, v50
	v_rcp_f32_e32 v74, v73
	v_div_fmas_f32 v68, v68, v69, v72
	v_div_fixup_f32 v54, v68, v60, v54
	v_mul_f32_e32 v68, 0xbfb8aa3b, v55
	v_exp_f32_e32 v68, v68
	v_mul_f32_e32 v54, v54, v58
	v_fma_f32 v58, -v73, v74, 1.0
	v_fmac_f32_e32 v74, v58, v74
	v_div_scale_f32 v58, vcc, v50, v71, v50
	v_mul_f32_e32 v60, v58, v74
	v_fma_f32 v69, -v73, v60, v58
	v_add_f32_e32 v68, 1.0, v68
	v_fmac_f32_e32 v60, v69, v74
	v_div_scale_f32 v69, s[2:3], v68, v68, v55
	v_fma_f32 v58, -v73, v60, v58
	v_rcp_f32_e32 v72, v69
	v_div_fmas_f32 v58, v58, v74, v60
	v_div_fixup_f32 v50, v58, v71, v50
	v_mul_f32_e32 v58, v50, v63
	v_mul_f32_e32 v63, 0xbfb8aa3b, v51
	v_fma_f32 v50, -v69, v72, 1.0
	v_exp_f32_e32 v63, v63
	v_fmac_f32_e32 v72, v50, v72
	v_div_scale_f32 v50, vcc, v55, v68, v55
	v_mul_f32_e32 v60, v50, v72
	v_fma_f32 v71, -v69, v60, v50
	v_fmac_f32_e32 v60, v71, v72
	v_add_f32_e32 v63, 1.0, v63
	v_fma_f32 v50, -v69, v60, v50
	v_div_scale_f32 v69, s[2:3], v63, v63, v51
	v_rcp_f32_e32 v71, v69
	v_div_fmas_f32 v50, v50, v72, v60
	v_mul_f32_e32 v60, 0xbfb8aa3b, v56
	v_exp_f32_e32 v60, v60
	v_div_fixup_f32 v50, v50, v68, v55
	v_fma_f32 v55, -v69, v71, 1.0
	v_fmac_f32_e32 v71, v55, v71
	v_div_scale_f32 v55, vcc, v51, v63, v51
	v_mul_f32_e32 v50, v50, v59
	v_mul_f32_e32 v59, v55, v71
	v_fma_f32 v68, -v69, v59, v55
	v_add_f32_e32 v60, 1.0, v60
	v_fmac_f32_e32 v59, v68, v71
	v_div_scale_f32 v68, s[2:3], v60, v60, v56
	v_fma_f32 v55, -v69, v59, v55
	v_rcp_f32_e32 v69, v68
	v_div_fmas_f32 v55, v55, v71, v59
	v_div_fixup_f32 v51, v55, v63, v51
	v_mul_f32_e32 v63, 0xbfb8aa3b, v52
	v_exp_f32_e32 v63, v63
	v_mul_f32_e32 v55, v51, v64
	v_fma_f32 v51, -v68, v69, 1.0
	v_fmac_f32_e32 v69, v51, v69
	v_div_scale_f32 v51, vcc, v56, v60, v56
	v_mul_f32_e32 v59, v51, v69
	v_fma_f32 v64, -v68, v59, v51
	v_add_f32_e32 v63, 1.0, v63
	v_fmac_f32_e32 v59, v64, v69
	v_div_scale_f32 v64, s[2:3], v63, v63, v52
	v_fma_f32 v51, -v68, v59, v51
	v_rcp_f32_e32 v68, v64
	v_div_fmas_f32 v51, v51, v69, v59
	v_div_fixup_f32 v51, v51, v60, v56
	v_mul_f32_e32 v60, 0xbfb8aa3b, v57
	v_exp_f32_e32 v60, v60
	v_fma_f32 v56, -v64, v68, 1.0
	v_fmac_f32_e32 v68, v56, v68
	v_div_scale_f32 v56, vcc, v52, v63, v52
	v_mul_f32_e32 v59, v56, v68
	v_mul_f32_e32 v51, v51, v61
	v_fma_f32 v61, -v64, v59, v56
	v_add_f32_e32 v60, 1.0, v60
	v_fmac_f32_e32 v59, v61, v68
	v_div_scale_f32 v61, s[2:3], v60, v60, v57
	v_fma_f32 v56, -v64, v59, v56
	v_rcp_f32_e32 v64, v61
	v_div_fmas_f32 v56, v56, v68, v59
	v_div_fixup_f32 v52, v56, v63, v52
	v_mul_f32_e32 v56, v52, v70
	v_fma_f32 v52, -v61, v64, 1.0
	v_mul_f32_e32 v63, 0xbfb8aa3b, v53
	v_fmac_f32_e32 v64, v52, v64
	v_div_scale_f32 v52, vcc, v57, v60, v57
	v_exp_f32_e32 v63, v63
	v_mul_f32_e32 v59, v52, v64
	v_fma_f32 v68, -v61, v59, v52
	v_fmac_f32_e32 v59, v68, v64
	v_fma_f32 v52, -v61, v59, v52
	v_add_f32_e32 v61, 1.0, v63
	v_div_scale_f32 v63, s[2:3], v61, v61, v53
	v_rcp_f32_e32 v68, v63
	v_div_fmas_f32 v52, v52, v64, v59
	v_div_fixup_f32 v52, v52, v60, v57
	v_mul_f32_e32 v52, v52, v62
	v_fma_f32 v57, -v63, v68, 1.0
	v_fmac_f32_e32 v68, v57, v68
	v_div_scale_f32 v57, vcc, v53, v61, v53
	v_mul_f32_e32 v59, v57, v68
	v_fma_f32 v60, -v63, v59, v57
	v_fmac_f32_e32 v59, v60, v68
	v_fma_f32 v57, -v63, v59, v57
	v_div_fmas_f32 v57, v57, v68, v59
	v_and_b32_e32 v65, 0xffff0000, v65
	v_div_fixup_f32 v53, v57, v61, v53
	v_cvt_pk_bf16_f32 v50, v54, v50
	v_cvt_pk_bf16_f32 v51, v51, v52
	v_cvt_pk_bf16_f32 v52, v58, v55
	v_add_co_u32_e32 v58, vcc, s49, v148
	v_mul_f32_e32 v53, v53, v65
	s_nop 0
	v_addc_co_u32_e32 v59, vcc, 0, v149, vcc
	v_cvt_pk_bf16_f32 v53, v56, v53
	s_waitcnt vmcnt(14)
;     __device__ __forceinline__ void operator()(const f32x4 (&acc)[2][2][4][2], const Unit& u, int wr, int wc, int fr, int fq) const {
;     ...
;         for (int ai = 0; ai < 2; ++ai)
; #pragma unroll
;             for (int m = 0; m < 4; ++m)
; #pragma unroll
;                 for (int bj = 0; bj < 2; ++bj) f(row0 + ai * HALF + m * 16, col0 + bj * HALF, acc[ai][bj][m][0], acc[ai][bj][m][1]);
	v_mov_b32_e32 v54, v226
	v_mov_b32_e32 v55, v227
	v_mov_b32_e32 v56, v228
	v_mov_b32_e32 v57, v229
	v_lshlrev_b32_e32 v61, 16, v56
	global_store_dwordx4 v[66:67], v[50:53], off offset:256
	v_mul_f32_e32 v67, 0xbfb8aa3b, v42
	v_exp_f32_e32 v67, v67
	v_lshlrev_b32_e32 v52, 16, v54
	v_and_b32_e32 v53, 0xffff0000, v54
	v_mul_f32_e32 v54, 0xbfb8aa3b, v46
	v_exp_f32_e32 v54, v54
	v_and_b32_e32 v56, 0xffff0000, v56
	v_lshlrev_b32_e32 v60, 16, v55
	v_lshlrev_b32_e32 v64, 16, v57
	v_add_f32_e32 v54, 1.0, v54
	v_div_scale_f32 v62, s[2:3], v54, v54, v46
	v_rcp_f32_e32 v63, v62
	v_and_b32_e32 v55, 0xffff0000, v55
	v_and_b32_e32 v57, 0xffff0000, v57
	v_lshl_add_u64 v[50:51], v[148:149], 0, s[16:17]
	v_fma_f32 v65, -v62, v63, 1.0
	v_fmac_f32_e32 v63, v65, v63
	v_div_scale_f32 v65, vcc, v46, v54, v46
	v_mul_f32_e32 v66, v65, v63
	v_fma_f32 v68, -v62, v66, v65
	v_fmac_f32_e32 v66, v68, v63
	v_fma_f32 v62, -v62, v66, v65
	v_add_f32_e32 v65, 1.0, v67
	v_div_scale_f32 v67, s[2:3], v65, v65, v42
	v_rcp_f32_e32 v68, v67
	v_div_fmas_f32 v62, v62, v63, v66
	v_div_fixup_f32 v46, v62, v54, v46
	v_mul_f32_e32 v62, 0xbfb8aa3b, v47
	v_exp_f32_e32 v62, v62
	v_mul_f32_e32 v46, v46, v52
	v_fma_f32 v52, -v67, v68, 1.0
	v_fmac_f32_e32 v68, v52, v68
	v_div_scale_f32 v52, vcc, v42, v65, v42
	v_mul_f32_e32 v54, v52, v68
	v_fma_f32 v63, -v67, v54, v52
	v_add_f32_e32 v62, 1.0, v62
	v_fmac_f32_e32 v54, v63, v68
	v_div_scale_f32 v63, s[2:3], v62, v62, v47
	v_fma_f32 v52, -v67, v54, v52
	v_rcp_f32_e32 v66, v63
	v_div_fmas_f32 v52, v52, v68, v54
	v_div_fixup_f32 v42, v52, v65, v42
	v_mul_f32_e32 v52, v42, v61
	v_mul_f32_e32 v61, 0xbfb8aa3b, v43
	v_fma_f32 v42, -v63, v66, 1.0
	v_exp_f32_e32 v61, v61
	v_fmac_f32_e32 v66, v42, v66
	v_div_scale_f32 v42, vcc, v47, v62, v47
	v_mul_f32_e32 v54, v42, v66
	v_fma_f32 v65, -v63, v54, v42
	v_fmac_f32_e32 v54, v65, v66
	v_add_f32_e32 v61, 1.0, v61
	v_fma_f32 v42, -v63, v54, v42
	v_div_scale_f32 v63, s[2:3], v61, v61, v43
	v_rcp_f32_e32 v65, v63
	v_div_fmas_f32 v42, v42, v66, v54
	v_mul_f32_e32 v54, 0xbfb8aa3b, v48
	v_div_fixup_f32 v42, v42, v62, v47
	v_fma_f32 v47, -v63, v65, 1.0
	v_exp_f32_e32 v54, v54
	v_fmac_f32_e32 v65, v47, v65
	v_div_scale_f32 v47, vcc, v43, v61, v43
	v_mul_f32_e32 v42, v42, v53
	v_mul_f32_e32 v53, v47, v65
	v_fma_f32 v62, -v63, v53, v47
	v_fmac_f32_e32 v53, v62, v65
	v_add_f32_e32 v54, 1.0, v54
	v_fma_f32 v47, -v63, v53, v47
	v_div_scale_f32 v62, s[2:3], v54, v54, v48
	v_rcp_f32_e32 v63, v62
	v_div_fmas_f32 v47, v47, v65, v53
	v_div_fixup_f32 v43, v47, v61, v43
	v_mul_f32_e32 v47, v43, v56
	v_mul_f32_e32 v56, 0xbfb8aa3b, v44
	v_exp_f32_e32 v56, v56
	v_fma_f32 v43, -v62, v63, 1.0
	v_fmac_f32_e32 v63, v43, v63
	v_div_scale_f32 v43, vcc, v48, v54, v48
	v_mul_f32_e32 v53, v43, v63
	v_fma_f32 v61, -v62, v53, v43
	v_add_f32_e32 v56, 1.0, v56
	v_fmac_f32_e32 v53, v61, v63
	v_div_scale_f32 v61, s[2:3], v56, v56, v44
	v_fma_f32 v43, -v62, v53, v43
	v_rcp_f32_e32 v62, v61
	v_div_fmas_f32 v43, v43, v63, v53
	v_div_fixup_f32 v43, v43, v54, v48
	v_mul_f32_e32 v54, 0xbfb8aa3b, v49
	v_exp_f32_e32 v54, v54
	v_fma_f32 v48, -v61, v62, 1.0
	v_fmac_f32_e32 v62, v48, v62
	v_div_scale_f32 v48, vcc, v44, v56, v44
	v_mul_f32_e32 v53, v48, v62
	v_mul_f32_e32 v43, v43, v60
	v_fma_f32 v60, -v61, v53, v48
	v_add_f32_e32 v54, 1.0, v54
	v_fmac_f32_e32 v53, v60, v62
	v_div_scale_f32 v60, s[2:3], v54, v54, v49
	v_fma_f32 v48, -v61, v53, v48
	v_rcp_f32_e32 v61, v60
	v_div_fmas_f32 v48, v48, v62, v53
	v_div_fixup_f32 v44, v48, v56, v44
	v_mul_f32_e32 v56, 0xbfb8aa3b, v45
	v_mul_f32_e32 v48, v44, v64
	v_fma_f32 v44, -v60, v61, 1.0
	v_exp_f32_e32 v56, v56
	v_fmac_f32_e32 v61, v44, v61
	v_div_scale_f32 v44, vcc, v49, v54, v49
	v_mul_f32_e32 v53, v44, v61
	v_fma_f32 v62, -v60, v53, v44
	v_fmac_f32_e32 v53, v62, v61
	v_add_f32_e32 v56, 1.0, v56
	v_fma_f32 v44, -v60, v53, v44
	v_div_scale_f32 v60, s[2:3], v56, v56, v45
	v_rcp_f32_e32 v62, v60
	v_div_fmas_f32 v44, v44, v61, v53
	v_div_fixup_f32 v44, v44, v54, v49
	v_mul_f32_e32 v44, v44, v55
	v_fma_f32 v49, -v60, v62, 1.0
	v_fmac_f32_e32 v62, v49, v62
	v_div_scale_f32 v49, vcc, v45, v56, v45
	v_mul_f32_e32 v53, v49, v62
	v_fma_f32 v54, -v60, v53, v49
	v_fmac_f32_e32 v53, v54, v62
	v_fma_f32 v49, -v60, v53, v49
	v_div_fmas_f32 v49, v49, v62, v53
	v_div_fixup_f32 v45, v49, v56, v45
	v_mul_f32_e32 v45, v45, v57
	v_cvt_pk_bf16_f32 v42, v46, v42
	v_cvt_pk_bf16_f32 v43, v43, v44
	v_cvt_pk_bf16_f32 v44, v52, v47
	v_cvt_pk_bf16_f32 v45, v48, v45
	v_mul_f32_e32 v57, 0xbfb8aa3b, v34
	global_store_dwordx4 v[58:59], v[42:45], off
	v_exp_f32_e32 v57, v57
	s_waitcnt vmcnt(14)
;     __device__ __forceinline__ void operator()(const f32x4 (&acc)[2][2][4][2], const Unit& u, int wr, int wc, int fr, int fq) const {
;     ...
;         for (int ai = 0; ai < 2; ++ai)
; #pragma unroll
;             for (int m = 0; m < 4; ++m)
; #pragma unroll
;                 for (int bj = 0; bj < 2; ++bj) f(row0 + ai * HALF + m * 16, col0 + bj * HALF, acc[ai][bj][m][0], acc[ai][bj][m][1]);
	v_mov_b32_e32 v46, v230
	v_mov_b32_e32 v47, v231
	v_mov_b32_e32 v48, v232
	v_mov_b32_e32 v49, v233
	v_lshlrev_b32_e32 v54, 16, v49
	v_mul_f32_e32 v44, 0xbfb8aa3b, v38
	v_exp_f32_e32 v44, v44
	v_lshlrev_b32_e32 v42, 16, v46
	v_and_b32_e32 v43, 0xffff0000, v46
	v_lshlrev_b32_e32 v45, 16, v47
	v_add_f32_e32 v44, 1.0, v44
	v_div_scale_f32 v52, s[2:3], v44, v44, v38
	v_rcp_f32_e32 v53, v52
	v_and_b32_e32 v46, 0xffff0000, v47
	v_lshlrev_b32_e32 v47, 16, v48
	v_and_b32_e32 v48, 0xffff0000, v48
	v_fma_f32 v55, -v52, v53, 1.0
	v_fmac_f32_e32 v53, v55, v53
	v_div_scale_f32 v55, vcc, v38, v44, v38
	v_mul_f32_e32 v56, v55, v53
	v_fma_f32 v58, -v52, v56, v55
	v_fmac_f32_e32 v56, v58, v53
	v_fma_f32 v52, -v52, v56, v55
	v_add_f32_e32 v55, 1.0, v57
	v_div_scale_f32 v57, s[2:3], v55, v55, v34
	v_rcp_f32_e32 v58, v57
	v_div_fmas_f32 v52, v52, v53, v56
	v_div_fixup_f32 v38, v52, v44, v38
	v_mul_f32_e32 v52, 0xbfb8aa3b, v39
	v_exp_f32_e32 v52, v52
	v_mul_f32_e32 v38, v38, v42
	v_fma_f32 v42, -v57, v58, 1.0
	v_fmac_f32_e32 v58, v42, v58
	v_div_scale_f32 v42, vcc, v34, v55, v34
	v_mul_f32_e32 v44, v42, v58
	v_fma_f32 v53, -v57, v44, v42
	v_add_f32_e32 v52, 1.0, v52
	v_fmac_f32_e32 v44, v53, v58
	v_div_scale_f32 v53, s[2:3], v52, v52, v39
	v_fma_f32 v42, -v57, v44, v42
	v_rcp_f32_e32 v56, v53
	v_div_fmas_f32 v42, v42, v58, v44
	v_div_fixup_f32 v34, v42, v55, v34
	v_mul_f32_e32 v42, v34, v47
	v_mul_f32_e32 v47, 0xbfb8aa3b, v35
	v_fma_f32 v34, -v53, v56, 1.0
	v_exp_f32_e32 v47, v47
	v_fmac_f32_e32 v56, v34, v56
	v_div_scale_f32 v34, vcc, v39, v52, v39
	v_mul_f32_e32 v44, v34, v56
	v_fma_f32 v55, -v53, v44, v34
	v_fmac_f32_e32 v44, v55, v56
	v_add_f32_e32 v47, 1.0, v47
	v_fma_f32 v34, -v53, v44, v34
	v_div_scale_f32 v53, s[2:3], v47, v47, v35
	v_rcp_f32_e32 v55, v53
	v_div_fmas_f32 v34, v34, v56, v44
	v_mul_f32_e32 v44, 0xbfb8aa3b, v40
	v_exp_f32_e32 v44, v44
	v_div_fixup_f32 v34, v34, v52, v39
	v_fma_f32 v39, -v53, v55, 1.0
	v_fmac_f32_e32 v55, v39, v55
	v_div_scale_f32 v39, vcc, v35, v47, v35
	v_mul_f32_e32 v34, v34, v43
	v_mul_f32_e32 v43, v39, v55
	v_fma_f32 v52, -v53, v43, v39
	v_add_f32_e32 v44, 1.0, v44
	v_fmac_f32_e32 v43, v52, v55
	v_div_scale_f32 v52, s[2:3], v44, v44, v40
	v_fma_f32 v39, -v53, v43, v39
	v_rcp_f32_e32 v53, v52
	v_div_fmas_f32 v39, v39, v55, v43
	v_div_fixup_f32 v35, v39, v47, v35
	v_mul_f32_e32 v47, 0xbfb8aa3b, v36
	v_exp_f32_e32 v47, v47
	v_mul_f32_e32 v39, v35, v48
	v_fma_f32 v35, -v52, v53, 1.0
	v_fmac_f32_e32 v53, v35, v53
	v_div_scale_f32 v35, vcc, v40, v44, v40
	v_mul_f32_e32 v43, v35, v53
	v_fma_f32 v48, -v52, v43, v35
	v_add_f32_e32 v47, 1.0, v47
	v_fmac_f32_e32 v43, v48, v53
	v_div_scale_f32 v48, s[2:3], v47, v47, v36
	v_fma_f32 v35, -v52, v43, v35
	v_rcp_f32_e32 v52, v48
	v_div_fmas_f32 v35, v35, v53, v43
	v_div_fixup_f32 v35, v35, v44, v40
	v_mul_f32_e32 v44, 0xbfb8aa3b, v41
	v_exp_f32_e32 v44, v44
	v_fma_f32 v40, -v48, v52, 1.0
	v_fmac_f32_e32 v52, v40, v52
	v_div_scale_f32 v40, vcc, v36, v47, v36
	v_mul_f32_e32 v43, v40, v52
	v_mul_f32_e32 v35, v35, v45
	v_fma_f32 v45, -v48, v43, v40
	v_add_f32_e32 v44, 1.0, v44
	v_fmac_f32_e32 v43, v45, v52
	v_div_scale_f32 v45, s[2:3], v44, v44, v41
	v_fma_f32 v40, -v48, v43, v40
	v_rcp_f32_e32 v48, v45
	v_div_fmas_f32 v40, v40, v52, v43
	v_div_fixup_f32 v36, v40, v47, v36
	v_mul_f32_e32 v40, v36, v54
	v_fma_f32 v36, -v45, v48, 1.0
	v_mul_f32_e32 v47, 0xbfb8aa3b, v37
	v_fmac_f32_e32 v48, v36, v48
	v_div_scale_f32 v36, vcc, v41, v44, v41
	v_exp_f32_e32 v47, v47
	v_mul_f32_e32 v43, v36, v48
	v_fma_f32 v52, -v45, v43, v36
	v_fmac_f32_e32 v43, v52, v48
	v_fma_f32 v36, -v45, v43, v36
	v_add_f32_e32 v45, 1.0, v47
	v_div_scale_f32 v47, s[2:3], v45, v45, v37
	v_rcp_f32_e32 v52, v47
	v_div_fmas_f32 v36, v36, v48, v43
	v_div_fixup_f32 v36, v36, v44, v41
	v_mul_f32_e32 v36, v36, v46
	v_fma_f32 v41, -v47, v52, 1.0
	v_fmac_f32_e32 v52, v41, v52
	v_div_scale_f32 v41, vcc, v37, v45, v37
	v_mul_f32_e32 v43, v41, v52
	v_fma_f32 v44, -v47, v43, v41
	v_fmac_f32_e32 v43, v44, v52
	v_fma_f32 v41, -v47, v43, v41
	v_div_fmas_f32 v41, v41, v52, v43
	v_and_b32_e32 v49, 0xffff0000, v49
	v_div_fixup_f32 v37, v41, v45, v37
	v_cvt_pk_bf16_f32 v34, v38, v34
	v_cvt_pk_bf16_f32 v35, v35, v36
	v_cvt_pk_bf16_f32 v36, v42, v39
	v_add_co_u32_e32 v42, vcc, s50, v148
	v_mul_f32_e32 v37, v37, v49
	s_nop 0
	v_addc_co_u32_e32 v43, vcc, 0, v149, vcc
	v_cvt_pk_bf16_f32 v37, v40, v37
	s_waitcnt vmcnt(14)
;     __device__ __forceinline__ void operator()(const f32x4 (&acc)[2][2][4][2], const Unit& u, int wr, int wc, int fr, int fq) const {
;     ...
;         for (int ai = 0; ai < 2; ++ai)
; #pragma unroll
;             for (int m = 0; m < 4; ++m)
; #pragma unroll
;                 for (int bj = 0; bj < 2; ++bj) f(row0 + ai * HALF + m * 16, col0 + bj * HALF, acc[ai][bj][m][0], acc[ai][bj][m][1]);
	v_mov_b32_e32 v38, v234
	v_mov_b32_e32 v39, v235
	v_mov_b32_e32 v40, v236
	v_mov_b32_e32 v41, v237
	v_lshlrev_b32_e32 v45, 16, v40
	global_store_dwordx4 v[50:51], v[34:37], off offset:256
	v_mul_f32_e32 v51, 0xbfb8aa3b, v26
	v_exp_f32_e32 v51, v51
	v_lshlrev_b32_e32 v36, 16, v38
	v_and_b32_e32 v37, 0xffff0000, v38
	v_mul_f32_e32 v38, 0xbfb8aa3b, v30
	v_exp_f32_e32 v38, v38
	v_and_b32_e32 v40, 0xffff0000, v40
	v_lshlrev_b32_e32 v44, 16, v39
	v_lshlrev_b32_e32 v48, 16, v41
	v_add_f32_e32 v38, 1.0, v38
	v_div_scale_f32 v46, s[2:3], v38, v38, v30
	v_rcp_f32_e32 v47, v46
	v_and_b32_e32 v39, 0xffff0000, v39
	v_and_b32_e32 v41, 0xffff0000, v41
	v_lshl_add_u64 v[34:35], v[148:149], 0, s[18:19]
	v_fma_f32 v49, -v46, v47, 1.0
	v_fmac_f32_e32 v47, v49, v47
	v_div_scale_f32 v49, vcc, v30, v38, v30
	v_mul_f32_e32 v50, v49, v47
	v_fma_f32 v52, -v46, v50, v49
	v_fmac_f32_e32 v50, v52, v47
	v_fma_f32 v46, -v46, v50, v49
	v_add_f32_e32 v49, 1.0, v51
	v_div_scale_f32 v51, s[2:3], v49, v49, v26
	v_rcp_f32_e32 v52, v51
	v_div_fmas_f32 v46, v46, v47, v50
	v_div_fixup_f32 v30, v46, v38, v30
	v_mul_f32_e32 v46, 0xbfb8aa3b, v31
	v_exp_f32_e32 v46, v46
	v_mul_f32_e32 v30, v30, v36
	v_fma_f32 v36, -v51, v52, 1.0
	v_fmac_f32_e32 v52, v36, v52
	v_div_scale_f32 v36, vcc, v26, v49, v26
	v_mul_f32_e32 v38, v36, v52
	v_fma_f32 v47, -v51, v38, v36
	v_add_f32_e32 v46, 1.0, v46
	v_fmac_f32_e32 v38, v47, v52
	v_div_scale_f32 v47, s[2:3], v46, v46, v31
	v_fma_f32 v36, -v51, v38, v36
	v_rcp_f32_e32 v50, v47
	v_div_fmas_f32 v36, v36, v52, v38
	v_div_fixup_f32 v26, v36, v49, v26
	v_mul_f32_e32 v36, v26, v45
	v_mul_f32_e32 v45, 0xbfb8aa3b, v27
	v_fma_f32 v26, -v47, v50, 1.0
	v_exp_f32_e32 v45, v45
	v_fmac_f32_e32 v50, v26, v50
	v_div_scale_f32 v26, vcc, v31, v46, v31
	v_mul_f32_e32 v38, v26, v50
	v_fma_f32 v49, -v47, v38, v26
	v_fmac_f32_e32 v38, v49, v50
	v_add_f32_e32 v45, 1.0, v45
	v_fma_f32 v26, -v47, v38, v26
	v_div_scale_f32 v47, s[2:3], v45, v45, v27
	v_rcp_f32_e32 v49, v47
	v_div_fmas_f32 v26, v26, v50, v38
	v_mul_f32_e32 v38, 0xbfb8aa3b, v32
	v_div_fixup_f32 v26, v26, v46, v31
	v_fma_f32 v31, -v47, v49, 1.0
	v_exp_f32_e32 v38, v38
	v_fmac_f32_e32 v49, v31, v49
	v_div_scale_f32 v31, vcc, v27, v45, v27
	v_mul_f32_e32 v26, v26, v37
	v_mul_f32_e32 v37, v31, v49
	v_fma_f32 v46, -v47, v37, v31
	v_fmac_f32_e32 v37, v46, v49
	v_add_f32_e32 v38, 1.0, v38
	v_fma_f32 v31, -v47, v37, v31
	v_div_scale_f32 v46, s[2:3], v38, v38, v32
	v_rcp_f32_e32 v47, v46
	v_div_fmas_f32 v31, v31, v49, v37
	v_div_fixup_f32 v27, v31, v45, v27
	v_mul_f32_e32 v31, v27, v40
	v_mul_f32_e32 v40, 0xbfb8aa3b, v28
	v_exp_f32_e32 v40, v40
	v_fma_f32 v27, -v46, v47, 1.0
	v_fmac_f32_e32 v47, v27, v47
	v_div_scale_f32 v27, vcc, v32, v38, v32
	v_mul_f32_e32 v37, v27, v47
	v_fma_f32 v45, -v46, v37, v27
	v_add_f32_e32 v40, 1.0, v40
	v_fmac_f32_e32 v37, v45, v47
	v_div_scale_f32 v45, s[2:3], v40, v40, v28
	v_fma_f32 v27, -v46, v37, v27
	v_rcp_f32_e32 v46, v45
	v_div_fmas_f32 v27, v27, v47, v37
	v_div_fixup_f32 v27, v27, v38, v32
	v_mul_f32_e32 v38, 0xbfb8aa3b, v33
	v_exp_f32_e32 v38, v38
	v_fma_f32 v32, -v45, v46, 1.0
	v_fmac_f32_e32 v46, v32, v46
	v_div_scale_f32 v32, vcc, v28, v40, v28
	v_mul_f32_e32 v37, v32, v46
	v_mul_f32_e32 v27, v27, v44
	v_fma_f32 v44, -v45, v37, v32
	v_add_f32_e32 v38, 1.0, v38
	v_fmac_f32_e32 v37, v44, v46
	v_div_scale_f32 v44, s[2:3], v38, v38, v33
	v_fma_f32 v32, -v45, v37, v32
	v_rcp_f32_e32 v45, v44
	v_div_fmas_f32 v32, v32, v46, v37
	v_div_fixup_f32 v28, v32, v40, v28
	v_mul_f32_e32 v40, 0xbfb8aa3b, v29
	v_mul_f32_e32 v32, v28, v48
	v_fma_f32 v28, -v44, v45, 1.0
	v_exp_f32_e32 v40, v40
	v_fmac_f32_e32 v45, v28, v45
	v_div_scale_f32 v28, vcc, v33, v38, v33
	v_mul_f32_e32 v37, v28, v45
	v_fma_f32 v46, -v44, v37, v28
	v_fmac_f32_e32 v37, v46, v45
	v_add_f32_e32 v40, 1.0, v40
	v_fma_f32 v28, -v44, v37, v28
	v_div_scale_f32 v44, s[2:3], v40, v40, v29
	v_rcp_f32_e32 v46, v44
	v_div_fmas_f32 v28, v28, v45, v37
	v_div_fixup_f32 v28, v28, v38, v33
	v_mul_f32_e32 v28, v28, v39
	v_fma_f32 v33, -v44, v46, 1.0
	v_fmac_f32_e32 v46, v33, v46
	v_div_scale_f32 v33, vcc, v29, v40, v29
	v_mul_f32_e32 v37, v33, v46
	v_fma_f32 v38, -v44, v37, v33
	v_fmac_f32_e32 v37, v38, v46
	v_fma_f32 v33, -v44, v37, v33
	v_div_fmas_f32 v33, v33, v46, v37
	v_div_fixup_f32 v29, v33, v40, v29
	v_mul_f32_e32 v29, v29, v41
	v_cvt_pk_bf16_f32 v26, v30, v26
	v_cvt_pk_bf16_f32 v27, v27, v28
	v_cvt_pk_bf16_f32 v28, v36, v31
	v_cvt_pk_bf16_f32 v29, v32, v29
	v_mul_f32_e32 v41, 0xbfb8aa3b, v18
	global_store_dwordx4 v[42:43], v[26:29], off
	v_exp_f32_e32 v41, v41
	s_waitcnt vmcnt(14)
;     __device__ __forceinline__ void operator()(const f32x4 (&acc)[2][2][4][2], const Unit& u, int wr, int wc, int fr, int fq) const {
;     ...
;         for (int ai = 0; ai < 2; ++ai)
; #pragma unroll
;             for (int m = 0; m < 4; ++m)
; #pragma unroll
;                 for (int bj = 0; bj < 2; ++bj) f(row0 + ai * HALF + m * 16, col0 + bj * HALF, acc[ai][bj][m][0], acc[ai][bj][m][1]);
	v_mov_b32_e32 v30, v238
	v_mov_b32_e32 v31, v239
	v_mov_b32_e32 v32, v240
	v_mov_b32_e32 v33, v241
	v_lshlrev_b32_e32 v38, 16, v33
	v_mul_f32_e32 v28, 0xbfb8aa3b, v22
	v_exp_f32_e32 v28, v28
	v_lshlrev_b32_e32 v26, 16, v30
	v_and_b32_e32 v27, 0xffff0000, v30
	v_lshlrev_b32_e32 v29, 16, v31
	v_add_f32_e32 v28, 1.0, v28
	v_div_scale_f32 v36, s[2:3], v28, v28, v22
	v_rcp_f32_e32 v37, v36
	v_and_b32_e32 v30, 0xffff0000, v31
	v_lshlrev_b32_e32 v31, 16, v32
	v_and_b32_e32 v32, 0xffff0000, v32
	v_fma_f32 v39, -v36, v37, 1.0
	v_fmac_f32_e32 v37, v39, v37
	v_div_scale_f32 v39, vcc, v22, v28, v22
	v_mul_f32_e32 v40, v39, v37
	v_fma_f32 v42, -v36, v40, v39
	v_fmac_f32_e32 v40, v42, v37
	v_fma_f32 v36, -v36, v40, v39
	v_add_f32_e32 v39, 1.0, v41
	v_div_scale_f32 v41, s[2:3], v39, v39, v18
	v_rcp_f32_e32 v42, v41
	v_div_fmas_f32 v36, v36, v37, v40
	v_div_fixup_f32 v22, v36, v28, v22
	v_mul_f32_e32 v36, 0xbfb8aa3b, v23
	v_exp_f32_e32 v36, v36
	v_mul_f32_e32 v22, v22, v26
	v_fma_f32 v26, -v41, v42, 1.0
	v_fmac_f32_e32 v42, v26, v42
	v_div_scale_f32 v26, vcc, v18, v39, v18
	v_mul_f32_e32 v28, v26, v42
	v_fma_f32 v37, -v41, v28, v26
	v_add_f32_e32 v36, 1.0, v36
	v_fmac_f32_e32 v28, v37, v42
	v_div_scale_f32 v37, s[2:3], v36, v36, v23
	v_fma_f32 v26, -v41, v28, v26
	v_rcp_f32_e32 v40, v37
	v_div_fmas_f32 v26, v26, v42, v28
	v_div_fixup_f32 v18, v26, v39, v18
	v_mul_f32_e32 v26, v18, v31
	v_mul_f32_e32 v31, 0xbfb8aa3b, v19
	v_fma_f32 v18, -v37, v40, 1.0
	v_exp_f32_e32 v31, v31
	v_fmac_f32_e32 v40, v18, v40
	v_div_scale_f32 v18, vcc, v23, v36, v23
	v_mul_f32_e32 v28, v18, v40
	v_fma_f32 v39, -v37, v28, v18
	v_fmac_f32_e32 v28, v39, v40
	v_add_f32_e32 v31, 1.0, v31
	v_fma_f32 v18, -v37, v28, v18
	v_div_scale_f32 v37, s[2:3], v31, v31, v19
	v_rcp_f32_e32 v39, v37
	v_div_fmas_f32 v18, v18, v40, v28
	v_mul_f32_e32 v28, 0xbfb8aa3b, v24
	v_exp_f32_e32 v28, v28
	v_div_fixup_f32 v18, v18, v36, v23
	v_fma_f32 v23, -v37, v39, 1.0
	v_fmac_f32_e32 v39, v23, v39
	v_div_scale_f32 v23, vcc, v19, v31, v19
	v_mul_f32_e32 v18, v18, v27
	v_mul_f32_e32 v27, v23, v39
	v_fma_f32 v36, -v37, v27, v23
	v_add_f32_e32 v28, 1.0, v28
	v_fmac_f32_e32 v27, v36, v39
	v_div_scale_f32 v36, s[2:3], v28, v28, v24
	v_fma_f32 v23, -v37, v27, v23
	v_rcp_f32_e32 v37, v36
	v_div_fmas_f32 v23, v23, v39, v27
	v_div_fixup_f32 v19, v23, v31, v19
	v_mul_f32_e32 v31, 0xbfb8aa3b, v20
	v_exp_f32_e32 v31, v31
	v_mul_f32_e32 v23, v19, v32
	v_fma_f32 v19, -v36, v37, 1.0
	v_fmac_f32_e32 v37, v19, v37
	v_div_scale_f32 v19, vcc, v24, v28, v24
	v_mul_f32_e32 v27, v19, v37
	v_fma_f32 v32, -v36, v27, v19
	v_add_f32_e32 v31, 1.0, v31
	v_fmac_f32_e32 v27, v32, v37
	v_div_scale_f32 v32, s[2:3], v31, v31, v20
	v_fma_f32 v19, -v36, v27, v19
	v_rcp_f32_e32 v36, v32
	v_div_fmas_f32 v19, v19, v37, v27
	v_div_fixup_f32 v19, v19, v28, v24
	v_mul_f32_e32 v28, 0xbfb8aa3b, v25
	v_exp_f32_e32 v28, v28
	v_fma_f32 v24, -v32, v36, 1.0
	v_fmac_f32_e32 v36, v24, v36
	v_div_scale_f32 v24, vcc, v20, v31, v20
	v_mul_f32_e32 v27, v24, v36
	v_mul_f32_e32 v19, v19, v29
	v_fma_f32 v29, -v32, v27, v24
	v_add_f32_e32 v28, 1.0, v28
	v_fmac_f32_e32 v27, v29, v36
	v_div_scale_f32 v29, s[2:3], v28, v28, v25
	v_fma_f32 v24, -v32, v27, v24
	v_rcp_f32_e32 v32, v29
	v_div_fmas_f32 v24, v24, v36, v27
	v_div_fixup_f32 v20, v24, v31, v20
	v_mul_f32_e32 v24, v20, v38
	v_fma_f32 v20, -v29, v32, 1.0
	v_mul_f32_e32 v31, 0xbfb8aa3b, v21
	v_fmac_f32_e32 v32, v20, v32
	v_div_scale_f32 v20, vcc, v25, v28, v25
	v_exp_f32_e32 v31, v31
	v_mul_f32_e32 v27, v20, v32
	v_fma_f32 v36, -v29, v27, v20
	v_fmac_f32_e32 v27, v36, v32
	v_fma_f32 v20, -v29, v27, v20
	v_add_f32_e32 v29, 1.0, v31
	v_div_scale_f32 v31, s[2:3], v29, v29, v21
	v_rcp_f32_e32 v36, v31
	v_div_fmas_f32 v20, v20, v32, v27
	v_div_fixup_f32 v20, v20, v28, v25
	v_mul_f32_e32 v20, v20, v30
	v_fma_f32 v25, -v31, v36, 1.0
	v_fmac_f32_e32 v36, v25, v36
	v_div_scale_f32 v25, vcc, v21, v29, v21
	v_mul_f32_e32 v27, v25, v36
	v_fma_f32 v28, -v31, v27, v25
	v_fmac_f32_e32 v27, v28, v36
	v_fma_f32 v25, -v31, v27, v25
	v_div_fmas_f32 v25, v25, v36, v27
	v_and_b32_e32 v33, 0xffff0000, v33
	v_div_fixup_f32 v21, v25, v29, v21
	v_cvt_pk_bf16_f32 v18, v22, v18
	v_cvt_pk_bf16_f32 v19, v19, v20
	v_cvt_pk_bf16_f32 v20, v26, v23
	v_add_co_u32_e32 v26, vcc, s51, v148
	v_mul_f32_e32 v21, v21, v33
	s_nop 0
	v_addc_co_u32_e32 v27, vcc, 0, v149, vcc
	v_cvt_pk_bf16_f32 v21, v24, v21
	s_waitcnt vmcnt(14)
;     __device__ __forceinline__ void operator()(const f32x4 (&acc)[2][2][4][2], const Unit& u, int wr, int wc, int fr, int fq) const {
;     ...
;         for (int ai = 0; ai < 2; ++ai)
; #pragma unroll
;             for (int m = 0; m < 4; ++m)
; #pragma unroll
;                 for (int bj = 0; bj < 2; ++bj) f(row0 + ai * HALF + m * 16, col0 + bj * HALF, acc[ai][bj][m][0], acc[ai][bj][m][1]);
	v_mov_b32_e32 v22, v242
	v_mov_b32_e32 v23, v243
	v_mov_b32_e32 v24, v244
	v_mov_b32_e32 v25, v245
	v_lshlrev_b32_e32 v29, 16, v24
	global_store_dwordx4 v[34:35], v[18:21], off offset:256
	v_mul_f32_e32 v35, 0xbfb8aa3b, v10
	v_exp_f32_e32 v35, v35
	v_lshlrev_b32_e32 v20, 16, v22
	v_and_b32_e32 v21, 0xffff0000, v22
	v_mul_f32_e32 v22, 0xbfb8aa3b, v14
	v_exp_f32_e32 v22, v22
	v_and_b32_e32 v24, 0xffff0000, v24
	v_lshlrev_b32_e32 v28, 16, v23
	v_lshlrev_b32_e32 v32, 16, v25
	v_add_f32_e32 v22, 1.0, v22
	v_div_scale_f32 v30, s[2:3], v22, v22, v14
	v_rcp_f32_e32 v31, v30
	v_and_b32_e32 v23, 0xffff0000, v23
	v_and_b32_e32 v25, 0xffff0000, v25
	v_lshl_add_u64 v[18:19], v[148:149], 0, s[20:21]
	v_fma_f32 v33, -v30, v31, 1.0
	v_fmac_f32_e32 v31, v33, v31
	v_div_scale_f32 v33, vcc, v14, v22, v14
	v_mul_f32_e32 v34, v33, v31
	v_fma_f32 v36, -v30, v34, v33
	v_fmac_f32_e32 v34, v36, v31
	v_fma_f32 v30, -v30, v34, v33
	v_add_f32_e32 v33, 1.0, v35
	v_div_scale_f32 v35, s[2:3], v33, v33, v10
	v_rcp_f32_e32 v36, v35
	v_div_fmas_f32 v30, v30, v31, v34
	v_div_fixup_f32 v14, v30, v22, v14
	v_mul_f32_e32 v30, 0xbfb8aa3b, v15
	v_exp_f32_e32 v30, v30
	v_mul_f32_e32 v14, v14, v20
	v_fma_f32 v20, -v35, v36, 1.0
	v_fmac_f32_e32 v36, v20, v36
	v_div_scale_f32 v20, vcc, v10, v33, v10
	v_mul_f32_e32 v22, v20, v36
	v_fma_f32 v31, -v35, v22, v20
	v_add_f32_e32 v30, 1.0, v30
	v_fmac_f32_e32 v22, v31, v36
	v_div_scale_f32 v31, s[2:3], v30, v30, v15
	v_fma_f32 v20, -v35, v22, v20
	v_rcp_f32_e32 v34, v31
	v_div_fmas_f32 v20, v20, v36, v22
	v_div_fixup_f32 v10, v20, v33, v10
	v_mul_f32_e32 v20, v10, v29
	v_mul_f32_e32 v29, 0xbfb8aa3b, v11
	v_fma_f32 v10, -v31, v34, 1.0
	v_exp_f32_e32 v29, v29
	v_fmac_f32_e32 v34, v10, v34
	v_div_scale_f32 v10, vcc, v15, v30, v15
	v_mul_f32_e32 v22, v10, v34
	v_fma_f32 v33, -v31, v22, v10
	v_fmac_f32_e32 v22, v33, v34
	v_add_f32_e32 v29, 1.0, v29
	v_fma_f32 v10, -v31, v22, v10
	v_div_scale_f32 v31, s[2:3], v29, v29, v11
	v_rcp_f32_e32 v33, v31
	v_div_fmas_f32 v10, v10, v34, v22
	v_mul_f32_e32 v22, 0xbfb8aa3b, v16
	v_div_fixup_f32 v10, v10, v30, v15
	v_fma_f32 v15, -v31, v33, 1.0
	v_exp_f32_e32 v22, v22
	v_fmac_f32_e32 v33, v15, v33
	v_div_scale_f32 v15, vcc, v11, v29, v11
	v_mul_f32_e32 v10, v10, v21
	v_mul_f32_e32 v21, v15, v33
	v_fma_f32 v30, -v31, v21, v15
	v_fmac_f32_e32 v21, v30, v33
	v_add_f32_e32 v22, 1.0, v22
	v_fma_f32 v15, -v31, v21, v15
	v_div_scale_f32 v30, s[2:3], v22, v22, v16
	v_rcp_f32_e32 v31, v30
	v_div_fmas_f32 v15, v15, v33, v21
	v_div_fixup_f32 v11, v15, v29, v11
	v_mul_f32_e32 v15, v11, v24
	v_mul_f32_e32 v24, 0xbfb8aa3b, v12
	v_exp_f32_e32 v24, v24
	v_fma_f32 v11, -v30, v31, 1.0
	v_fmac_f32_e32 v31, v11, v31
	v_div_scale_f32 v11, vcc, v16, v22, v16
	v_mul_f32_e32 v21, v11, v31
	v_fma_f32 v29, -v30, v21, v11
	v_add_f32_e32 v24, 1.0, v24
	v_fmac_f32_e32 v21, v29, v31
	v_div_scale_f32 v29, s[2:3], v24, v24, v12
	v_fma_f32 v11, -v30, v21, v11
	v_rcp_f32_e32 v30, v29
	v_div_fmas_f32 v11, v11, v31, v21
	v_div_fixup_f32 v11, v11, v22, v16
	v_mul_f32_e32 v22, 0xbfb8aa3b, v17
	v_exp_f32_e32 v22, v22
	v_fma_f32 v16, -v29, v30, 1.0
	v_fmac_f32_e32 v30, v16, v30
	v_div_scale_f32 v16, vcc, v12, v24, v12
	v_mul_f32_e32 v21, v16, v30
	v_mul_f32_e32 v11, v11, v28
	v_fma_f32 v28, -v29, v21, v16
	v_add_f32_e32 v22, 1.0, v22
	v_fmac_f32_e32 v21, v28, v30
	v_div_scale_f32 v28, s[2:3], v22, v22, v17
	v_fma_f32 v16, -v29, v21, v16
	v_rcp_f32_e32 v29, v28
	v_div_fmas_f32 v16, v16, v30, v21
	v_div_fixup_f32 v12, v16, v24, v12
	v_mul_f32_e32 v24, 0xbfb8aa3b, v13
	v_mul_f32_e32 v16, v12, v32
	v_fma_f32 v12, -v28, v29, 1.0
	v_exp_f32_e32 v24, v24
	v_fmac_f32_e32 v29, v12, v29
	v_div_scale_f32 v12, vcc, v17, v22, v17
	v_mul_f32_e32 v21, v12, v29
	v_fma_f32 v30, -v28, v21, v12
	v_fmac_f32_e32 v21, v30, v29
	v_add_f32_e32 v24, 1.0, v24
	v_fma_f32 v12, -v28, v21, v12
	v_div_scale_f32 v28, s[2:3], v24, v24, v13
	v_rcp_f32_e32 v30, v28
	v_div_fmas_f32 v12, v12, v29, v21
	v_div_fixup_f32 v12, v12, v22, v17
	v_mul_f32_e32 v12, v12, v23
	v_fma_f32 v17, -v28, v30, 1.0
	v_fmac_f32_e32 v30, v17, v30
	v_div_scale_f32 v17, vcc, v13, v24, v13
	v_mul_f32_e32 v21, v17, v30
	v_fma_f32 v22, -v28, v21, v17
	v_fmac_f32_e32 v21, v22, v30
	v_fma_f32 v17, -v28, v21, v17
	v_div_fmas_f32 v17, v17, v30, v21
	v_div_fixup_f32 v13, v17, v24, v13
	v_mul_f32_e32 v13, v13, v25
	v_cvt_pk_bf16_f32 v10, v14, v10
	v_cvt_pk_bf16_f32 v11, v11, v12
	v_cvt_pk_bf16_f32 v12, v20, v15
	v_cvt_pk_bf16_f32 v13, v16, v13
	v_mul_f32_e32 v25, 0xbfb8aa3b, v2
	global_store_dwordx4 v[26:27], v[10:13], off
	v_exp_f32_e32 v25, v25
	s_waitcnt vmcnt(14)
; #define PG8_WAIT_V(n) asm volatile("s_waitcnt vmcnt(" #n ")" ::: "memory")
; #define PG8_BAR __builtin_amdgcn_s_barrier()
; template <class Epi>
; __device__ __forceinline__ void gemm_phase(PG8_LAS unsigned char* lds, const Gemm g, const StaticOrder& S, const Epi& E) {
;     ...
;         E(acc, cur, wr, wc, fr, fq);
;         if (!has_next) break;
; #pragma unroll
;         for (int a = 0; a < 2; ++a)
; #pragma unroll
;             for (int b = 0; b < 2; ++b)
; #pragma unroll
;                 for (int m = 0; m < 4; ++m)
; #pragma unroll
;                     for (int n = 0; n < 2; ++n) acc[a][b][m][n] = (f32x4){0.f, 0.f, 0.f, 0.f};
;         cur = nxt; cA = nA; cB = nB; ++ui;
;     }
;     PG8_WAIT_V(0);
;     if (wr == 0) PG8_BAR;
;     PG8_BAR;
	v_mov_b32_e32 v14, v246
	v_mov_b32_e32 v15, v247
	v_mov_b32_e32 v16, v248
	v_mov_b32_e32 v17, v249
	v_lshlrev_b32_e32 v22, 16, v17
	v_mul_f32_e32 v12, 0xbfb8aa3b, v6
	v_exp_f32_e32 v12, v12
	v_lshlrev_b32_e32 v10, 16, v14
	v_and_b32_e32 v11, 0xffff0000, v14
	v_lshlrev_b32_e32 v13, 16, v15
	v_add_f32_e32 v12, 1.0, v12
	v_div_scale_f32 v20, s[2:3], v12, v12, v6
	v_rcp_f32_e32 v21, v20
	v_and_b32_e32 v14, 0xffff0000, v15
	v_lshlrev_b32_e32 v15, 16, v16
	v_and_b32_e32 v16, 0xffff0000, v16
	v_fma_f32 v23, -v20, v21, 1.0
	v_fmac_f32_e32 v21, v23, v21
	v_div_scale_f32 v23, vcc, v6, v12, v6
	v_mul_f32_e32 v24, v23, v21
	v_fma_f32 v26, -v20, v24, v23
	v_fmac_f32_e32 v24, v26, v21
	v_fma_f32 v20, -v20, v24, v23
	v_add_f32_e32 v23, 1.0, v25
	v_div_scale_f32 v25, s[2:3], v23, v23, v2
	v_rcp_f32_e32 v26, v25
	v_div_fmas_f32 v20, v20, v21, v24
	v_div_fixup_f32 v6, v20, v12, v6
	v_mul_f32_e32 v20, 0xbfb8aa3b, v7
	v_exp_f32_e32 v20, v20
	v_mul_f32_e32 v6, v6, v10
	v_fma_f32 v10, -v25, v26, 1.0
	v_fmac_f32_e32 v26, v10, v26
	v_div_scale_f32 v10, vcc, v2, v23, v2
	v_mul_f32_e32 v12, v10, v26
	v_fma_f32 v21, -v25, v12, v10
	v_add_f32_e32 v20, 1.0, v20
	v_fmac_f32_e32 v12, v21, v26
	v_div_scale_f32 v21, s[2:3], v20, v20, v7
	v_fma_f32 v10, -v25, v12, v10
	v_rcp_f32_e32 v24, v21
	v_div_fmas_f32 v10, v10, v26, v12
	v_div_fixup_f32 v2, v10, v23, v2
	v_mul_f32_e32 v10, v2, v15
	v_mul_f32_e32 v15, 0xbfb8aa3b, v3
	v_fma_f32 v2, -v21, v24, 1.0
	v_exp_f32_e32 v15, v15
	v_fmac_f32_e32 v24, v2, v24
	v_div_scale_f32 v2, vcc, v7, v20, v7
	v_mul_f32_e32 v12, v2, v24
	v_fma_f32 v23, -v21, v12, v2
	v_fmac_f32_e32 v12, v23, v24
	v_add_f32_e32 v15, 1.0, v15
	v_fma_f32 v2, -v21, v12, v2
	v_div_scale_f32 v21, s[2:3], v15, v15, v3
	v_rcp_f32_e32 v23, v21
	v_div_fmas_f32 v2, v2, v24, v12
	v_mul_f32_e32 v12, 0xbfb8aa3b, v8
	v_exp_f32_e32 v12, v12
	v_div_fixup_f32 v2, v2, v20, v7
	v_fma_f32 v7, -v21, v23, 1.0
	v_fmac_f32_e32 v23, v7, v23
	v_div_scale_f32 v7, vcc, v3, v15, v3
	v_mul_f32_e32 v2, v2, v11
	v_mul_f32_e32 v11, v7, v23
	v_fma_f32 v20, -v21, v11, v7
	v_add_f32_e32 v12, 1.0, v12
	v_fmac_f32_e32 v11, v20, v23
	v_div_scale_f32 v20, s[2:3], v12, v12, v8
	v_fma_f32 v7, -v21, v11, v7
	v_rcp_f32_e32 v21, v20
	v_div_fmas_f32 v7, v7, v23, v11
	v_div_fixup_f32 v3, v7, v15, v3
	v_mul_f32_e32 v15, 0xbfb8aa3b, v4
	v_exp_f32_e32 v15, v15
	v_mul_f32_e32 v7, v3, v16
	v_fma_f32 v3, -v20, v21, 1.0
	v_fmac_f32_e32 v21, v3, v21
	v_div_scale_f32 v3, vcc, v8, v12, v8
	v_mul_f32_e32 v11, v3, v21
	v_fma_f32 v16, -v20, v11, v3
	v_add_f32_e32 v15, 1.0, v15
	v_fmac_f32_e32 v11, v16, v21
	v_div_scale_f32 v16, s[2:3], v15, v15, v4
	v_fma_f32 v3, -v20, v11, v3
	v_rcp_f32_e32 v20, v16
	v_div_fmas_f32 v3, v3, v21, v11
	v_div_fixup_f32 v3, v3, v12, v8
	v_mul_f32_e32 v12, 0xbfb8aa3b, v9
	v_exp_f32_e32 v12, v12
	v_fma_f32 v8, -v16, v20, 1.0
	v_fmac_f32_e32 v20, v8, v20
	v_div_scale_f32 v8, vcc, v4, v15, v4
	v_mul_f32_e32 v11, v8, v20
	v_mul_f32_e32 v3, v3, v13
	v_fma_f32 v13, -v16, v11, v8
	v_add_f32_e32 v12, 1.0, v12
	v_fmac_f32_e32 v11, v13, v20
	v_div_scale_f32 v13, s[2:3], v12, v12, v9
	v_fma_f32 v8, -v16, v11, v8
	v_rcp_f32_e32 v16, v13
	v_div_fmas_f32 v8, v8, v20, v11
	v_div_fixup_f32 v4, v8, v15, v4
	v_mul_f32_e32 v8, v4, v22
	v_fma_f32 v4, -v13, v16, 1.0
	v_mul_f32_e32 v15, 0xbfb8aa3b, v5
	v_fmac_f32_e32 v16, v4, v16
	v_div_scale_f32 v4, vcc, v9, v12, v9
	v_exp_f32_e32 v15, v15
	v_mul_f32_e32 v11, v4, v16
	v_fma_f32 v20, -v13, v11, v4
	v_fmac_f32_e32 v11, v20, v16
	v_fma_f32 v4, -v13, v11, v4
	v_add_f32_e32 v13, 1.0, v15
	v_div_scale_f32 v15, s[2:3], v13, v13, v5
	v_rcp_f32_e32 v20, v15
	v_div_fmas_f32 v4, v4, v16, v11
	v_div_fixup_f32 v4, v4, v12, v9
	v_and_b32_e32 v17, 0xffff0000, v17
	v_fma_f32 v9, -v15, v20, 1.0
	v_fmac_f32_e32 v20, v9, v20
	v_div_scale_f32 v9, vcc, v5, v13, v5
	v_mul_f32_e32 v11, v9, v20
	v_fma_f32 v12, -v15, v11, v9
	v_fmac_f32_e32 v11, v12, v20
	v_fma_f32 v9, -v15, v11, v9
	v_div_fmas_f32 v9, v9, v20, v11
	v_div_fixup_f32 v5, v9, v13, v5
	v_mul_f32_e32 v4, v4, v14
	v_mul_f32_e32 v5, v5, v17
	s_and_b64 vcc, exec, s[0:1]
	s_mov_b32 s3, s22
	s_mov_b32 s2, s24
	v_cvt_pk_bf16_f32 v2, v6, v2
	v_cvt_pk_bf16_f32 v3, v3, v4
	v_cvt_pk_bf16_f32 v4, v10, v7
	v_cvt_pk_bf16_f32 v5, v8, v5
	global_store_dwordx4 v[18:19], v[2:5], off offset:256
	s_cbranch_vccz .LBB0_1049
	s_waitcnt vmcnt(0)
	s_cmpk_gt_u32 s33, 0xff
	s_cbranch_scc1 .LBB0_1060
	s_barrier

; #define PG8_STAGE(bufoff, gbase, voff) do { _Pragma("unroll") for (int _i = 0; _i < 2; ++_i) \
;         __builtin_amdgcn_global_load_lds((const unsigned*)((const char*)(gbase) + (voff)[_i]), (PG8_LAS unsigned*)(lds + (bufoff) + ldsw + _i * 8192), 16, 0, 0); } while (0)
; #define PG8_WAIT_V(n) asm volatile("s_waitcnt vmcnt(" #n ")" ::: "memory")
; template <class Epi>
; __device__ __forceinline__ void gemm_phase(PG8_LAS unsigned char* lds, const Gemm g, const StaticOrder& S, const Epi& E) {
;     const int tid = threadIdx.x, wid = __builtin_amdgcn_readfirstlane(tid >> 6), lane = tid & 63, wr = wid >> 2, wc = wid & 3, fr = lane & 15, fq = lane >> 4;
;     const int K = g.K, nt = K / BK;
;     unsigned voffA[2], voffB[2];
; #pragma unroll
;     for (int i = 0; i < 2; ++i) { int R, C; stage_rc(tid * 16 + i * 8192, R, C); const int Rb = Epi::PERM ? ((R & ~31) + perm32(R & 31)) : R;
;         voffA[i] = (unsigned)(R * K + C) * 2u; voffB[i] = (unsigned)(Rb * K + C) * 2u; }
;     const size_t kstep = (size_t)(BK * 2);
;     const size_t hstep = (size_t)HALF * K * 2;
;     const size_t tstep = 2 * hstep;
;     const unsigned ldsw = (unsigned)wid * 1024u;
;     const int aoff = lds_byte(wr * 64 + fr, fq * 8), boff = lds_byte(wc * 32 + fr, fq * 8);
;     ...
;     Unit cur, nxt; int ui = 0;
;     if (!S.next(0, cur)) return;
;     f32x4 acc[2][2][4][2];
; #pragma unroll
;     for (int a = 0; a < 2; ++a)
; #pragma unroll
;         for (int b = 0; b < 2; ++b)
; #pragma unroll
;             for (int m = 0; m < 4; ++m)
; #pragma unroll
;                 for (int n = 0; n < 2; ++n) acc[a][b][m][n] = (f32x4){0.f, 0.f, 0.f, 0.f};
;     bf16x8 At[4][2], B0[2][2], B1[2][2];
;     const char* cA = (const char*)g.A + (size_t)cur.pm * tstep; const char* cB = (const char*)g.Bt + (size_t)cur.pn * tstep;
;     PG8_STAGE(PG8_SB(0, 0), cB, voffB); PG8_STAGE(PG8_SA(0, 0), cA, voffA); PG8_STAGE(PG8_SB(0, 1), cB + hstep, voffB); PG8_STAGE(PG8_SA(0, 1), cA + hstep, voffA);
;     if (wr == 1) PG8_BAR;
;     PG8_WAIT_V(4); PG8_BAR;
;     PG8_STAGE(PG8_SB(1, 0), cB + kstep, voffB); PG8_STAGE(PG8_SA(1, 0), cA + kstep, voffA); PG8_STAGE(PG8_SB(1, 1), cB + hstep + kstep, voffB);
; __global__ void __launch_bounds__(512, 2) mega(Params p) {
;     ...
;         pg8::Gemm g{(const u16*)(ws + OFF_R), (const u16*)(ws + OFF_W1OUT), NTOK, 2048, 4096}; pg8::StaticOrder S; S.init(NTOK, 2048, gridDim.x, blockIdx.x);
.LBB0_1079:
	s_add_u32 s35, s64, 0x4000000
	s_waitcnt vmcnt(0)
	v_lshrrev_b32_e32 v3, 1, v10
	s_addc_u32 s36, s65, 0
	v_and_b32_e32 v14, 24, v3
	v_lshrrev_b32_e32 v3, 5, v10
	s_add_u32 s37, s64, 0x1d000000
	v_and_b32_e32 v3, 4, v3
	v_bfe_u32 v4, v10, 2, 2
	s_addc_u32 s38, s65, 0
	v_lshlrev_b32_e32 v1, 4, v10
	v_and_b32_e32 v2, 32, v10
	v_bfe_u32 v13, v10, 2, 4
	v_or3_b32 v3, v3, v4, v14
	v_lshrrev_b32_e32 v4, 3, v10
	s_movk_i32 s5, 0x70
	s_add_i32 s0, s4, s0
	v_bitop3_b32 v11, v1, v2, 48 bitop3:0x6c
	v_and_b32_e32 v12, 64, v10
	v_and_or_b32 v5, v4, s5, v13
	s_movk_i32 s5, 0x60
	v_add_u32_e32 v15, 0x2000, v1
	s_ashr_i32 s4, s0, 31
	v_or_b32_e32 v2, v11, v12
	v_and_or_b32 v4, v4, s5, v3
	v_lshrrev_b32_e32 v1, 7, v15
	s_movk_i32 s5, 0xf0
	s_lshr_b32 s4, s4, 26
	v_lshl_or_b32 v134, v4, 13, v2
	v_and_or_b32 v4, v1, s5, v13
	s_movk_i32 s5, 0xe0
	s_add_i32 s4, s0, s4
	v_and_or_b32 v1, v1, s5, v3
	s_ashr_i32 s5, s4, 6
	s_and_b32 s4, s4, 0xffc0
	s_sub_i32 s4, s0, s4
	s_bfe_i32 s0, s4, 0x80000
	s_bfe_u32 s0, s0, 0x3000c
	s_add_i32 s7, s4, s0
	s_bfe_i32 s0, s7, 0x80000
	s_and_b32 s7, s7, 0xf8
	s_sub_i32 s4, s4, s7
	s_lshl_b32 s5, s5, 3
	s_sext_i32_i16 s0, s0
	s_sext_i32_i8 s4, s4
	s_lshr_b32 s1, s33, 8
	s_lshr_b32 s0, s0, 3
	s_add_i32 s24, s5, s4
	s_lshr_b32 s6, s33, 6
	s_ashr_i32 s25, s24, 31
	s_bfe_i64 s[8:9], s[0:1], 0x100000
	s_lshl_b32 s39, s6, 10
	s_lshl_b64 s[4:5], s[24:25], 21
	s_lshl_b64 s[8:9], s[8:9], 21
	s_add_u32 s28, s37, s8
	s_addc_u32 s29, s38, s9
	s_add_i32 s25, s39, 0
	s_add_i32 m0, s25, 0x10000
	v_lshl_or_b32 v138, v1, 13, v2
	global_load_lds_dwordx4 v134, s[28:29]
	s_add_i32 m0, s25, 0x12000
	s_add_u32 s26, s35, s4
	v_lshl_or_b32 v132, v5, 13, v2
	global_load_lds_dwordx4 v138, s[28:29]
	s_addc_u32 s27, s36, s5
	s_mov_b32 m0, s25
	s_add_i32 s40, s25, 0x2000
	v_lshl_or_b32 v136, v4, 13, v2
	global_load_lds_dwordx4 v132, s[26:27]
	s_mov_b32 m0, s40
	s_add_u32 s4, s28, 0x100000
	global_load_lds_dwordx4 v136, s[26:27]
	s_addc_u32 s5, s29, 0
	s_add_i32 m0, s25, 0x14000
	v_mov_b32_e32 v135, 0
	global_load_lds_dwordx4 v134, s[4:5]
	s_add_i32 m0, s25, 0x16000
	v_mov_b32_e32 v139, v135
	global_load_lds_dwordx4 v138, s[4:5]
	s_add_u32 s4, s26, 0x100000
	s_addc_u32 s5, s27, 0
	s_add_i32 s41, s25, 0x4000
	s_mov_b32 m0, s41
	s_add_i32 s42, s25, 0x6000
	global_load_lds_dwordx4 v132, s[4:5]
	s_mov_b32 m0, s42
	v_mov_b32_e32 v133, v135
	global_load_lds_dwordx4 v136, s[4:5]
	v_mov_b32_e32 v137, v135
	s_mov_b32 s43, 0
	v_lshl_add_u64 v[8:9], s[28:29], 0, v[134:135]
	v_lshl_add_u64 v[6:7], s[28:29], 0, v[138:139]
	v_lshl_add_u64 v[4:5], s[26:27], 0, v[132:133]
	s_cmp_lg_u32 s1, 1
	v_lshl_add_u64 v[2:3], s[26:27], 0, v[136:137]
	s_cbranch_scc1 .LBB0_1081
	s_setprio 1
	s_barrier

; #define PG8_STAGE(bufoff, gbase, voff) do { _Pragma("unroll") for (int _i = 0; _i < 2; ++_i) \
;         __builtin_amdgcn_global_load_lds((const unsigned*)((const char*)(gbase) + (voff)[_i]), (PG8_LAS unsigned*)(lds + (bufoff) + ldsw + _i * 8192), 16, 0, 0); } while (0)
; #define PG8_LDA(dst, b, h) do { _Pragma("unroll") for (int m = 0; m < 4; ++m) _Pragma("unroll") for (int k = 0; k < 2; ++k) dst[m][k] = *(const PG8_LAS bf16x8*)(lds + PG8_SA(b, h) + aoff + m * 2048 + k * 1024); } while (0)
; #define PG8_LDB(dst, b, h) do { _Pragma("unroll") for (int n = 0; n < 2; ++n) _Pragma("unroll") for (int k = 0; k < 2; ++k) dst[n][k] = *(const PG8_LAS bf16x8*)(lds + PG8_SB(b, h) + boff + n * 2048 + k * 1024); } while (0)
; #define PG8_MMA(ai, bj, At, Bt) do { __builtin_amdgcn_s_setprio(1); _Pragma("unroll") for (int m = 0; m < 4; ++m) _Pragma("unroll") for (int n = 0; n < 2; ++n) _Pragma("unroll") for (int k = 0; k < 2; ++k) \
;         acc[ai][bj][m][n] = __builtin_amdgcn_mfma_f32_16x16x32_bf16(Bt[n][k], At[m][k], acc[ai][bj][m][n], 0, 0, 0); __builtin_amdgcn_s_setprio(0); } while (0)
; #define PG8_WAIT_V(n) asm volatile("s_waitcnt vmcnt(" #n ")" ::: "memory")
; #define PG8_WAIT_L(n) asm volatile("s_waitcnt lgkmcnt(" #n ")" ::: "memory")
; #define PG8_BAR __builtin_amdgcn_s_barrier()
; #define PG8_SCHED __builtin_amdgcn_sched_barrier(0)
; template <class Epi>
; __device__ __forceinline__ void gemm_phase(PG8_LAS unsigned char* lds, const Gemm g, const StaticOrder& S, const Epi& E) {
;     ...
;             PG8_LDB(B0, 0, 0); PG8_SCHED; PG8_LDA(At, 0, 0); PG8_STAGE(PG8_SA(1, 1), a1 + hstep, voffA);
;             PG8_WAIT_L(8); PG8_BAR; PG8_WAIT_L(0); PG8_MMA(0, 0, At, B0); PG8_BAR; PG8_SCHED;
;             PG8_LDB(B1, 0, 1); PG8_STAGE(PG8_SB(0, 0), b2, voffB);
;             PG8_BAR; PG8_WAIT_L(0); PG8_MMA(0, 1, At, B1); PG8_BAR;
;             PG8_LDA(At, 0, 1); PG8_STAGE(PG8_SA(0, 0), a2, voffA);
;             PG8_BAR; PG8_WAIT_L(0); PG8_MMA(1, 0, At, B0); PG8_BAR; PG8_SCHED;
;             PG8_STAGE(PG8_SB(0, 1), b2 + hstep, voffB);
;             PG8_WAIT_V(6); PG8_BAR; PG8_MMA(1, 1, At, B1); PG8_BAR;
;             PG8_LDB(B0, 1, 0); PG8_SCHED; PG8_LDA(At, 1, 0); PG8_STAGE(PG8_SA(0, 1), a2 + hstep, voffA);
;             PG8_WAIT_L(8); PG8_BAR; PG8_WAIT_L(0); PG8_MMA(0, 0, At, B0); PG8_BAR; PG8_SCHED;
.LBB0_1089:
	ds_read_b128 v[154:157], v151
	ds_read_b128 v[158:161], v151 offset:1024
	ds_read_b128 v[162:165], v151 offset:2048
	ds_read_b128 v[166:169], v151 offset:3072
	s_add_u32 s28, s26, 0xfff00080
	s_addc_u32 s29, s27, -1
	s_cmp_eq_u32 s58, 60
	s_cselect_b32 s31, s19, s29
	s_cselect_b32 s30, s54, s28
	s_cselect_b32 s29, s17, s57
	s_cselect_b32 s28, s55, s56
	v_lshl_add_u64 v[148:149], s[26:27], 0, v[140:141]
	s_add_i32 m0, s25, 0xc000
	ds_read_b128 v[170:173], v152
	ds_read_b128 v[174:177], v152 offset:1024
	ds_read_b128 v[178:181], v152 offset:2048
	ds_read_b128 v[182:185], v152 offset:3072
	ds_read_b128 v[186:189], v152 offset:4096
	ds_read_b128 v[190:193], v152 offset:5120
	ds_read_b128 v[194:197], v152 offset:6144
	ds_read_b128 v[198:201], v152 offset:7168
	global_load_lds_dwordx4 v[148:149], off
	v_lshl_add_u64 v[148:149], s[26:27], 0, v[142:143]
	s_add_i32 m0, s25, 0xe000
	s_nop 0
	global_load_lds_dwordx4 v[148:149], off
	s_waitcnt lgkmcnt(8)
	s_barrier
	s_waitcnt lgkmcnt(0)
	s_nop 0
	s_waitcnt lgkmcnt(0)
	v_mfma_f32_16x16x32_bf16 v[126:129], v[154:157], v[170:173], v[126:129]
	v_mfma_f32_16x16x32_bf16 v[122:125], v[162:165], v[170:173], v[122:125]
	v_mfma_f32_16x16x32_bf16 v[114:117], v[154:157], v[178:181], v[114:117]
	v_mfma_f32_16x16x32_bf16 v[106:109], v[162:165], v[178:181], v[106:109]
	v_mfma_f32_16x16x32_bf16 v[98:101], v[154:157], v[186:189], v[98:101]
	v_mfma_f32_16x16x32_bf16 v[90:93], v[162:165], v[186:189], v[90:93]
	v_mfma_f32_16x16x32_bf16 v[82:85], v[154:157], v[194:197], v[82:85]
	v_mfma_f32_16x16x32_bf16 v[74:77], v[162:165], v[194:197], v[74:77]
	v_mfma_f32_16x16x32_bf16 v[126:129], v[158:161], v[174:177], v[126:129]
	v_mfma_f32_16x16x32_bf16 v[122:125], v[166:169], v[174:177], v[122:125]
	v_mfma_f32_16x16x32_bf16 v[114:117], v[158:161], v[182:185], v[114:117]
	v_mfma_f32_16x16x32_bf16 v[106:109], v[166:169], v[182:185], v[106:109]
	v_mfma_f32_16x16x32_bf16 v[98:101], v[158:161], v[190:193], v[98:101]
	v_mfma_f32_16x16x32_bf16 v[90:93], v[166:169], v[190:193], v[90:93]
	v_mfma_f32_16x16x32_bf16 v[82:85], v[158:161], v[198:201], v[82:85]
	v_mfma_f32_16x16x32_bf16 v[74:77], v[166:169], v[198:201], v[74:77]
	s_nop 0
	s_barrier
	s_add_i32 s59, s47, s39
	v_lshl_add_u64 v[148:149], s[28:29], 0, v[134:135]
	s_mov_b32 m0, s59
	ds_read_b128 v[202:205], v153
	ds_read_b128 v[206:209], v153 offset:1024
	ds_read_b128 v[210:213], v153 offset:2048
	ds_read_b128 v[214:217], v153 offset:3072
	global_load_lds_dwordx4 v[148:149], off
	v_lshl_add_u64 v[218:219], s[28:29], 0, v[138:139]
	s_add_i32 m0, s59, 0x2000
	s_nop 0
	global_load_lds_dwordx4 v[218:219], off
	s_barrier
	s_waitcnt lgkmcnt(0)
	s_nop 0
	s_waitcnt lgkmcnt(0)
	v_mfma_f32_16x16x32_bf16 v[118:121], v[202:205], v[170:173], v[118:121]
	v_mfma_f32_16x16x32_bf16 v[110:113], v[210:213], v[170:173], v[110:113]
	v_mfma_f32_16x16x32_bf16 v[102:105], v[202:205], v[178:181], v[102:105]
	v_mfma_f32_16x16x32_bf16 v[94:97], v[210:213], v[178:181], v[94:97]
	v_mfma_f32_16x16x32_bf16 v[86:89], v[202:205], v[186:189], v[86:89]
	v_mfma_f32_16x16x32_bf16 v[78:81], v[210:213], v[186:189], v[78:81]
	v_mfma_f32_16x16x32_bf16 v[70:73], v[202:205], v[194:197], v[70:73]
	v_mfma_f32_16x16x32_bf16 v[66:69], v[210:213], v[194:197], v[66:69]
	v_mfma_f32_16x16x32_bf16 v[118:121], v[206:209], v[174:177], v[118:121]
	v_mfma_f32_16x16x32_bf16 v[110:113], v[214:217], v[174:177], v[110:113]
	v_mfma_f32_16x16x32_bf16 v[102:105], v[206:209], v[182:185], v[102:105]
	v_mfma_f32_16x16x32_bf16 v[94:97], v[214:217], v[182:185], v[94:97]
	v_mfma_f32_16x16x32_bf16 v[86:89], v[206:209], v[190:193], v[86:89]
	v_mfma_f32_16x16x32_bf16 v[78:81], v[214:217], v[190:193], v[78:81]
	v_mfma_f32_16x16x32_bf16 v[70:73], v[206:209], v[198:201], v[70:73]
	v_mfma_f32_16x16x32_bf16 v[66:69], v[214:217], v[198:201], v[66:69]
	s_nop 0
	s_mov_b32 m0, s25
	v_lshl_add_u64 v[220:221], s[30:31], 0, v[132:133]
	s_barrier
	ds_read_b128 v[170:173], v152 offset:16384
	ds_read_b128 v[174:177], v152 offset:17408
	ds_read_b128 v[178:181], v152 offset:18432
	ds_read_b128 v[182:185], v152 offset:19456
	ds_read_b128 v[186:189], v152 offset:20480
	ds_read_b128 v[190:193], v152 offset:21504
	ds_read_b128 v[194:197], v152 offset:22528
	ds_read_b128 v[198:201], v152 offset:23552
	global_load_lds_dwordx4 v[220:221], off
	v_lshl_add_u64 v[222:223], s[30:31], 0, v[136:137]
	s_mov_b32 m0, s40
	s_nop 0
	global_load_lds_dwordx4 v[222:223], off
	s_barrier
	s_waitcnt lgkmcnt(0)
	s_nop 0
	s_waitcnt lgkmcnt(0)
	v_mfma_f32_16x16x32_bf16 v[62:65], v[154:157], v[170:173], v[62:65]
	v_mfma_f32_16x16x32_bf16 v[58:61], v[162:165], v[170:173], v[58:61]
	v_mfma_f32_16x16x32_bf16 v[54:57], v[154:157], v[178:181], v[54:57]
	v_mfma_f32_16x16x32_bf16 v[46:49], v[162:165], v[178:181], v[46:49]
	v_mfma_f32_16x16x32_bf16 v[38:41], v[154:157], v[186:189], v[38:41]
	v_mfma_f32_16x16x32_bf16 v[30:33], v[162:165], v[186:189], v[30:33]
	v_mfma_f32_16x16x32_bf16 v[22:25], v[154:157], v[194:197], v[22:25]
	v_mfma_f32_16x16x32_bf16 v[14:17], v[162:165], v[194:197], v[14:17]
	v_mfma_f32_16x16x32_bf16 v[62:65], v[158:161], v[174:177], v[62:65]
	v_mfma_f32_16x16x32_bf16 v[58:61], v[166:169], v[174:177], v[58:61]
	v_mfma_f32_16x16x32_bf16 v[54:57], v[158:161], v[182:185], v[54:57]
	v_mfma_f32_16x16x32_bf16 v[46:49], v[166:169], v[182:185], v[46:49]
	v_mfma_f32_16x16x32_bf16 v[38:41], v[158:161], v[190:193], v[38:41]
	v_mfma_f32_16x16x32_bf16 v[30:33], v[166:169], v[190:193], v[30:33]
	v_mfma_f32_16x16x32_bf16 v[22:25], v[158:161], v[198:201], v[22:25]
	v_mfma_f32_16x16x32_bf16 v[14:17], v[166:169], v[198:201], v[14:17]
	s_nop 0
	s_barrier
; #define PG8_STAGE(bufoff, gbase, voff) do { _Pragma("unroll") for (int _i = 0; _i < 2; ++_i) \
;         __builtin_amdgcn_global_load_lds((const unsigned*)((const char*)(gbase) + (voff)[_i]), (PG8_LAS unsigned*)(lds + (bufoff) + ldsw + _i * 8192), 16, 0, 0); } while (0)
; #define PG8_LDA(dst, b, h) do { _Pragma("unroll") for (int m = 0; m < 4; ++m) _Pragma("unroll") for (int k = 0; k < 2; ++k) dst[m][k] = *(const PG8_LAS bf16x8*)(lds + PG8_SA(b, h) + aoff + m * 2048 + k * 1024); } while (0)
; #define PG8_LDB(dst, b, h) do { _Pragma("unroll") for (int n = 0; n < 2; ++n) _Pragma("unroll") for (int k = 0; k < 2; ++k) dst[n][k] = *(const PG8_LAS bf16x8*)(lds + PG8_SB(b, h) + boff + n * 2048 + k * 1024); } while (0)
; #define PG8_MMA(ai, bj, At, Bt) do { __builtin_amdgcn_s_setprio(1); _Pragma("unroll") for (int m = 0; m < 4; ++m) _Pragma("unroll") for (int n = 0; n < 2; ++n) _Pragma("unroll") for (int k = 0; k < 2; ++k) \
;         acc[ai][bj][m][n] = __builtin_amdgcn_mfma_f32_16x16x32_bf16(Bt[n][k], At[m][k], acc[ai][bj][m][n], 0, 0, 0); __builtin_amdgcn_s_setprio(0); } while (0)
; #define PG8_WAIT_V(n) asm volatile("s_waitcnt vmcnt(" #n ")" ::: "memory")
; #define PG8_WAIT_L(n) asm volatile("s_waitcnt lgkmcnt(" #n ")" ::: "memory")
; #define PG8_BAR __builtin_amdgcn_s_barrier()
; #define PG8_SCHED __builtin_amdgcn_sched_barrier(0)
; template <class Epi>
; __device__ __forceinline__ void gemm_phase(PG8_LAS unsigned char* lds, const Gemm g, const StaticOrder& S, const Epi& E) {
;     ...
;             PG8_WAIT_V(6); PG8_BAR; PG8_MMA(1, 1, At, B1); PG8_BAR;
;             PG8_LDB(B0, 1, 0); PG8_SCHED; PG8_LDA(At, 1, 0); PG8_STAGE(PG8_SA(0, 1), a2 + hstep, voffA);
;             PG8_WAIT_L(8); PG8_BAR; PG8_WAIT_L(0); PG8_MMA(0, 0, At, B0); PG8_BAR; PG8_SCHED;
;             PG8_LDB(B1, 1, 1); PG8_STAGE(PG8_SB(1, 0), b3, voffB);
;             PG8_BAR; PG8_WAIT_L(0); PG8_MMA(0, 1, At, B1); PG8_BAR;
;             PG8_LDA(At, 1, 1); PG8_STAGE(PG8_SA(1, 0), a3, voffA);
;             PG8_BAR; PG8_WAIT_L(0); PG8_MMA(1, 0, At, B0); PG8_BAR; PG8_SCHED;
	s_add_u32 s60, s28, 0x100000
	s_addc_u32 s61, s29, 0
	s_add_i32 s59, s48, s39
	v_lshl_add_u64 v[154:155], s[60:61], 0, v[134:135]
	s_mov_b32 m0, s59
	s_nop 0
	global_load_lds_dwordx4 v[154:155], off
	v_lshl_add_u64 v[154:155], s[60:61], 0, v[138:139]
	s_add_i32 m0, s59, 0x2000
	s_nop 0
	global_load_lds_dwordx4 v[154:155], off
	s_waitcnt vmcnt(6)
	s_barrier
	s_nop 0
	v_mfma_f32_16x16x32_bf16 v[50:53], v[202:205], v[170:173], v[50:53]
	v_mfma_f32_16x16x32_bf16 v[42:45], v[210:213], v[170:173], v[42:45]
	v_mfma_f32_16x16x32_bf16 v[34:37], v[202:205], v[178:181], v[34:37]
	v_mfma_f32_16x16x32_bf16 v[26:29], v[210:213], v[178:181], v[26:29]
	v_mfma_f32_16x16x32_bf16 v[18:21], v[202:205], v[186:189], v[18:21]
	v_mfma_f32_16x16x32_bf16 v[10:13], v[210:213], v[186:189], v[10:13]
	v_mfma_f32_16x16x32_bf16 v[6:9], v[202:205], v[194:197], v[6:9]
	v_mfma_f32_16x16x32_bf16 v[2:5], v[210:213], v[194:197], v[2:5]
	v_mfma_f32_16x16x32_bf16 v[50:53], v[206:209], v[174:177], v[50:53]
	v_mfma_f32_16x16x32_bf16 v[42:45], v[214:217], v[174:177], v[42:45]
	v_mfma_f32_16x16x32_bf16 v[34:37], v[206:209], v[182:185], v[34:37]
	v_mfma_f32_16x16x32_bf16 v[26:29], v[214:217], v[182:185], v[26:29]
	v_mfma_f32_16x16x32_bf16 v[18:21], v[206:209], v[190:193], v[18:21]
	v_mfma_f32_16x16x32_bf16 v[10:13], v[214:217], v[190:193], v[10:13]
	v_mfma_f32_16x16x32_bf16 v[6:9], v[206:209], v[198:201], v[6:9]
	v_mfma_f32_16x16x32_bf16 v[2:5], v[214:217], v[198:201], v[2:5]
	s_nop 0
	s_add_i32 s59, 0, 0x18000
	v_add_u32_e32 v166, s59, v131
	s_barrier
	ds_read_b128 v[154:157], v166
	ds_read_b128 v[158:161], v166 offset:1024
	ds_read_b128 v[162:165], v166 offset:2048
	ds_read_b128 v[166:169], v166 offset:3072
	s_add_u32 s30, s30, 0x100000
	s_addc_u32 s31, s31, 0
	s_mov_b32 m0, s41
	v_lshl_add_u64 v[202:203], s[30:31], 0, v[132:133]
	ds_read_b128 v[170:173], v152 offset:32768
	ds_read_b128 v[174:177], v152 offset:33792
	ds_read_b128 v[178:181], v152 offset:34816
	ds_read_b128 v[182:185], v152 offset:35840
	ds_read_b128 v[186:189], v152 offset:36864
	ds_read_b128 v[190:193], v152 offset:37888
	ds_read_b128 v[194:197], v152 offset:38912
	ds_read_b128 v[198:201], v152 offset:39936
	global_load_lds_dwordx4 v[202:203], off
	v_lshl_add_u64 v[202:203], s[30:31], 0, v[136:137]
	s_mov_b32 m0, s42
	s_nop 0
	global_load_lds_dwordx4 v[202:203], off
	s_waitcnt lgkmcnt(8)
	s_barrier
	s_waitcnt lgkmcnt(0)
	s_nop 0
	s_waitcnt lgkmcnt(0)
	v_mfma_f32_16x16x32_bf16 v[126:129], v[154:157], v[170:173], v[126:129]
	v_mfma_f32_16x16x32_bf16 v[122:125], v[162:165], v[170:173], v[122:125]
	v_mfma_f32_16x16x32_bf16 v[114:117], v[154:157], v[178:181], v[114:117]
	v_mfma_f32_16x16x32_bf16 v[106:109], v[162:165], v[178:181], v[106:109]
	v_mfma_f32_16x16x32_bf16 v[98:101], v[154:157], v[186:189], v[98:101]
	v_mfma_f32_16x16x32_bf16 v[90:93], v[162:165], v[186:189], v[90:93]
	v_mfma_f32_16x16x32_bf16 v[82:85], v[154:157], v[194:197], v[82:85]
	v_mfma_f32_16x16x32_bf16 v[74:77], v[162:165], v[194:197], v[74:77]
	v_mfma_f32_16x16x32_bf16 v[126:129], v[158:161], v[174:177], v[126:129]
	v_mfma_f32_16x16x32_bf16 v[122:125], v[166:169], v[174:177], v[122:125]
	v_mfma_f32_16x16x32_bf16 v[114:117], v[158:161], v[182:185], v[114:117]
	v_mfma_f32_16x16x32_bf16 v[106:109], v[166:169], v[182:185], v[106:109]
	v_mfma_f32_16x16x32_bf16 v[98:101], v[158:161], v[190:193], v[98:101]
	v_mfma_f32_16x16x32_bf16 v[90:93], v[166:169], v[190:193], v[90:93]
	v_mfma_f32_16x16x32_bf16 v[82:85], v[158:161], v[198:201], v[82:85]
	v_mfma_f32_16x16x32_bf16 v[74:77], v[166:169], v[198:201], v[74:77]
	s_nop 0
	s_barrier
	s_add_i32 s30, 0, 0x1c000
	s_add_i32 s31, s59, s39
	v_add_u32_e32 v214, s30, v131
	v_lshl_add_u64 v[148:149], v[148:149], 0, s[6:7]
	s_mov_b32 m0, s31
	ds_read_b128 v[202:205], v214
	ds_read_b128 v[206:209], v214 offset:1024
	ds_read_b128 v[210:213], v214 offset:2048
	ds_read_b128 v[214:217], v214 offset:3072
	global_load_lds_dwordx4 v[148:149], off
	v_lshl_add_u64 v[148:149], v[218:219], 0, s[6:7]
	s_add_i32 m0, s31, 0x2000
	s_nop 0
	global_load_lds_dwordx4 v[148:149], off
	s_barrier
	s_waitcnt lgkmcnt(0)
	s_nop 0
	s_waitcnt lgkmcnt(0)
	v_mfma_f32_16x16x32_bf16 v[118:121], v[202:205], v[170:173], v[118:121]
	v_mfma_f32_16x16x32_bf16 v[110:113], v[210:213], v[170:173], v[110:113]
	v_mfma_f32_16x16x32_bf16 v[102:105], v[202:205], v[178:181], v[102:105]
	v_mfma_f32_16x16x32_bf16 v[94:97], v[210:213], v[178:181], v[94:97]
	v_mfma_f32_16x16x32_bf16 v[86:89], v[202:205], v[186:189], v[86:89]
	v_mfma_f32_16x16x32_bf16 v[78:81], v[210:213], v[186:189], v[78:81]
	v_mfma_f32_16x16x32_bf16 v[70:73], v[202:205], v[194:197], v[70:73]
	v_mfma_f32_16x16x32_bf16 v[66:69], v[210:213], v[194:197], v[66:69]
	v_mfma_f32_16x16x32_bf16 v[118:121], v[206:209], v[174:177], v[118:121]
	v_mfma_f32_16x16x32_bf16 v[110:113], v[214:217], v[174:177], v[110:113]
	v_mfma_f32_16x16x32_bf16 v[102:105], v[206:209], v[182:185], v[102:105]
	v_mfma_f32_16x16x32_bf16 v[94:97], v[214:217], v[182:185], v[94:97]
	v_mfma_f32_16x16x32_bf16 v[86:89], v[206:209], v[190:193], v[86:89]
	v_mfma_f32_16x16x32_bf16 v[78:81], v[214:217], v[190:193], v[78:81]
	v_mfma_f32_16x16x32_bf16 v[70:73], v[206:209], v[198:201], v[70:73]
	v_mfma_f32_16x16x32_bf16 v[66:69], v[214:217], v[198:201], v[66:69]
	s_nop 0
	s_mov_b32 m0, s44
	v_lshl_add_u64 v[148:149], v[220:221], 0, s[6:7]
	s_barrier
	ds_read_b128 v[170:173], v152 offset:49152
	ds_read_b128 v[174:177], v152 offset:50176
	ds_read_b128 v[178:181], v152 offset:51200
	ds_read_b128 v[182:185], v152 offset:52224
	ds_read_b128 v[186:189], v152 offset:53248
	ds_read_b128 v[190:193], v152 offset:54272
	ds_read_b128 v[194:197], v152 offset:55296
	ds_read_b128 v[198:201], v152 offset:56320
	global_load_lds_dwordx4 v[148:149], off
	v_lshl_add_u64 v[148:149], v[222:223], 0, s[6:7]
	s_mov_b32 m0, s45
	s_nop 0
	global_load_lds_dwordx4 v[148:149], off
	s_barrier
; #define PG8_STAGE(bufoff, gbase, voff) do { _Pragma("unroll") for (int _i = 0; _i < 2; ++_i) \
;         __builtin_amdgcn_global_load_lds((const unsigned*)((const char*)(gbase) + (voff)[_i]), (PG8_LAS unsigned*)(lds + (bufoff) + ldsw + _i * 8192), 16, 0, 0); } while (0)
; #define PG8_LDA(dst, b, h) do { _Pragma("unroll") for (int m = 0; m < 4; ++m) _Pragma("unroll") for (int k = 0; k < 2; ++k) dst[m][k] = *(const PG8_LAS bf16x8*)(lds + PG8_SA(b, h) + aoff + m * 2048 + k * 1024); } while (0)
; #define PG8_MMA(ai, bj, At, Bt) do { __builtin_amdgcn_s_setprio(1); _Pragma("unroll") for (int m = 0; m < 4; ++m) _Pragma("unroll") for (int n = 0; n < 2; ++n) _Pragma("unroll") for (int k = 0; k < 2; ++k) \
;         acc[ai][bj][m][n] = __builtin_amdgcn_mfma_f32_16x16x32_bf16(Bt[n][k], At[m][k], acc[ai][bj][m][n], 0, 0, 0); __builtin_amdgcn_s_setprio(0); } while (0)
; #define PG8_WAIT_V(n) asm volatile("s_waitcnt vmcnt(" #n ")" ::: "memory")
; #define PG8_WAIT_L(n) asm volatile("s_waitcnt lgkmcnt(" #n ")" ::: "memory")
; #define PG8_BAR __builtin_amdgcn_s_barrier()
; #define PG8_SCHED __builtin_amdgcn_sched_barrier(0)
; template <class Epi>
; __device__ __forceinline__ void gemm_phase(PG8_LAS unsigned char* lds, const Gemm g, const StaticOrder& S, const Epi& E) {
;     ...
;             PG8_LDA(At, 1, 1); PG8_STAGE(PG8_SA(1, 0), a3, voffA);
;             PG8_BAR; PG8_WAIT_L(0); PG8_MMA(1, 0, At, B0); PG8_BAR; PG8_SCHED;
;             PG8_STAGE(PG8_SB(1, 1), b3 + hstep, voffB);
;             PG8_WAIT_V(6); PG8_BAR; PG8_MMA(1, 1, At, B1); PG8_BAR;
	s_waitcnt lgkmcnt(0)
	s_nop 0
	s_waitcnt lgkmcnt(0)
	v_mfma_f32_16x16x32_bf16 v[62:65], v[154:157], v[170:173], v[62:65]
	v_mfma_f32_16x16x32_bf16 v[58:61], v[162:165], v[170:173], v[58:61]
	v_mfma_f32_16x16x32_bf16 v[54:57], v[154:157], v[178:181], v[54:57]
	v_mfma_f32_16x16x32_bf16 v[46:49], v[162:165], v[178:181], v[46:49]
	v_mfma_f32_16x16x32_bf16 v[38:41], v[154:157], v[186:189], v[38:41]
	v_mfma_f32_16x16x32_bf16 v[30:33], v[162:165], v[186:189], v[30:33]
	v_mfma_f32_16x16x32_bf16 v[22:25], v[154:157], v[194:197], v[22:25]
	v_mfma_f32_16x16x32_bf16 v[14:17], v[162:165], v[194:197], v[14:17]
	v_mfma_f32_16x16x32_bf16 v[62:65], v[158:161], v[174:177], v[62:65]
	v_mfma_f32_16x16x32_bf16 v[58:61], v[166:169], v[174:177], v[58:61]
	v_mfma_f32_16x16x32_bf16 v[54:57], v[158:161], v[182:185], v[54:57]
	v_mfma_f32_16x16x32_bf16 v[46:49], v[166:169], v[182:185], v[46:49]
	v_mfma_f32_16x16x32_bf16 v[38:41], v[158:161], v[190:193], v[38:41]
	v_mfma_f32_16x16x32_bf16 v[30:33], v[166:169], v[190:193], v[30:33]
	v_mfma_f32_16x16x32_bf16 v[22:25], v[158:161], v[198:201], v[22:25]
	v_mfma_f32_16x16x32_bf16 v[14:17], v[166:169], v[198:201], v[14:17]
	s_nop 0
	s_barrier
	s_add_u32 s28, s28, 0x100080
	s_addc_u32 s29, s29, 0
	s_add_i32 s30, s30, s39
	v_lshl_add_u64 v[148:149], s[28:29], 0, v[134:135]
	s_mov_b32 m0, s30
	s_nop 0
	global_load_lds_dwordx4 v[148:149], off
	v_lshl_add_u64 v[148:149], s[28:29], 0, v[138:139]
	s_add_i32 m0, s30, 0x2000
	s_nop 0
	global_load_lds_dwordx4 v[148:149], off
	s_waitcnt vmcnt(6)
	s_barrier
	s_nop 0
	v_mfma_f32_16x16x32_bf16 v[50:53], v[202:205], v[170:173], v[50:53]
	v_mfma_f32_16x16x32_bf16 v[42:45], v[210:213], v[170:173], v[42:45]
	v_mfma_f32_16x16x32_bf16 v[34:37], v[202:205], v[178:181], v[34:37]
	v_mfma_f32_16x16x32_bf16 v[26:29], v[210:213], v[178:181], v[26:29]
	v_mfma_f32_16x16x32_bf16 v[18:21], v[202:205], v[186:189], v[18:21]
	v_mfma_f32_16x16x32_bf16 v[10:13], v[210:213], v[186:189], v[10:13]
	v_mfma_f32_16x16x32_bf16 v[6:9], v[202:205], v[194:197], v[6:9]
	v_mfma_f32_16x16x32_bf16 v[2:5], v[210:213], v[194:197], v[2:5]
	v_mfma_f32_16x16x32_bf16 v[50:53], v[206:209], v[174:177], v[50:53]
	v_mfma_f32_16x16x32_bf16 v[42:45], v[214:217], v[174:177], v[42:45]
	v_mfma_f32_16x16x32_bf16 v[34:37], v[206:209], v[182:185], v[34:37]
	v_mfma_f32_16x16x32_bf16 v[26:29], v[214:217], v[182:185], v[26:29]
	v_mfma_f32_16x16x32_bf16 v[18:21], v[206:209], v[190:193], v[18:21]
	v_mfma_f32_16x16x32_bf16 v[10:13], v[214:217], v[190:193], v[10:13]
	v_mfma_f32_16x16x32_bf16 v[6:9], v[206:209], v[198:201], v[6:9]
	v_mfma_f32_16x16x32_bf16 v[2:5], v[214:217], v[198:201], v[2:5]
	s_nop 0
	s_add_i32 s58, s58, 2
	s_add_u32 s26, s26, 0x100
	s_addc_u32 s27, s27, 0
	s_add_u32 s56, s56, 0x100
	s_addc_u32 s57, s57, 0
	s_cmp_gt_u32 s58, 61
	s_barrier
	s_cbranch_scc0 .LBB0_1089
; __device__ __forceinline__ unsigned pk2(float lo, float hi) { unsigned r; asm volatile("v_cvt_pk_bf16_f32 %0, %1, %2" : "=v"(r) : "v"(lo), "v"(hi)); return r; }
;     __device__ __forceinline__ void operator()(const f32x4 (&acc)[2][2][4][2], const Unit& u, int wr, int wc, int fr, int fq) const {
;         const int row0 = u.pm * BM + wr * 64 + fr, col0 = u.pn * BM + wc * 32 + 8 * fq;
; #pragma unroll
;         for (int ai = 0; ai < 2; ++ai)
; #pragma unroll
;             for (int m = 0; m < 4; ++m)
; #pragma unroll
;                 for (int bj = 0; bj < 2; ++bj) f(row0 + ai * HALF + m * 16, col0 + bj * HALF, acc[ai][bj][m][0], acc[ai][bj][m][1]);
; __device__ __forceinline__ void store8bf(u16* dst, f32x4 v0, f32x4 v1) { u32x4 w; w.x = pk2(v0[0], v0[1]); w.y = pk2(v0[2], v0[3]); w.z = pk2(v1[0], v1[1]); w.w = pk2(v1[2], v1[3]); *(u32x4*)dst = w; }
	v_lshl_add_u32 v154, s24, 8, v1
	v_lshl_or_b32 v148, s53, 8, v150
	v_ashrrev_i32_e32 v155, 31, v154
	v_lshlrev_b64 v[156:157], 12, v[154:155]
	v_ashrrev_i32_e32 v149, 31, v148
	v_lshl_add_u64 v[156:157], s[4:5], 0, v[156:157]
	v_lshlrev_b64 v[158:159], 1, v[148:149]
	v_lshl_add_u64 v[148:149], v[156:157], 0, v[158:159]
	v_cvt_pk_bf16_f32 v126, v126, v127
	v_cvt_pk_bf16_f32 v127, v128, v129
	v_cvt_pk_bf16_f32 v128, v122, v123
	v_cvt_pk_bf16_f32 v129, v124, v125
	global_store_dwordx4 v[148:149], v[126:129], off
	v_cvt_pk_bf16_f32 v118, v118, v119
	v_cvt_pk_bf16_f32 v119, v120, v121
	v_cvt_pk_bf16_f32 v120, v110, v111
	v_or_b32_e32 v110, 16, v154
	v_ashrrev_i32_e32 v111, 31, v110
	v_lshlrev_b64 v[110:111], 12, v[110:111]
	v_lshl_add_u64 v[110:111], s[4:5], 0, v[110:111]
	v_cvt_pk_bf16_f32 v121, v112, v113
	global_store_dwordx4 v[148:149], v[118:121], off offset:256
	s_mov_b32 s53, s16
	s_mov_b32 s24, s18
	v_lshl_add_u64 v[118:119], v[110:111], 0, v[158:159]
	v_cvt_pk_bf16_f32 v110, v114, v115
	v_cvt_pk_bf16_f32 v111, v116, v117
	v_cvt_pk_bf16_f32 v112, v106, v107
	v_cvt_pk_bf16_f32 v113, v108, v109
	global_store_dwordx4 v[118:119], v[110:113], off
	v_cvt_pk_bf16_f32 v102, v102, v103
	v_cvt_pk_bf16_f32 v103, v104, v105
	v_cvt_pk_bf16_f32 v104, v94, v95
	v_or_b32_e32 v94, 32, v154
	v_ashrrev_i32_e32 v95, 31, v94
	v_lshlrev_b64 v[94:95], 12, v[94:95]
	v_lshl_add_u64 v[94:95], s[4:5], 0, v[94:95]
	v_cvt_pk_bf16_f32 v105, v96, v97
	global_store_dwordx4 v[118:119], v[102:105], off offset:256
	s_mov_b64 s[28:29], s[22:23]
	s_mov_b64 s[26:27], s[20:21]
	v_lshl_add_u64 v[102:103], v[94:95], 0, v[158:159]
	v_cvt_pk_bf16_f32 v94, v98, v99
	v_cvt_pk_bf16_f32 v95, v100, v101
	v_cvt_pk_bf16_f32 v96, v90, v91
	v_cvt_pk_bf16_f32 v97, v92, v93
	global_store_dwordx4 v[102:103], v[94:97], off
	v_cvt_pk_bf16_f32 v86, v86, v87
	v_cvt_pk_bf16_f32 v87, v88, v89
	v_cvt_pk_bf16_f32 v88, v78, v79
	v_or_b32_e32 v78, 48, v154
	v_ashrrev_i32_e32 v79, 31, v78
	v_lshlrev_b64 v[78:79], 12, v[78:79]
	v_lshl_add_u64 v[78:79], s[4:5], 0, v[78:79]
	v_cvt_pk_bf16_f32 v89, v80, v81
	global_store_dwordx4 v[102:103], v[86:89], off offset:256
	s_nop 1
	v_lshl_add_u64 v[86:87], v[78:79], 0, v[158:159]
	v_cvt_pk_bf16_f32 v78, v82, v83
	v_cvt_pk_bf16_f32 v79, v84, v85
	v_cvt_pk_bf16_f32 v80, v74, v75
	v_cvt_pk_bf16_f32 v81, v76, v77
	global_store_dwordx4 v[86:87], v[78:81], off
	v_cvt_pk_bf16_f32 v70, v70, v71
	v_cvt_pk_bf16_f32 v71, v72, v73
	v_cvt_pk_bf16_f32 v72, v66, v67
	v_cvt_pk_bf16_f32 v73, v68, v69
	global_store_dwordx4 v[86:87], v[70:73], off offset:256
	v_cvt_pk_bf16_f32 v62, v62, v63
	v_cvt_pk_bf16_f32 v63, v64, v65
	v_cvt_pk_bf16_f32 v64, v58, v59
	v_add_co_u32_e32 v58, vcc, s49, v148
	v_lshl_add_u64 v[66:67], v[148:149], 0, s[8:9]
	s_nop 0
	v_addc_co_u32_e32 v59, vcc, 0, v149, vcc
	v_cvt_pk_bf16_f32 v65, v60, v61
	global_store_dwordx4 v[58:59], v[62:65], off
	v_cvt_pk_bf16_f32 v50, v50, v51
	v_cvt_pk_bf16_f32 v51, v52, v53
	v_cvt_pk_bf16_f32 v52, v42, v43
	v_cvt_pk_bf16_f32 v53, v44, v45
	global_store_dwordx4 v[66:67], v[50:53], off offset:256
	v_cvt_pk_bf16_f32 v42, v54, v55
	v_cvt_pk_bf16_f32 v43, v56, v57
	v_cvt_pk_bf16_f32 v44, v46, v47
	v_add_co_u32_e32 v46, vcc, s50, v148
	s_nop 0
	v_lshl_add_u64 v[50:51], v[148:149], 0, s[10:11]
	v_addc_co_u32_e32 v47, vcc, 0, v149, vcc
	v_cvt_pk_bf16_f32 v45, v48, v49
	global_store_dwordx4 v[46:47], v[42:45], off
	v_cvt_pk_bf16_f32 v34, v34, v35
	v_cvt_pk_bf16_f32 v35, v36, v37
	v_cvt_pk_bf16_f32 v36, v26, v27
	v_cvt_pk_bf16_f32 v37, v28, v29
	global_store_dwordx4 v[50:51], v[34:37], off offset:256
	v_cvt_pk_bf16_f32 v26, v38, v39
	v_cvt_pk_bf16_f32 v27, v40, v41
	v_cvt_pk_bf16_f32 v28, v30, v31
	v_add_co_u32_e32 v30, vcc, s51, v148
	s_nop 0
	v_lshl_add_u64 v[34:35], v[148:149], 0, s[12:13]
	v_addc_co_u32_e32 v31, vcc, 0, v149, vcc
	v_cvt_pk_bf16_f32 v29, v32, v33
	global_store_dwordx4 v[30:31], v[26:29], off
	v_cvt_pk_bf16_f32 v18, v18, v19
	v_cvt_pk_bf16_f32 v19, v20, v21
	v_cvt_pk_bf16_f32 v20, v10, v11
	v_cvt_pk_bf16_f32 v21, v12, v13
	global_store_dwordx4 v[34:35], v[18:21], off offset:256
	v_cvt_pk_bf16_f32 v10, v22, v23
	v_cvt_pk_bf16_f32 v11, v24, v25
	v_cvt_pk_bf16_f32 v12, v14, v15
	v_add_co_u32_e32 v14, vcc, s52, v148
	s_nop 0
	v_lshl_add_u64 v[18:19], v[148:149], 0, s[14:15]
	v_addc_co_u32_e32 v15, vcc, 0, v149, vcc
	s_and_b64 vcc, exec, s[0:1]
	v_cvt_pk_bf16_f32 v13, v16, v17
	global_store_dwordx4 v[14:15], v[10:13], off
	v_cvt_pk_bf16_f32 v6, v6, v7
	v_cvt_pk_bf16_f32 v7, v8, v9
	v_cvt_pk_bf16_f32 v8, v2, v3
	v_cvt_pk_bf16_f32 v9, v4, v5
	global_store_dwordx4 v[18:19], v[6:9], off offset:256
	s_cbranch_vccz .LBB0_1082
	s_waitcnt vmcnt(0)
	s_cmpk_gt_u32 s33, 0xff
	s_cbranch_scc1 .LBB0_1093
	s_barrier
